# trailing-half restore barrier moved after the per-tile scheduling header (both halves compute the next-tile header concurrently)
# baseline (speedup 1.0000x reference)
; #define LAS __attribute__((address_space(3)))
; __global__ void __launch_bounds__(512, 2) mk_fwd(Params p) {
;     extern __shared__ __attribute__((aligned(16))) unsigned char smem[];
;     LAS unsigned char* lds = (LAS unsigned char*)smem;
;     const int G = gridDim.x;
;     unsigned char* ws = p.ws;
;     const int lo = p.ph_lo, hi = p.ph_hi;
;     ...
;     bf16_t* XN = (bf16_t*)(ws + WS_XN); bf16_t* HID = (bf16_t*)(ws + WS_HID); bf16_t* Y = (bf16_t*)(ws + WS_Y);
;     volatile LAS unsigned* xst = (volatile LAS unsigned*)(lds + 131072);
;     if (threadIdx.x == 0) { xst[0] = 0u; xst[1] = 0u; }
;     __syncthreads();
_Z6mk_fwd6Params:
	s_load_dwordx8 s[88:95], s[0:1], 0xc0
	s_load_dword s3, s[0:1], 0xe0
	s_add_u32 s4, s0, 0xe0
	s_addc_u32 s5, s1, 0
	s_mov_b32 s98, 0
	v_and_b32_e32 v166, 0x3ff, v0
	v_writelane_b32 v254, s4, 0
	v_cmp_eq_u32_e64 s[30:31], 0, v166
	s_nop 0
	v_writelane_b32 v254, s5, 1
	s_and_saveexec_b64 s[4:5], s[30:31]
	s_cbranch_execz .LBB0_2
	s_add_i32 s6, 0, 0x20000
	v_mov_b32_e32 v1, 0
	v_mov_b32_e32 v2, s6
	s_add_i32 s6, 0, 0x20004
	ds_write_b32 v2, v1
	v_mov_b32_e32 v2, s6
	ds_write_b32 v2, v1

; #define PG8_STAGE(bufoff, gbase, voff) do { _Pragma("unroll") for (int _i = 0; _i < 2; ++_i) \
;         __builtin_amdgcn_global_load_lds((const unsigned*)((const char*)(gbase) + (voff)[_i]), (PG8_LAS unsigned*)(lds + (bufoff) + ldsw + _i * 8192), 16, 0, 0); } while (0)
; #define PG8_LDA(dst, b, h) do { _Pragma("unroll") for (int m = 0; m < 4; ++m) _Pragma("unroll") for (int k = 0; k < 2; ++k) dst[m][k] = *(const PG8_LAS bf16x8*)(lds + PG8_SA(b, h) + aoff + m * 2048 + k * 1024); } while (0)
; #define PG8_LDB(dst, b, h) do { _Pragma("unroll") for (int n = 0; n < 2; ++n) _Pragma("unroll") for (int k = 0; k < 2; ++k) dst[n][k] = *(const PG8_LAS bf16x8*)(lds + PG8_SB(b, h) + boff + n * 2048 + k * 1024); } while (0)
; #define PG8_MMA(ai, bj, At, Bt) do { __builtin_amdgcn_s_setprio(1); _Pragma("unroll") for (int m = 0; m < 4; ++m) _Pragma("unroll") for (int n = 0; n < 2; ++n) _Pragma("unroll") for (int k = 0; k < 2; ++k) \
;         acc[ai][bj][m][n] = __builtin_amdgcn_mfma_f32_16x16x32_bf16(Bt[n][k], At[m][k], acc[ai][bj][m][n], 0, 0, 0); __builtin_amdgcn_s_setprio(0); } while (0)
; template <class Epi, class Sched, bool ALIGN_EPI = false, bool SP2 = false, bool ABLK = false>
; __device__ __forceinline__ void gemm_phase(PG8_LAS unsigned char* lds, const Gemm g, const Sched& S, const Epi& E) {
;     ...
;         const bool has_next = S.next(ui + 1, nxt);
;         const char* nA = has_next ? (const char*)g.A + (size_t)nxt.pm * tstep : cA; const char* nB = has_next ? (const char*)g.Bt + (size_t)nxt.pn * tstep : cB;
;         for (int t = 0; t < nt; t += 2) {
;             const bool last = (t == nt - 2);
;             const char* a1 = cA + (size_t)(t + 1) * kstepA;
;             const char* a2 = last ? nA : cA + (size_t)(t + 2) * kstepA; const char* b2 = last ? nB : cB + (size_t)(t + 2) * kstep;
;             const char* a3 = a2 + kstepA; const char* b3 = b2 + kstep;
;             if (last && has_next) S.a_ready(nxt);
;             if constexpr (SP2) {
;             PG8_LDB(B0, 0, 0); PG8_LDB(B1, 0, 1); PG8_SCHED; PG8_LDA(At, 0, 0); PG8_STAGE(PG8_SA(1, 1), a1 + hstepA, voffA);
;             PG8_WAIT_V(8); PG8_WAIT_L(0); PG8_BAR; PG8_MMA(0, 0, At, B0); PG8_MMA(0, 1, At, B1); PG8_BAR; PG8_SCHED;
;             PG8_LDA(At, 0, 1); PG8_STAGE(PG8_SB(0, 0), b2, voffB); PG8_STAGE(PG8_SB(0, 1), b2 + hstep, voffB); PG8_STAGE(PG8_SA(0, 0), a2, voffA);
.LBB0_174:
	s_ashr_i32 s17, s16, 31
	s_lshl_b64 s[18:19], s[16:17], 19
	s_add_u32 s18, s96, s18
	s_addc_u32 s19, s97, s19
	s_and_b64 s[20:21], s[0:1], exec
	s_cselect_b32 s17, s19, s25
	s_cselect_b32 s47, s18, s24
	s_ashr_i32 s15, s14, 31
	s_lshl_b64 s[20:21], s[14:15], 19
	s_add_u32 s20, s92, s20
	s_addc_u32 s21, s93, s21
	s_and_b64 s[28:29], s[0:1], exec
	s_cselect_b32 s15, s21, s27
	s_cselect_b32 s48, s20, s26
	s_add_u32 s24, s24, 0x40080
	s_addc_u32 s25, s25, 0
	s_add_u32 s49, s26, 0x100
	v_mov_b32_e32 v0, 0
	s_addc_u32 s50, s27, 0
	s_mov_b32 s51, -2
	s_cmp_eq_u32 s98, 1
	s_cbranch_scc0 .Ldefbar_0
	s_barrier
	s_mov_b32 s98, 0
.Ldefbar_0:
.LBB0_175:
	ds_read_b128 v[162:165], v159
	ds_read_b128 v[168:171], v159 offset:1024
	ds_read_b128 v[172:175], v159 offset:2048
	ds_read_b128 v[176:179], v159 offset:3072
	ds_read_b128 v[180:183], v160
	ds_read_b128 v[184:187], v160 offset:1024
	ds_read_b128 v[188:191], v160 offset:2048
	ds_read_b128 v[192:195], v160 offset:3072
	s_add_u32 s26, s24, 0xfffc0080
	s_addc_u32 s27, s25, -1
	s_cmp_eq_u32 s51, 12
	s_cselect_b32 s29, s17, s27
	s_cselect_b32 s28, s47, s26
	s_cselect_b32 s27, s15, s50
	s_cselect_b32 s26, s48, s49
	v_lshl_add_u64 v[156:157], s[24:25], 0, v[148:149]
	s_add_i32 m0, s23, 0xc000
	ds_read_b128 v[196:199], v161
	ds_read_b128 v[200:203], v161 offset:1024
	ds_read_b128 v[204:207], v161 offset:2048
	ds_read_b128 v[208:211], v161 offset:3072
	ds_read_b128 v[212:215], v161 offset:4096
	ds_read_b128 v[216:219], v161 offset:5120
	ds_read_b128 v[220:223], v161 offset:6144
	ds_read_b128 v[224:227], v161 offset:7168
	global_load_lds_dwordx4 v[156:157], off
	v_lshl_add_u64 v[156:157], s[24:25], 0, v[150:151]
	s_add_i32 m0, s23, 0xe000
	s_nop 0
	global_load_lds_dwordx4 v[156:157], off
	s_waitcnt vmcnt(8)
	s_waitcnt lgkmcnt(0)
	s_barrier
	s_setprio 1
	s_waitcnt lgkmcnt(0)
	v_mfma_f32_16x16x32_bf16 v[124:127], v[162:165], v[196:199], 0
	v_mfma_f32_16x16x32_bf16 v[120:123], v[172:175], v[196:199], 0
	v_mfma_f32_16x16x32_bf16 v[108:111], v[162:165], v[204:207], 0
	v_mfma_f32_16x16x32_bf16 v[104:107], v[172:175], v[204:207], 0
	v_mfma_f32_16x16x32_bf16 v[92:95], v[162:165], v[212:215], 0
	v_mfma_f32_16x16x32_bf16 v[88:91], v[172:175], v[212:215], 0
	v_mfma_f32_16x16x32_bf16 v[76:79], v[162:165], v[220:223], 0
	v_mfma_f32_16x16x32_bf16 v[72:75], v[172:175], v[220:223], 0
	v_mfma_f32_16x16x32_bf16 v[124:127], v[168:171], v[200:203], v[124:127]
	v_mfma_f32_16x16x32_bf16 v[120:123], v[176:179], v[200:203], v[120:123]
	v_mfma_f32_16x16x32_bf16 v[108:111], v[168:171], v[208:211], v[108:111]
	v_mfma_f32_16x16x32_bf16 v[104:107], v[176:179], v[208:211], v[104:107]
	v_mfma_f32_16x16x32_bf16 v[92:95], v[168:171], v[216:219], v[92:95]
	v_mfma_f32_16x16x32_bf16 v[88:91], v[176:179], v[216:219], v[88:91]
	v_mfma_f32_16x16x32_bf16 v[76:79], v[168:171], v[224:227], v[76:79]
	v_mfma_f32_16x16x32_bf16 v[72:75], v[176:179], v[224:227], v[72:75]
	s_setprio 0
	s_setprio 1
	v_mfma_f32_16x16x32_bf16 v[116:119], v[180:183], v[196:199], 0
	v_mfma_f32_16x16x32_bf16 v[112:115], v[188:191], v[196:199], 0
	v_mfma_f32_16x16x32_bf16 v[100:103], v[180:183], v[204:207], 0
	v_mfma_f32_16x16x32_bf16 v[96:99], v[188:191], v[204:207], 0
	v_mfma_f32_16x16x32_bf16 v[84:87], v[180:183], v[212:215], 0
	v_mfma_f32_16x16x32_bf16 v[80:83], v[188:191], v[212:215], 0
	v_mfma_f32_16x16x32_bf16 v[68:71], v[180:183], v[220:223], 0
	v_mfma_f32_16x16x32_bf16 v[64:67], v[188:191], v[220:223], 0
	v_mfma_f32_16x16x32_bf16 v[116:119], v[184:187], v[200:203], v[116:119]
	v_mfma_f32_16x16x32_bf16 v[112:115], v[192:195], v[200:203], v[112:115]
	v_mfma_f32_16x16x32_bf16 v[100:103], v[184:187], v[208:211], v[100:103]
	v_mfma_f32_16x16x32_bf16 v[96:99], v[192:195], v[208:211], v[96:99]
	v_mfma_f32_16x16x32_bf16 v[84:87], v[184:187], v[216:219], v[84:87]
	v_mfma_f32_16x16x32_bf16 v[80:83], v[192:195], v[216:219], v[80:83]
	v_mfma_f32_16x16x32_bf16 v[68:71], v[184:187], v[224:227], v[68:71]
	v_mfma_f32_16x16x32_bf16 v[64:67], v[192:195], v[224:227], v[64:67]
	s_setprio 0
	s_barrier
	s_add_i32 s53, s43, s30
	v_lshl_add_u64 v[156:157], s[26:27], 0, v[132:133]
	s_mov_b32 m0, s53
	ds_read_b128 v[196:199], v161 offset:16384
	ds_read_b128 v[200:203], v161 offset:17408
	ds_read_b128 v[204:207], v161 offset:18432
	ds_read_b128 v[208:211], v161 offset:19456
	ds_read_b128 v[212:215], v161 offset:20480
	ds_read_b128 v[216:219], v161 offset:21504
	ds_read_b128 v[220:223], v161 offset:22528
	ds_read_b128 v[224:227], v161 offset:23552
	global_load_lds_dwordx4 v[156:157], off
	s_add_i32 m0, s53, 0x2000
	s_add_u32 s54, s26, 0x40000
	v_lshl_add_u64 v[228:229], s[26:27], 0, v[128:129]
	s_addc_u32 s55, s27, 0
	s_add_i32 s53, s44, s30
	global_load_lds_dwordx4 v[228:229], off
	v_lshl_add_u64 v[230:231], s[54:55], 0, v[132:133]
	s_mov_b32 m0, s53
	v_lshl_add_u64 v[232:233], s[28:29], 0, v[130:131]
	global_load_lds_dwordx4 v[230:231], off
	v_lshl_add_u64 v[230:231], s[54:55], 0, v[128:129]
	s_add_i32 m0, s53, 0x2000
	s_nop 0
	global_load_lds_dwordx4 v[230:231], off
	v_lshl_add_u64 v[230:231], s[28:29], 0, v[134:135]
	s_mov_b32 m0, s23
	s_nop 0
	global_load_lds_dwordx4 v[230:231], off
	s_mov_b32 m0, s34
	s_nop 0
	global_load_lds_dwordx4 v[232:233], off
	s_waitcnt vmcnt(8)
	s_waitcnt lgkmcnt(0)
	s_barrier
; #define PG8_STAGE(bufoff, gbase, voff) do { _Pragma("unroll") for (int _i = 0; _i < 2; ++_i) \
;         __builtin_amdgcn_global_load_lds((const unsigned*)((const char*)(gbase) + (voff)[_i]), (PG8_LAS unsigned*)(lds + (bufoff) + ldsw + _i * 8192), 16, 0, 0); } while (0)
; #define PG8_LDA(dst, b, h) do { _Pragma("unroll") for (int m = 0; m < 4; ++m) _Pragma("unroll") for (int k = 0; k < 2; ++k) dst[m][k] = *(const PG8_LAS bf16x8*)(lds + PG8_SA(b, h) + aoff + m * 2048 + k * 1024); } while (0)
; #define PG8_LDB(dst, b, h) do { _Pragma("unroll") for (int n = 0; n < 2; ++n) _Pragma("unroll") for (int k = 0; k < 2; ++k) dst[n][k] = *(const PG8_LAS bf16x8*)(lds + PG8_SB(b, h) + boff + n * 2048 + k * 1024); } while (0)
; #define PG8_MMA(ai, bj, At, Bt) do { __builtin_amdgcn_s_setprio(1); _Pragma("unroll") for (int m = 0; m < 4; ++m) _Pragma("unroll") for (int n = 0; n < 2; ++n) _Pragma("unroll") for (int k = 0; k < 2; ++k) \
;         acc[ai][bj][m][n] = __builtin_amdgcn_mfma_f32_16x16x32_bf16(Bt[n][k], At[m][k], acc[ai][bj][m][n], 0, 0, 0); __builtin_amdgcn_s_setprio(0); } while (0)
; #define PG8_WAIT_V(n) asm volatile("s_waitcnt vmcnt(" #n ")" ::: "memory")
; #define PG8_WAIT_L(n) asm volatile("s_waitcnt lgkmcnt(" #n ")" ::: "memory")
; #define PG8_BAR __builtin_amdgcn_s_barrier()
; #define PG8_SCHED __builtin_amdgcn_sched_barrier(0)
; template <class Epi, class Sched, bool ALIGN_EPI = false, bool SP2 = false, bool ABLK = false>
; __device__ __forceinline__ void gemm_phase(PG8_LAS unsigned char* lds, const Gemm g, const Sched& S, const Epi& E) {
;     ...
;             PG8_WAIT_V(8); PG8_WAIT_L(0); PG8_BAR; PG8_MMA(1, 0, At, B0); PG8_MMA(1, 1, At, B1); PG8_BAR; PG8_SCHED;
;             PG8_LDB(B0, 1, 0); PG8_LDB(B1, 1, 1); PG8_SCHED; PG8_LDA(At, 1, 0); PG8_STAGE(PG8_SA(0, 1), a2 + hstepA, voffA);
;             PG8_WAIT_V(8); PG8_WAIT_L(0); PG8_BAR; PG8_MMA(0, 0, At, B0); PG8_MMA(0, 1, At, B1); PG8_BAR; PG8_SCHED;
	s_setprio 1
	s_waitcnt lgkmcnt(0)
	v_mfma_f32_16x16x32_bf16 v[60:63], v[162:165], v[196:199], 0
	v_mfma_f32_16x16x32_bf16 v[56:59], v[172:175], v[196:199], 0
	v_mfma_f32_16x16x32_bf16 v[44:47], v[162:165], v[204:207], 0
	v_mfma_f32_16x16x32_bf16 v[40:43], v[172:175], v[204:207], 0
	v_mfma_f32_16x16x32_bf16 v[28:31], v[162:165], v[212:215], 0
	v_mfma_f32_16x16x32_bf16 v[24:27], v[172:175], v[212:215], 0
	v_mfma_f32_16x16x32_bf16 v[12:15], v[162:165], v[220:223], 0
	v_mfma_f32_16x16x32_bf16 v[8:11], v[172:175], v[220:223], 0
	v_mfma_f32_16x16x32_bf16 v[60:63], v[168:171], v[200:203], v[60:63]
	v_mfma_f32_16x16x32_bf16 v[56:59], v[176:179], v[200:203], v[56:59]
	v_mfma_f32_16x16x32_bf16 v[44:47], v[168:171], v[208:211], v[44:47]
	v_mfma_f32_16x16x32_bf16 v[40:43], v[176:179], v[208:211], v[40:43]
	v_mfma_f32_16x16x32_bf16 v[28:31], v[168:171], v[216:219], v[28:31]
	v_mfma_f32_16x16x32_bf16 v[24:27], v[176:179], v[216:219], v[24:27]
	v_mfma_f32_16x16x32_bf16 v[12:15], v[168:171], v[224:227], v[12:15]
	v_mfma_f32_16x16x32_bf16 v[8:11], v[176:179], v[224:227], v[8:11]
	s_setprio 0
	s_setprio 1
	v_mfma_f32_16x16x32_bf16 v[52:55], v[180:183], v[196:199], 0
	v_mfma_f32_16x16x32_bf16 v[48:51], v[188:191], v[196:199], 0
	v_mfma_f32_16x16x32_bf16 v[36:39], v[180:183], v[204:207], 0
	v_mfma_f32_16x16x32_bf16 v[32:35], v[188:191], v[204:207], 0
	v_mfma_f32_16x16x32_bf16 v[20:23], v[180:183], v[212:215], 0
	v_mfma_f32_16x16x32_bf16 v[16:19], v[188:191], v[212:215], 0
	v_mfma_f32_16x16x32_bf16 v[4:7], v[180:183], v[220:223], 0
	v_mfma_f32_16x16x32_bf16 v[0:3], v[188:191], v[220:223], 0
	v_mfma_f32_16x16x32_bf16 v[52:55], v[184:187], v[200:203], v[52:55]
	v_mfma_f32_16x16x32_bf16 v[48:51], v[192:195], v[200:203], v[48:51]
	v_mfma_f32_16x16x32_bf16 v[36:39], v[184:187], v[208:211], v[36:39]
	v_mfma_f32_16x16x32_bf16 v[32:35], v[192:195], v[208:211], v[32:35]
	v_mfma_f32_16x16x32_bf16 v[20:23], v[184:187], v[216:219], v[20:23]
	v_mfma_f32_16x16x32_bf16 v[16:19], v[192:195], v[216:219], v[16:19]
	v_mfma_f32_16x16x32_bf16 v[4:7], v[184:187], v[224:227], v[4:7]
	v_mfma_f32_16x16x32_bf16 v[0:3], v[192:195], v[224:227], v[0:3]
	s_setprio 0
	s_barrier
	s_add_i32 s53, 0, 0x18000
	v_add_u32_e32 v167, s53, v158
	s_add_i32 s54, 0, 0x1c000
	ds_read_b128 v[162:165], v167
	ds_read_b128 v[168:171], v167 offset:1024
	ds_read_b128 v[172:175], v167 offset:2048
	ds_read_b128 v[176:179], v167 offset:3072
	v_add_u32_e32 v167, s54, v158
	ds_read_b128 v[180:183], v167
	ds_read_b128 v[184:187], v167 offset:1024
	ds_read_b128 v[188:191], v167 offset:2048
	ds_read_b128 v[192:195], v167 offset:3072
	s_add_u32 s28, s28, 0x40000
	s_addc_u32 s29, s29, 0
	s_mov_b32 m0, s35
	v_lshl_add_u64 v[234:235], s[28:29], 0, v[134:135]
	ds_read_b128 v[196:199], v161 offset:32768
	ds_read_b128 v[200:203], v161 offset:33792
	ds_read_b128 v[204:207], v161 offset:34816
	ds_read_b128 v[208:211], v161 offset:35840
	ds_read_b128 v[212:215], v161 offset:36864
	ds_read_b128 v[216:219], v161 offset:37888
	ds_read_b128 v[220:223], v161 offset:38912
	ds_read_b128 v[224:227], v161 offset:39936
	global_load_lds_dwordx4 v[234:235], off
	v_lshl_add_u64 v[234:235], s[28:29], 0, v[130:131]
	s_mov_b32 m0, s38
	s_nop 0
	global_load_lds_dwordx4 v[234:235], off
	s_waitcnt vmcnt(8)
	s_waitcnt lgkmcnt(0)
	s_barrier
	s_setprio 1
	s_waitcnt lgkmcnt(0)
	v_mfma_f32_16x16x32_bf16 v[124:127], v[162:165], v[196:199], v[124:127]
	v_mfma_f32_16x16x32_bf16 v[120:123], v[172:175], v[196:199], v[120:123]
	v_mfma_f32_16x16x32_bf16 v[108:111], v[162:165], v[204:207], v[108:111]
	v_mfma_f32_16x16x32_bf16 v[104:107], v[172:175], v[204:207], v[104:107]
	v_mfma_f32_16x16x32_bf16 v[92:95], v[162:165], v[212:215], v[92:95]
	v_mfma_f32_16x16x32_bf16 v[88:91], v[172:175], v[212:215], v[88:91]
	v_mfma_f32_16x16x32_bf16 v[76:79], v[162:165], v[220:223], v[76:79]
	v_mfma_f32_16x16x32_bf16 v[72:75], v[172:175], v[220:223], v[72:75]
	v_mfma_f32_16x16x32_bf16 v[124:127], v[168:171], v[200:203], v[124:127]
	v_mfma_f32_16x16x32_bf16 v[120:123], v[176:179], v[200:203], v[120:123]
	v_mfma_f32_16x16x32_bf16 v[108:111], v[168:171], v[208:211], v[108:111]
	v_mfma_f32_16x16x32_bf16 v[104:107], v[176:179], v[208:211], v[104:107]
	v_mfma_f32_16x16x32_bf16 v[92:95], v[168:171], v[216:219], v[92:95]
	v_mfma_f32_16x16x32_bf16 v[88:91], v[176:179], v[216:219], v[88:91]
	v_mfma_f32_16x16x32_bf16 v[76:79], v[168:171], v[224:227], v[76:79]
	v_mfma_f32_16x16x32_bf16 v[72:75], v[176:179], v[224:227], v[72:75]
	s_setprio 0
	s_setprio 1
	v_mfma_f32_16x16x32_bf16 v[116:119], v[180:183], v[196:199], v[116:119]
	v_mfma_f32_16x16x32_bf16 v[112:115], v[188:191], v[196:199], v[112:115]
	v_mfma_f32_16x16x32_bf16 v[100:103], v[180:183], v[204:207], v[100:103]
	v_mfma_f32_16x16x32_bf16 v[96:99], v[188:191], v[204:207], v[96:99]
	v_mfma_f32_16x16x32_bf16 v[84:87], v[180:183], v[212:215], v[84:87]
	v_mfma_f32_16x16x32_bf16 v[80:83], v[188:191], v[212:215], v[80:83]
	v_mfma_f32_16x16x32_bf16 v[68:71], v[180:183], v[220:223], v[68:71]
	v_mfma_f32_16x16x32_bf16 v[64:67], v[188:191], v[220:223], v[64:67]
	v_mfma_f32_16x16x32_bf16 v[116:119], v[184:187], v[200:203], v[116:119]
	v_mfma_f32_16x16x32_bf16 v[112:115], v[192:195], v[200:203], v[112:115]
	v_mfma_f32_16x16x32_bf16 v[100:103], v[184:187], v[208:211], v[100:103]
	v_mfma_f32_16x16x32_bf16 v[96:99], v[192:195], v[208:211], v[96:99]
	v_mfma_f32_16x16x32_bf16 v[84:87], v[184:187], v[216:219], v[84:87]
	v_mfma_f32_16x16x32_bf16 v[80:83], v[192:195], v[216:219], v[80:83]
	v_mfma_f32_16x16x32_bf16 v[68:71], v[184:187], v[224:227], v[68:71]
	v_mfma_f32_16x16x32_bf16 v[64:67], v[192:195], v[224:227], v[64:67]
	s_setprio 0
	s_barrier
; #define PG8_STAGE(bufoff, gbase, voff) do { _Pragma("unroll") for (int _i = 0; _i < 2; ++_i) \
;         __builtin_amdgcn_global_load_lds((const unsigned*)((const char*)(gbase) + (voff)[_i]), (PG8_LAS unsigned*)(lds + (bufoff) + ldsw + _i * 8192), 16, 0, 0); } while (0)
; #define PG8_LDA(dst, b, h) do { _Pragma("unroll") for (int m = 0; m < 4; ++m) _Pragma("unroll") for (int k = 0; k < 2; ++k) dst[m][k] = *(const PG8_LAS bf16x8*)(lds + PG8_SA(b, h) + aoff + m * 2048 + k * 1024); } while (0)
; #define PG8_MMA(ai, bj, At, Bt) do { __builtin_amdgcn_s_setprio(1); _Pragma("unroll") for (int m = 0; m < 4; ++m) _Pragma("unroll") for (int n = 0; n < 2; ++n) _Pragma("unroll") for (int k = 0; k < 2; ++k) \
;         acc[ai][bj][m][n] = __builtin_amdgcn_mfma_f32_16x16x32_bf16(Bt[n][k], At[m][k], acc[ai][bj][m][n], 0, 0, 0); __builtin_amdgcn_s_setprio(0); } while (0)
; #define PG8_WAIT_V(n) asm volatile("s_waitcnt vmcnt(" #n ")" ::: "memory")
; #define PG8_WAIT_L(n) asm volatile("s_waitcnt lgkmcnt(" #n ")" ::: "memory")
; #define PG8_BAR __builtin_amdgcn_s_barrier()
; #define PG8_SCHED __builtin_amdgcn_sched_barrier(0)
; template <class Epi, class Sched, bool ALIGN_EPI = false, bool SP2 = false, bool ABLK = false>
; __device__ __forceinline__ void gemm_phase(PG8_LAS unsigned char* lds, const Gemm g, const Sched& S, const Epi& E) {
;     ...
;             PG8_WAIT_V(8); PG8_WAIT_L(0); PG8_BAR; PG8_MMA(0, 0, At, B0); PG8_MMA(0, 1, At, B1); PG8_BAR; PG8_SCHED;
;             PG8_LDA(At, 1, 1); PG8_STAGE(PG8_SB(1, 0), b3, voffB); PG8_STAGE(PG8_SB(1, 1), b3 + hstep, voffB); PG8_STAGE(PG8_SA(1, 0), a3, voffA);
;             PG8_WAIT_V(8); PG8_WAIT_L(0); PG8_BAR; PG8_MMA(1, 0, At, B0); PG8_MMA(1, 1, At, B1); PG8_BAR; PG8_SCHED;
	s_add_i32 s28, s53, s30
	v_lshl_add_u64 v[156:157], v[156:157], 0, s[8:9]
	s_mov_b32 m0, s28
	ds_read_b128 v[196:199], v161 offset:49152
	ds_read_b128 v[200:203], v161 offset:50176
	ds_read_b128 v[204:207], v161 offset:51200
	ds_read_b128 v[208:211], v161 offset:52224
	ds_read_b128 v[212:215], v161 offset:53248
	ds_read_b128 v[216:219], v161 offset:54272
	ds_read_b128 v[220:223], v161 offset:55296
	ds_read_b128 v[224:227], v161 offset:56320
	global_load_lds_dwordx4 v[156:157], off
	s_add_i32 m0, s28, 0x2000
	s_add_u32 s26, s26, 0x40080
	v_lshl_add_u64 v[156:157], v[228:229], 0, s[8:9]
	s_addc_u32 s27, s27, 0
	s_add_i32 s28, s54, s30
	global_load_lds_dwordx4 v[156:157], off
	v_lshl_add_u64 v[156:157], s[26:27], 0, v[132:133]
	s_mov_b32 m0, s28
	s_nop 0
	global_load_lds_dwordx4 v[156:157], off
	v_lshl_add_u64 v[156:157], s[26:27], 0, v[128:129]
	s_add_i32 m0, s28, 0x2000
	s_nop 0
	global_load_lds_dwordx4 v[156:157], off
	v_lshl_add_u64 v[156:157], v[230:231], 0, s[8:9]
	s_mov_b32 m0, s41
	s_nop 0
	global_load_lds_dwordx4 v[156:157], off
	v_lshl_add_u64 v[156:157], v[232:233], 0, s[8:9]
	s_mov_b32 m0, s42
	s_nop 0
	global_load_lds_dwordx4 v[156:157], off
	s_waitcnt vmcnt(8)
	s_waitcnt lgkmcnt(0)
	s_barrier
	s_setprio 1
	s_waitcnt lgkmcnt(0)
	v_mfma_f32_16x16x32_bf16 v[60:63], v[162:165], v[196:199], v[60:63]
	v_mfma_f32_16x16x32_bf16 v[56:59], v[172:175], v[196:199], v[56:59]
	v_mfma_f32_16x16x32_bf16 v[44:47], v[162:165], v[204:207], v[44:47]
	v_mfma_f32_16x16x32_bf16 v[40:43], v[172:175], v[204:207], v[40:43]
	v_mfma_f32_16x16x32_bf16 v[28:31], v[162:165], v[212:215], v[28:31]
	v_mfma_f32_16x16x32_bf16 v[24:27], v[172:175], v[212:215], v[24:27]
	v_mfma_f32_16x16x32_bf16 v[12:15], v[162:165], v[220:223], v[12:15]
	v_mfma_f32_16x16x32_bf16 v[8:11], v[172:175], v[220:223], v[8:11]
	v_mfma_f32_16x16x32_bf16 v[60:63], v[168:171], v[200:203], v[60:63]
	v_mfma_f32_16x16x32_bf16 v[56:59], v[176:179], v[200:203], v[56:59]
	v_mfma_f32_16x16x32_bf16 v[44:47], v[168:171], v[208:211], v[44:47]
	v_mfma_f32_16x16x32_bf16 v[40:43], v[176:179], v[208:211], v[40:43]
	v_mfma_f32_16x16x32_bf16 v[28:31], v[168:171], v[216:219], v[28:31]
	v_mfma_f32_16x16x32_bf16 v[24:27], v[176:179], v[216:219], v[24:27]
	v_mfma_f32_16x16x32_bf16 v[12:15], v[168:171], v[224:227], v[12:15]
	v_mfma_f32_16x16x32_bf16 v[8:11], v[176:179], v[224:227], v[8:11]
	s_setprio 0
	s_setprio 1
	v_mfma_f32_16x16x32_bf16 v[52:55], v[180:183], v[196:199], v[52:55]
	v_mfma_f32_16x16x32_bf16 v[48:51], v[188:191], v[196:199], v[48:51]
	v_mfma_f32_16x16x32_bf16 v[36:39], v[180:183], v[204:207], v[36:39]
	v_mfma_f32_16x16x32_bf16 v[32:35], v[188:191], v[204:207], v[32:35]
	v_mfma_f32_16x16x32_bf16 v[20:23], v[180:183], v[212:215], v[20:23]
	v_mfma_f32_16x16x32_bf16 v[16:19], v[188:191], v[212:215], v[16:19]
	v_mfma_f32_16x16x32_bf16 v[4:7], v[180:183], v[220:223], v[4:7]
	v_mfma_f32_16x16x32_bf16 v[0:3], v[188:191], v[220:223], v[0:3]
	v_mfma_f32_16x16x32_bf16 v[52:55], v[184:187], v[200:203], v[52:55]
	v_mfma_f32_16x16x32_bf16 v[48:51], v[192:195], v[200:203], v[48:51]
	v_mfma_f32_16x16x32_bf16 v[36:39], v[184:187], v[208:211], v[36:39]
	v_mfma_f32_16x16x32_bf16 v[32:35], v[192:195], v[208:211], v[32:35]
	v_mfma_f32_16x16x32_bf16 v[20:23], v[184:187], v[216:219], v[20:23]
	v_mfma_f32_16x16x32_bf16 v[16:19], v[192:195], v[216:219], v[16:19]
	v_mfma_f32_16x16x32_bf16 v[4:7], v[184:187], v[224:227], v[4:7]
	v_mfma_f32_16x16x32_bf16 v[0:3], v[192:195], v[224:227], v[0:3]
	s_setprio 0
	s_barrier
	s_add_i32 s51, s51, 2
	s_add_u32 s24, s24, 0x100
	s_addc_u32 s25, s25, 0
	s_add_u32 s49, s49, 0x100
	s_addc_u32 s50, s50, 0
	s_cmp_gt_u32 s51, 13
	s_cbranch_scc1 .Lpeel_post_0

; __device__ __forceinline__ float silu_f(float g) { return g * __builtin_amdgcn_rcpf(1.f + __builtin_amdgcn_exp2f(-1.4426950408889634f * g)); }
; __device__ __forceinline__ u32x4 pack8(f32x4 a, f32x4 b) { u32x4 o; o.x = cvt_pk(a.x, a.y); o.y = cvt_pk(a.z, a.w); o.z = cvt_pk(b.x, b.y); o.w = cvt_pk(b.z, b.w); return o; }
; __device__ __forceinline__ float rstd_of(const float* SS, int row, float invw) { return 1.0f / sqrtf(SS[row] * invw + EPS); }
;     __device__ __forceinline__ void operator()(const f32x4 (&acc)[2][2][4][2], const pg8::Unit& u, int wr, int wc, int fr, int fq) const {
;         const int row0 = u.pm * 256 + wr * 64 + fr, col0 = u.pn * 128 + wc * 32 + 8 * fq;
;         bf16_t* hb = H + (size_t)u.pm * 256 * FF + (size_t)(col0 >> 6) * (256 * 64) + (col0 & 63);
; #pragma unroll
;         for (int ai = 0; ai < 2; ++ai)
; #pragma unroll
;             for (int m = 0; m < 4; ++m) {
;                 const int row = row0 + ai * 128 + m * 16;
;                 const float r = SCALE ? rstd_of(SS, row, 1.f / 1024.f) : 1.f;
;                 const f32x4 g0 = acc[ai][0][m][0] * r, g1 = acc[ai][0][m][1] * r, u0 = acc[ai][1][m][0] * r, u1 = acc[ai][1][m][1] * r;
;                 f32x4 h0, h1;
;                 h0.x = silu_f(g0.x) * u0.x; h0.y = silu_f(g0.y) * u0.y; h0.z = silu_f(g0.z) * u0.z; h0.w = silu_f(g0.w) * u0.w;
;                 h1.x = silu_f(g1.x) * u1.x; h1.y = silu_f(g1.y) * u1.y; h1.z = silu_f(g1.z) * u1.z; h1.w = silu_f(g1.w) * u1.w;
;                 *(u32x4*)(hb + (wr * 64 + fr + ai * 128 + m * 16) * 64) = pack8(h0, h1);
.LBB0_178:
	s_lshl_b32 s15, s46, 7
	s_or_b32 s15, s15, s40
	s_mul_hi_i32 s17, s22, 0x160000
	s_mul_i32 s22, s22, 0x160000
	s_add_u32 s22, s64, s22
	s_addc_u32 s17, s65, s17
	s_ashr_i32 s24, s15, 6
	s_ashr_i32 s25, s24, 31
	s_lshl_b64 s[24:25], s[24:25], 15
	s_add_u32 s24, s22, s24
	s_addc_u32 s25, s17, s25
	v_mov_b32_e32 v162, 0xbfb8aa3b
	v_mov_b32_e32 v163, 0xbfb8aa3b
	v_mov_b32_e32 v164, 1.0
	v_mov_b32_e32 v165, 1.0
	v_lshl_add_u64 v[156:157], s[24:25], 0, v[136:137]
	v_lshl_add_u64 v[168:169], v[138:139], 1, v[156:157]
	v_add_co_u32_e32 v170, vcc, s45, v168
	v_addc_co_u32_e32 v171, vcc, 0, v169, vcc
	v_lshl_add_u64 v[172:173], v[140:141], 1, v[156:157]
	v_lshl_add_u64 v[174:175], v[142:143], 1, v[156:157]
	v_lshl_add_u64 v[176:177], v[144:145], 1, v[156:157]
	v_lshl_add_u64 v[194:195], v[146:147], 1, v[156:157]
	v_pk_mul_f32 v[178:179], v[124:125], v[162:163]
	v_pk_mul_f32 v[180:181], v[126:127], v[162:163]
	v_pk_mul_f32 v[182:183], v[120:121], v[162:163]
	v_pk_mul_f32 v[184:185], v[122:123], v[162:163]
	v_exp_f32_e32 v178, v178
	v_exp_f32_e32 v179, v179
	v_exp_f32_e32 v180, v180
	v_exp_f32_e32 v181, v181
	v_exp_f32_e32 v182, v182
	v_exp_f32_e32 v183, v183
	v_exp_f32_e32 v184, v184
	v_exp_f32_e32 v185, v185
	v_pk_add_f32 v[178:179], v[178:179], v[164:165]
	v_pk_add_f32 v[180:181], v[180:181], v[164:165]
	v_pk_add_f32 v[182:183], v[182:183], v[164:165]
	v_pk_add_f32 v[184:185], v[184:185], v[164:165]
	v_rcp_f32_e32 v178, v178
	v_rcp_f32_e32 v179, v179
	v_rcp_f32_e32 v180, v180
	v_rcp_f32_e32 v181, v181
	v_rcp_f32_e32 v182, v182
	v_rcp_f32_e32 v183, v183
	v_rcp_f32_e32 v184, v184
	v_rcp_f32_e32 v185, v185
	v_pk_mul_f32 v[178:179], v[124:125], v[178:179]
	v_pk_mul_f32 v[180:181], v[126:127], v[180:181]
	v_pk_mul_f32 v[182:183], v[120:121], v[182:183]
	v_pk_mul_f32 v[184:185], v[122:123], v[184:185]
	v_pk_mul_f32 v[178:179], v[178:179], v[116:117]
	v_pk_mul_f32 v[180:181], v[180:181], v[118:119]
	v_pk_mul_f32 v[182:183], v[182:183], v[112:113]
	v_pk_mul_f32 v[184:185], v[184:185], v[114:115]
	v_cvt_pk_bf16_f32 v112, v178, v179
	v_cvt_pk_bf16_f32 v113, v180, v181
	v_cvt_pk_bf16_f32 v114, v182, v183
	v_cvt_pk_bf16_f32 v115, v184, v185
	global_store_dwordx4 v[168:169], v[112:115], off
	v_pk_mul_f32 v[186:187], v[108:109], v[162:163]
	v_pk_mul_f32 v[188:189], v[110:111], v[162:163]
	v_pk_mul_f32 v[190:191], v[104:105], v[162:163]
	v_pk_mul_f32 v[192:193], v[106:107], v[162:163]
	v_exp_f32_e32 v186, v186
	v_exp_f32_e32 v187, v187
	v_exp_f32_e32 v188, v188
	v_exp_f32_e32 v189, v189
	v_exp_f32_e32 v190, v190
	v_exp_f32_e32 v191, v191
	v_exp_f32_e32 v192, v192
	v_exp_f32_e32 v193, v193
	v_pk_add_f32 v[186:187], v[186:187], v[164:165]
	v_pk_add_f32 v[188:189], v[188:189], v[164:165]
	v_pk_add_f32 v[190:191], v[190:191], v[164:165]
	v_pk_add_f32 v[192:193], v[192:193], v[164:165]
	v_rcp_f32_e32 v186, v186
	v_rcp_f32_e32 v187, v187
	v_rcp_f32_e32 v188, v188
	v_rcp_f32_e32 v189, v189
	v_rcp_f32_e32 v190, v190
	v_rcp_f32_e32 v191, v191
	v_rcp_f32_e32 v192, v192
	v_rcp_f32_e32 v193, v193
	v_pk_mul_f32 v[186:187], v[108:109], v[186:187]
	v_pk_mul_f32 v[188:189], v[110:111], v[188:189]
	v_pk_mul_f32 v[190:191], v[104:105], v[190:191]
	v_pk_mul_f32 v[192:193], v[106:107], v[192:193]
	v_pk_mul_f32 v[186:187], v[186:187], v[100:101]
	v_pk_mul_f32 v[188:189], v[188:189], v[102:103]
	v_pk_mul_f32 v[190:191], v[190:191], v[96:97]
	v_pk_mul_f32 v[192:193], v[192:193], v[98:99]
	v_cvt_pk_bf16_f32 v96, v186, v187
	v_cvt_pk_bf16_f32 v97, v188, v189
	v_cvt_pk_bf16_f32 v98, v190, v191
	v_cvt_pk_bf16_f32 v99, v192, v193
	global_store_dwordx4 v[168:169], v[96:99], off offset:2048
	v_pk_mul_f32 v[178:179], v[92:93], v[162:163]
	v_pk_mul_f32 v[180:181], v[94:95], v[162:163]
	v_pk_mul_f32 v[182:183], v[88:89], v[162:163]
	v_pk_mul_f32 v[184:185], v[90:91], v[162:163]
	v_exp_f32_e32 v178, v178
	v_exp_f32_e32 v179, v179
	v_exp_f32_e32 v180, v180
	v_exp_f32_e32 v181, v181
	v_exp_f32_e32 v182, v182
	v_exp_f32_e32 v183, v183
	v_exp_f32_e32 v184, v184
	v_exp_f32_e32 v185, v185
	v_pk_add_f32 v[178:179], v[178:179], v[164:165]
	v_pk_add_f32 v[180:181], v[180:181], v[164:165]
	v_pk_add_f32 v[182:183], v[182:183], v[164:165]
	v_pk_add_f32 v[184:185], v[184:185], v[164:165]
	v_rcp_f32_e32 v178, v178
	v_rcp_f32_e32 v179, v179
	v_rcp_f32_e32 v180, v180
	v_rcp_f32_e32 v181, v181
	v_rcp_f32_e32 v182, v182
	v_rcp_f32_e32 v183, v183
	v_rcp_f32_e32 v184, v184
	v_rcp_f32_e32 v185, v185
	v_pk_mul_f32 v[178:179], v[92:93], v[178:179]
	v_pk_mul_f32 v[180:181], v[94:95], v[180:181]
	v_pk_mul_f32 v[182:183], v[88:89], v[182:183]
	v_pk_mul_f32 v[184:185], v[90:91], v[184:185]
	v_pk_mul_f32 v[178:179], v[178:179], v[84:85]
	v_pk_mul_f32 v[180:181], v[180:181], v[86:87]
	v_pk_mul_f32 v[182:183], v[182:183], v[80:81]
	v_pk_mul_f32 v[184:185], v[184:185], v[82:83]
	v_cvt_pk_bf16_f32 v80, v178, v179
	v_cvt_pk_bf16_f32 v81, v180, v181
	v_cvt_pk_bf16_f32 v82, v182, v183
	v_cvt_pk_bf16_f32 v83, v184, v185
	global_store_dwordx4 v[170:171], v[80:83], off
	v_pk_mul_f32 v[186:187], v[76:77], v[162:163]
	v_pk_mul_f32 v[188:189], v[78:79], v[162:163]
	v_pk_mul_f32 v[190:191], v[72:73], v[162:163]
	v_pk_mul_f32 v[192:193], v[74:75], v[162:163]
	v_exp_f32_e32 v186, v186
	v_exp_f32_e32 v187, v187
	v_exp_f32_e32 v188, v188
	v_exp_f32_e32 v189, v189
	v_exp_f32_e32 v190, v190
	v_exp_f32_e32 v191, v191
	v_exp_f32_e32 v192, v192
	v_exp_f32_e32 v193, v193
	v_pk_add_f32 v[186:187], v[186:187], v[164:165]
	v_pk_add_f32 v[188:189], v[188:189], v[164:165]
	v_pk_add_f32 v[190:191], v[190:191], v[164:165]
	v_pk_add_f32 v[192:193], v[192:193], v[164:165]
	v_rcp_f32_e32 v186, v186
	v_rcp_f32_e32 v187, v187
	v_rcp_f32_e32 v188, v188
; #define PG8_BAR __builtin_amdgcn_s_barrier()
; __device__ __forceinline__ float silu_f(float g) { return g * __builtin_amdgcn_rcpf(1.f + __builtin_amdgcn_exp2f(-1.4426950408889634f * g)); }
; __device__ __forceinline__ u32x4 pack8(f32x4 a, f32x4 b) { u32x4 o; o.x = cvt_pk(a.x, a.y); o.y = cvt_pk(a.z, a.w); o.z = cvt_pk(b.x, b.y); o.w = cvt_pk(b.z, b.w); return o; }
; __device__ __forceinline__ float rstd_of(const float* SS, int row, float invw) { return 1.0f / sqrtf(SS[row] * invw + EPS); }
; template <class Epi, class Sched, bool ALIGN_EPI = false, bool SP2 = false, bool ABLK = false>
; __device__ __forceinline__ void gemm_phase(PG8_LAS unsigned char* lds, const Gemm g, const Sched& S, const Epi& E) {
;     ...
;         if (!has_next) break;
; #pragma unroll
;         for (int a = 0; a < 2; ++a)
; #pragma unroll
;             for (int b = 0; b < 2; ++b)
; #pragma unroll
;                 for (int m = 0; m < 4; ++m)
; #pragma unroll
;                     for (int n = 0; n < 2; ++n) acc[a][b][m][n] = (f32x4){0.f, 0.f, 0.f, 0.f};
;         cur = nxt; cA = nA; cB = nB; ++ui;
;         if constexpr (ALIGN_EPI) { if (wr == 1) PG8_BAR; }
;     __device__ __forceinline__ void operator()(const f32x4 (&acc)[2][2][4][2], const pg8::Unit& u, int wr, int wc, int fr, int fq) const {
;     ...
;             for (int m = 0; m < 4; ++m) {
;                 const int row = row0 + ai * 128 + m * 16;
;                 const float r = SCALE ? rstd_of(SS, row, 1.f / 1024.f) : 1.f;
;                 const f32x4 g0 = acc[ai][0][m][0] * r, g1 = acc[ai][0][m][1] * r, u0 = acc[ai][1][m][0] * r, u1 = acc[ai][1][m][1] * r;
;                 f32x4 h0, h1;
;                 h0.x = silu_f(g0.x) * u0.x; h0.y = silu_f(g0.y) * u0.y; h0.z = silu_f(g0.z) * u0.z; h0.w = silu_f(g0.w) * u0.w;
;                 h1.x = silu_f(g1.x) * u1.x; h1.y = silu_f(g1.y) * u1.y; h1.z = silu_f(g1.z) * u1.z; h1.w = silu_f(g1.w) * u1.w;
;                 *(u32x4*)(hb + (wr * 64 + fr + ai * 128 + m * 16) * 64) = pack8(h0, h1);
	v_rcp_f32_e32 v189, v189
	v_rcp_f32_e32 v190, v190
	v_rcp_f32_e32 v191, v191
	v_rcp_f32_e32 v192, v192
	v_rcp_f32_e32 v193, v193
	v_pk_mul_f32 v[186:187], v[76:77], v[186:187]
	v_pk_mul_f32 v[188:189], v[78:79], v[188:189]
	v_pk_mul_f32 v[190:191], v[72:73], v[190:191]
	v_pk_mul_f32 v[192:193], v[74:75], v[192:193]
	v_pk_mul_f32 v[186:187], v[186:187], v[68:69]
	v_pk_mul_f32 v[188:189], v[188:189], v[70:71]
	v_pk_mul_f32 v[190:191], v[190:191], v[64:65]
	v_pk_mul_f32 v[192:193], v[192:193], v[66:67]
	v_cvt_pk_bf16_f32 v64, v186, v187
	v_cvt_pk_bf16_f32 v65, v188, v189
	v_cvt_pk_bf16_f32 v66, v190, v191
	v_cvt_pk_bf16_f32 v67, v192, v193
	global_store_dwordx4 v[170:171], v[64:67], off offset:2048
	v_pk_mul_f32 v[178:179], v[60:61], v[162:163]
	v_pk_mul_f32 v[180:181], v[62:63], v[162:163]
	v_pk_mul_f32 v[182:183], v[56:57], v[162:163]
	v_pk_mul_f32 v[184:185], v[58:59], v[162:163]
	v_exp_f32_e32 v178, v178
	v_exp_f32_e32 v179, v179
	v_exp_f32_e32 v180, v180
	v_exp_f32_e32 v181, v181
	v_exp_f32_e32 v182, v182
	v_exp_f32_e32 v183, v183
	v_exp_f32_e32 v184, v184
	v_exp_f32_e32 v185, v185
	v_pk_add_f32 v[178:179], v[178:179], v[164:165]
	v_pk_add_f32 v[180:181], v[180:181], v[164:165]
	v_pk_add_f32 v[182:183], v[182:183], v[164:165]
	v_pk_add_f32 v[184:185], v[184:185], v[164:165]
	v_rcp_f32_e32 v178, v178
	v_rcp_f32_e32 v179, v179
	v_rcp_f32_e32 v180, v180
	v_rcp_f32_e32 v181, v181
	v_rcp_f32_e32 v182, v182
	v_rcp_f32_e32 v183, v183
	v_rcp_f32_e32 v184, v184
	v_rcp_f32_e32 v185, v185
	v_pk_mul_f32 v[178:179], v[60:61], v[178:179]
	v_pk_mul_f32 v[180:181], v[62:63], v[180:181]
	v_pk_mul_f32 v[182:183], v[56:57], v[182:183]
	v_pk_mul_f32 v[184:185], v[58:59], v[184:185]
	v_pk_mul_f32 v[178:179], v[178:179], v[52:53]
	v_pk_mul_f32 v[180:181], v[180:181], v[54:55]
	v_pk_mul_f32 v[182:183], v[182:183], v[48:49]
	v_pk_mul_f32 v[184:185], v[184:185], v[50:51]
	v_cvt_pk_bf16_f32 v48, v178, v179
	v_cvt_pk_bf16_f32 v49, v180, v181
	v_cvt_pk_bf16_f32 v50, v182, v183
	v_cvt_pk_bf16_f32 v51, v184, v185
	global_store_dwordx4 v[172:173], v[48:51], off
	v_pk_mul_f32 v[186:187], v[44:45], v[162:163]
	v_pk_mul_f32 v[188:189], v[46:47], v[162:163]
	v_pk_mul_f32 v[190:191], v[40:41], v[162:163]
	v_pk_mul_f32 v[192:193], v[42:43], v[162:163]
	v_exp_f32_e32 v186, v186
	v_exp_f32_e32 v187, v187
	v_exp_f32_e32 v188, v188
	v_exp_f32_e32 v189, v189
	v_exp_f32_e32 v190, v190
	v_exp_f32_e32 v191, v191
	v_exp_f32_e32 v192, v192
	v_exp_f32_e32 v193, v193
	v_pk_add_f32 v[186:187], v[186:187], v[164:165]
	v_pk_add_f32 v[188:189], v[188:189], v[164:165]
	v_pk_add_f32 v[190:191], v[190:191], v[164:165]
	v_pk_add_f32 v[192:193], v[192:193], v[164:165]
	v_rcp_f32_e32 v186, v186
	v_rcp_f32_e32 v187, v187
	v_rcp_f32_e32 v188, v188
	v_rcp_f32_e32 v189, v189
	v_rcp_f32_e32 v190, v190
	v_rcp_f32_e32 v191, v191
	v_rcp_f32_e32 v192, v192
	v_rcp_f32_e32 v193, v193
	v_pk_mul_f32 v[186:187], v[44:45], v[186:187]
	v_pk_mul_f32 v[188:189], v[46:47], v[188:189]
	v_pk_mul_f32 v[190:191], v[40:41], v[190:191]
	v_pk_mul_f32 v[192:193], v[42:43], v[192:193]
	v_pk_mul_f32 v[186:187], v[186:187], v[36:37]
	v_pk_mul_f32 v[188:189], v[188:189], v[38:39]
	v_pk_mul_f32 v[190:191], v[190:191], v[32:33]
	v_pk_mul_f32 v[192:193], v[192:193], v[34:35]
	v_cvt_pk_bf16_f32 v32, v186, v187
	v_cvt_pk_bf16_f32 v33, v188, v189
	v_cvt_pk_bf16_f32 v34, v190, v191
	v_cvt_pk_bf16_f32 v35, v192, v193
	global_store_dwordx4 v[174:175], v[32:35], off
	v_pk_mul_f32 v[178:179], v[28:29], v[162:163]
	v_pk_mul_f32 v[180:181], v[30:31], v[162:163]
	v_pk_mul_f32 v[182:183], v[24:25], v[162:163]
	v_pk_mul_f32 v[184:185], v[26:27], v[162:163]
	v_exp_f32_e32 v178, v178
	v_exp_f32_e32 v179, v179
	v_exp_f32_e32 v180, v180
	v_exp_f32_e32 v181, v181
	v_exp_f32_e32 v182, v182
	v_exp_f32_e32 v183, v183
	v_exp_f32_e32 v184, v184
	v_exp_f32_e32 v185, v185
	v_pk_add_f32 v[178:179], v[178:179], v[164:165]
	v_pk_add_f32 v[180:181], v[180:181], v[164:165]
	v_pk_add_f32 v[182:183], v[182:183], v[164:165]
	v_pk_add_f32 v[184:185], v[184:185], v[164:165]
	v_rcp_f32_e32 v178, v178
	v_rcp_f32_e32 v179, v179
	v_rcp_f32_e32 v180, v180
	v_rcp_f32_e32 v181, v181
	v_rcp_f32_e32 v182, v182
	v_rcp_f32_e32 v183, v183
	v_rcp_f32_e32 v184, v184
	v_rcp_f32_e32 v185, v185
	v_pk_mul_f32 v[178:179], v[28:29], v[178:179]
	v_pk_mul_f32 v[180:181], v[30:31], v[180:181]
	v_pk_mul_f32 v[182:183], v[24:25], v[182:183]
	v_pk_mul_f32 v[184:185], v[26:27], v[184:185]
	v_pk_mul_f32 v[178:179], v[178:179], v[20:21]
	v_pk_mul_f32 v[180:181], v[180:181], v[22:23]
	v_pk_mul_f32 v[182:183], v[182:183], v[16:17]
	v_pk_mul_f32 v[184:185], v[184:185], v[18:19]
	v_cvt_pk_bf16_f32 v16, v178, v179
	v_cvt_pk_bf16_f32 v17, v180, v181
	v_cvt_pk_bf16_f32 v18, v182, v183
	v_cvt_pk_bf16_f32 v19, v184, v185
	global_store_dwordx4 v[176:177], v[16:19], off
	v_pk_mul_f32 v[186:187], v[12:13], v[162:163]
	v_pk_mul_f32 v[188:189], v[14:15], v[162:163]
	v_pk_mul_f32 v[190:191], v[8:9], v[162:163]
	v_pk_mul_f32 v[192:193], v[10:11], v[162:163]
	v_exp_f32_e32 v186, v186
	v_exp_f32_e32 v187, v187
	v_exp_f32_e32 v188, v188
	v_exp_f32_e32 v189, v189
	v_exp_f32_e32 v190, v190
	v_exp_f32_e32 v191, v191
	v_exp_f32_e32 v192, v192
	v_exp_f32_e32 v193, v193
	v_pk_add_f32 v[186:187], v[186:187], v[164:165]
	v_pk_add_f32 v[188:189], v[188:189], v[164:165]
	v_pk_add_f32 v[190:191], v[190:191], v[164:165]
	v_pk_add_f32 v[192:193], v[192:193], v[164:165]
	v_rcp_f32_e32 v186, v186
	v_rcp_f32_e32 v187, v187
	v_rcp_f32_e32 v188, v188
	v_rcp_f32_e32 v189, v189
	v_rcp_f32_e32 v190, v190
	v_rcp_f32_e32 v191, v191
	v_rcp_f32_e32 v192, v192
	v_rcp_f32_e32 v193, v193
	v_pk_mul_f32 v[186:187], v[12:13], v[186:187]
	v_pk_mul_f32 v[188:189], v[14:15], v[188:189]
	v_pk_mul_f32 v[190:191], v[8:9], v[190:191]
	v_pk_mul_f32 v[192:193], v[10:11], v[192:193]
	v_pk_mul_f32 v[186:187], v[186:187], v[4:5]
	v_pk_mul_f32 v[188:189], v[188:189], v[6:7]
	v_pk_mul_f32 v[190:191], v[190:191], v[0:1]
	v_pk_mul_f32 v[192:193], v[192:193], v[2:3]
	v_cvt_pk_bf16_f32 v0, v186, v187
	v_cvt_pk_bf16_f32 v1, v188, v189
	v_cvt_pk_bf16_f32 v2, v190, v191
	v_cvt_pk_bf16_f32 v3, v192, v193
	global_store_dwordx4 v[194:195], v[0:3], off
	s_andn2_b64 vcc, exec, s[0:1]
	s_mov_b64 s[0:1], -1
	s_cbranch_vccnz .LBB0_171
	s_andn2_b64 vcc, exec, s[6:7]
	s_cbranch_vccnz .LBB0_170
	s_mov_b32 s98, 1
	s_branch .LBB0_170

; #define PG8_STAGE(bufoff, gbase, voff) do { _Pragma("unroll") for (int _i = 0; _i < 2; ++_i) \
;         __builtin_amdgcn_global_load_lds((const unsigned*)((const char*)(gbase) + (voff)[_i]), (PG8_LAS unsigned*)(lds + (bufoff) + ldsw + _i * 8192), 16, 0, 0); } while (0)
; #define PG8_LDA(dst, b, h) do { _Pragma("unroll") for (int m = 0; m < 4; ++m) _Pragma("unroll") for (int k = 0; k < 2; ++k) dst[m][k] = *(const PG8_LAS bf16x8*)(lds + PG8_SA(b, h) + aoff + m * 2048 + k * 1024); } while (0)
; #define PG8_LDB(dst, b, h) do { _Pragma("unroll") for (int n = 0; n < 2; ++n) _Pragma("unroll") for (int k = 0; k < 2; ++k) dst[n][k] = *(const PG8_LAS bf16x8*)(lds + PG8_SB(b, h) + boff + n * 2048 + k * 1024); } while (0)
; #define PG8_WAIT_V(n) asm volatile("s_waitcnt vmcnt(" #n ")" ::: "memory")
; #define PG8_WAIT_L(n) asm volatile("s_waitcnt lgkmcnt(" #n ")" ::: "memory")
; #define PG8_BAR __builtin_amdgcn_s_barrier()
; #define PG8_SCHED __builtin_amdgcn_sched_barrier(0)
; template <class Epi, class Sched, bool ALIGN_EPI = false, bool SP2 = false, bool ABLK = false>
; __device__ __forceinline__ void gemm_phase(PG8_LAS unsigned char* lds, const Gemm g, const Sched& S, const Epi& E) {
;     ...
;     for (;;) {
;         const bool has_next = S.next(ui + 1, nxt);
;         const char* nA = has_next ? (const char*)g.A + (size_t)nxt.pm * tstep : cA; const char* nB = has_next ? (const char*)g.Bt + (size_t)nxt.pn * tstep : cB;
;         for (int t = 0; t < nt; t += 2) {
;             const bool last = (t == nt - 2);
;             const char* a1 = cA + (size_t)(t + 1) * kstepA;
;             const char* a2 = last ? nA : cA + (size_t)(t + 2) * kstepA; const char* b2 = last ? nB : cB + (size_t)(t + 2) * kstep;
;             const char* a3 = a2 + kstepA; const char* b3 = b2 + kstep;
;             if (last && has_next) S.a_ready(nxt);
;             if constexpr (SP2) {
;             PG8_LDB(B0, 0, 0); PG8_LDB(B1, 0, 1); PG8_SCHED; PG8_LDA(At, 0, 0); PG8_STAGE(PG8_SA(1, 1), a1 + hstepA, voffA);
;             PG8_WAIT_V(8); PG8_WAIT_L(0); PG8_BAR; PG8_MMA(0, 0, At, B0); PG8_MMA(0, 1, At, B1); PG8_BAR; PG8_SCHED;
;             PG8_LDA(At, 0, 1); PG8_STAGE(PG8_SB(0, 0), b2, voffB); PG8_STAGE(PG8_SB(0, 1), b2 + hstep, voffB); PG8_STAGE(PG8_SA(0, 0), a2, voffA);
;             PG8_WAIT_V(8); PG8_WAIT_L(0); PG8_BAR; PG8_MMA(1, 0, At, B0); PG8_MMA(1, 1, At, B1); PG8_BAR; PG8_SCHED;
.LBB0_255:
	s_add_u32 s14, s44, 0x100
	s_addc_u32 s15, s45, 0
	s_add_u32 s44, s46, 0xc000
	v_mov_b32_e32 v0, 0
	s_addc_u32 s45, s47, 0
	s_mov_b32 s68, -2
	s_waitcnt lgkmcnt(0)
	s_cmp_eq_u32 s98, 1
	s_cbranch_scc0 .Ldefbar_1
	s_barrier
	s_mov_b32 s98, 0
.Ldefbar_1:
.LBB0_256:
	ds_read_b128 v[144:147], v151
	ds_read_b128 v[156:159], v151 offset:1024
	ds_read_b128 v[160:163], v151 offset:2048
	ds_read_b128 v[168:171], v151 offset:3072
	ds_read_b128 v[172:175], v152
	ds_read_b128 v[176:179], v152 offset:1024
	ds_read_b128 v[180:183], v152 offset:2048
	ds_read_b128 v[184:187], v152 offset:3072
	s_add_u32 s16, s44, 0x4000
	s_addc_u32 s17, s45, 0
	s_cmp_eq_u32 s68, 40
	s_cselect_b32 s52, s0, s16
	s_cselect_b32 s53, s1, s17
	s_cselect_b32 s50, s36, s14
	s_cselect_b32 s51, s37, s15
	s_add_u32 s46, s52, 0x8000
	s_addc_u32 s47, s53, 0
	v_lshl_add_u64 v[164:165], s[44:45], 0, v[136:137]
	s_add_i32 m0, s7, 0xc000
	ds_read_b128 v[188:191], v153
	ds_read_b128 v[192:195], v153 offset:1024
	ds_read_b128 v[196:199], v153 offset:2048
	ds_read_b128 v[200:203], v153 offset:3072
	ds_read_b128 v[204:207], v153 offset:4096
	ds_read_b128 v[208:211], v153 offset:5120
	ds_read_b128 v[212:215], v153 offset:6144
	ds_read_b128 v[216:219], v153 offset:7168
	global_load_lds_dwordx4 v[164:165], off
	v_lshl_add_u64 v[164:165], s[44:45], 0, v[138:139]
	s_add_i32 m0, s7, 0xe000
	s_nop 0
	global_load_lds_dwordx4 v[164:165], off
	s_waitcnt vmcnt(8)
	s_waitcnt lgkmcnt(0)
	s_barrier
	s_setprio 1
	s_waitcnt lgkmcnt(0)
	v_mfma_f32_16x16x32_bf16 v[124:127], v[144:147], v[188:191], 0
	v_mfma_f32_16x16x32_bf16 v[120:123], v[160:163], v[188:191], 0
	v_mfma_f32_16x16x32_bf16 v[108:111], v[144:147], v[196:199], 0
	v_mfma_f32_16x16x32_bf16 v[104:107], v[160:163], v[196:199], 0
	v_mfma_f32_16x16x32_bf16 v[92:95], v[144:147], v[204:207], 0
	v_mfma_f32_16x16x32_bf16 v[88:91], v[160:163], v[204:207], 0
	v_mfma_f32_16x16x32_bf16 v[76:79], v[144:147], v[212:215], 0
	v_mfma_f32_16x16x32_bf16 v[72:75], v[160:163], v[212:215], 0
	v_mfma_f32_16x16x32_bf16 v[124:127], v[156:159], v[192:195], v[124:127]
	v_mfma_f32_16x16x32_bf16 v[120:123], v[168:171], v[192:195], v[120:123]
	v_mfma_f32_16x16x32_bf16 v[108:111], v[156:159], v[200:203], v[108:111]
	v_mfma_f32_16x16x32_bf16 v[104:107], v[168:171], v[200:203], v[104:107]
	v_mfma_f32_16x16x32_bf16 v[92:95], v[156:159], v[208:211], v[92:95]
	v_mfma_f32_16x16x32_bf16 v[88:91], v[168:171], v[208:211], v[88:91]
	v_mfma_f32_16x16x32_bf16 v[76:79], v[156:159], v[216:219], v[76:79]
	v_mfma_f32_16x16x32_bf16 v[72:75], v[168:171], v[216:219], v[72:75]
	s_setprio 0
	s_setprio 1
	v_mfma_f32_16x16x32_bf16 v[116:119], v[172:175], v[188:191], 0
	v_mfma_f32_16x16x32_bf16 v[112:115], v[180:183], v[188:191], 0
	v_mfma_f32_16x16x32_bf16 v[100:103], v[172:175], v[196:199], 0
	v_mfma_f32_16x16x32_bf16 v[96:99], v[180:183], v[196:199], 0
	v_mfma_f32_16x16x32_bf16 v[84:87], v[172:175], v[204:207], 0
	v_mfma_f32_16x16x32_bf16 v[80:83], v[180:183], v[204:207], 0
	v_mfma_f32_16x16x32_bf16 v[68:71], v[172:175], v[212:215], 0
	v_mfma_f32_16x16x32_bf16 v[64:67], v[180:183], v[212:215], 0
	v_mfma_f32_16x16x32_bf16 v[116:119], v[176:179], v[192:195], v[116:119]
	v_mfma_f32_16x16x32_bf16 v[112:115], v[184:187], v[192:195], v[112:115]
	v_mfma_f32_16x16x32_bf16 v[100:103], v[176:179], v[200:203], v[100:103]
	v_mfma_f32_16x16x32_bf16 v[96:99], v[184:187], v[200:203], v[96:99]
	v_mfma_f32_16x16x32_bf16 v[84:87], v[176:179], v[208:211], v[84:87]
	v_mfma_f32_16x16x32_bf16 v[80:83], v[184:187], v[208:211], v[80:83]
	v_mfma_f32_16x16x32_bf16 v[68:71], v[176:179], v[216:219], v[68:71]
	v_mfma_f32_16x16x32_bf16 v[64:67], v[184:187], v[216:219], v[64:67]
	s_setprio 0
	s_barrier
	s_add_i32 s16, s58, s4
	v_lshl_add_u64 v[164:165], s[50:51], 0, v[130:131]
	s_mov_b32 m0, s16
	ds_read_b128 v[188:191], v153 offset:16384
	ds_read_b128 v[192:195], v153 offset:17408
	ds_read_b128 v[196:199], v153 offset:18432
	ds_read_b128 v[200:203], v153 offset:19456
	ds_read_b128 v[204:207], v153 offset:20480
	ds_read_b128 v[208:211], v153 offset:21504
	ds_read_b128 v[212:215], v153 offset:22528
	ds_read_b128 v[216:219], v153 offset:23552
	global_load_lds_dwordx4 v[164:165], off
	s_add_i32 m0, s16, 0x2000
	s_add_u32 s16, s50, 0xb0000
	v_lshl_add_u64 v[220:221], s[50:51], 0, v[134:135]
	s_addc_u32 s17, s51, 0
	s_add_i32 s18, s59, s4
	global_load_lds_dwordx4 v[220:221], off
	v_lshl_add_u64 v[222:223], s[16:17], 0, v[130:131]
	s_mov_b32 m0, s18
	s_nop 0
	global_load_lds_dwordx4 v[222:223], off
	v_lshl_add_u64 v[222:223], s[16:17], 0, v[134:135]
	s_add_i32 m0, s18, 0x2000
	s_nop 0
	global_load_lds_dwordx4 v[222:223], off
	v_lshl_add_u64 v[222:223], s[52:53], 0, v[128:129]
	s_mov_b32 m0, s7
	s_nop 0
	global_load_lds_dwordx4 v[222:223], off
	v_lshl_add_u64 v[222:223], s[52:53], 0, v[132:133]
	s_mov_b32 m0, s54
	s_nop 0
	global_load_lds_dwordx4 v[222:223], off
	s_waitcnt vmcnt(8)
	s_waitcnt lgkmcnt(0)
	s_barrier
; #define PG8_STAGE(bufoff, gbase, voff) do { _Pragma("unroll") for (int _i = 0; _i < 2; ++_i) \
;         __builtin_amdgcn_global_load_lds((const unsigned*)((const char*)(gbase) + (voff)[_i]), (PG8_LAS unsigned*)(lds + (bufoff) + ldsw + _i * 8192), 16, 0, 0); } while (0)
; #define PG8_LDA(dst, b, h) do { _Pragma("unroll") for (int m = 0; m < 4; ++m) _Pragma("unroll") for (int k = 0; k < 2; ++k) dst[m][k] = *(const PG8_LAS bf16x8*)(lds + PG8_SA(b, h) + aoff + m * 2048 + k * 1024); } while (0)
; #define PG8_LDB(dst, b, h) do { _Pragma("unroll") for (int n = 0; n < 2; ++n) _Pragma("unroll") for (int k = 0; k < 2; ++k) dst[n][k] = *(const PG8_LAS bf16x8*)(lds + PG8_SB(b, h) + boff + n * 2048 + k * 1024); } while (0)
; #define PG8_MMA(ai, bj, At, Bt) do { __builtin_amdgcn_s_setprio(1); _Pragma("unroll") for (int m = 0; m < 4; ++m) _Pragma("unroll") for (int n = 0; n < 2; ++n) _Pragma("unroll") for (int k = 0; k < 2; ++k) \
;         acc[ai][bj][m][n] = __builtin_amdgcn_mfma_f32_16x16x32_bf16(Bt[n][k], At[m][k], acc[ai][bj][m][n], 0, 0, 0); __builtin_amdgcn_s_setprio(0); } while (0)
; #define PG8_WAIT_V(n) asm volatile("s_waitcnt vmcnt(" #n ")" ::: "memory")
; #define PG8_WAIT_L(n) asm volatile("s_waitcnt lgkmcnt(" #n ")" ::: "memory")
; #define PG8_BAR __builtin_amdgcn_s_barrier()
; #define PG8_SCHED __builtin_amdgcn_sched_barrier(0)
; template <class Epi, class Sched, bool ALIGN_EPI = false, bool SP2 = false, bool ABLK = false>
; __device__ __forceinline__ void gemm_phase(PG8_LAS unsigned char* lds, const Gemm g, const Sched& S, const Epi& E) {
;     ...
;             PG8_WAIT_V(8); PG8_WAIT_L(0); PG8_BAR; PG8_MMA(1, 0, At, B0); PG8_MMA(1, 1, At, B1); PG8_BAR; PG8_SCHED;
;             PG8_LDB(B0, 1, 0); PG8_LDB(B1, 1, 1); PG8_SCHED; PG8_LDA(At, 1, 0); PG8_STAGE(PG8_SA(0, 1), a2 + hstepA, voffA);
;             PG8_WAIT_V(8); PG8_WAIT_L(0); PG8_BAR; PG8_MMA(0, 0, At, B0); PG8_MMA(0, 1, At, B1); PG8_BAR; PG8_SCHED;
;             PG8_LDA(At, 1, 1); PG8_STAGE(PG8_SB(1, 0), b3, voffB); PG8_STAGE(PG8_SB(1, 1), b3 + hstep, voffB); PG8_STAGE(PG8_SA(1, 0), a3, voffA);
	s_setprio 1
	s_waitcnt lgkmcnt(0)
	v_mfma_f32_16x16x32_bf16 v[60:63], v[144:147], v[188:191], 0
	v_mfma_f32_16x16x32_bf16 v[56:59], v[160:163], v[188:191], 0
	v_mfma_f32_16x16x32_bf16 v[44:47], v[144:147], v[196:199], 0
	v_mfma_f32_16x16x32_bf16 v[40:43], v[160:163], v[196:199], 0
	v_mfma_f32_16x16x32_bf16 v[28:31], v[144:147], v[204:207], 0
	v_mfma_f32_16x16x32_bf16 v[24:27], v[160:163], v[204:207], 0
	v_mfma_f32_16x16x32_bf16 v[12:15], v[144:147], v[212:215], 0
	v_mfma_f32_16x16x32_bf16 v[8:11], v[160:163], v[212:215], 0
	v_mfma_f32_16x16x32_bf16 v[60:63], v[156:159], v[192:195], v[60:63]
	v_mfma_f32_16x16x32_bf16 v[56:59], v[168:171], v[192:195], v[56:59]
	v_mfma_f32_16x16x32_bf16 v[44:47], v[156:159], v[200:203], v[44:47]
	v_mfma_f32_16x16x32_bf16 v[40:43], v[168:171], v[200:203], v[40:43]
	v_mfma_f32_16x16x32_bf16 v[28:31], v[156:159], v[208:211], v[28:31]
	v_mfma_f32_16x16x32_bf16 v[24:27], v[168:171], v[208:211], v[24:27]
	v_mfma_f32_16x16x32_bf16 v[12:15], v[156:159], v[216:219], v[12:15]
	v_mfma_f32_16x16x32_bf16 v[8:11], v[168:171], v[216:219], v[8:11]
	s_setprio 0
	s_setprio 1
	v_mfma_f32_16x16x32_bf16 v[52:55], v[172:175], v[188:191], 0
	v_mfma_f32_16x16x32_bf16 v[48:51], v[180:183], v[188:191], 0
	v_mfma_f32_16x16x32_bf16 v[36:39], v[172:175], v[196:199], 0
	v_mfma_f32_16x16x32_bf16 v[32:35], v[180:183], v[196:199], 0
	v_mfma_f32_16x16x32_bf16 v[20:23], v[172:175], v[204:207], 0
	v_mfma_f32_16x16x32_bf16 v[16:19], v[180:183], v[204:207], 0
	v_mfma_f32_16x16x32_bf16 v[4:7], v[172:175], v[212:215], 0
	v_mfma_f32_16x16x32_bf16 v[0:3], v[180:183], v[212:215], 0
	v_mfma_f32_16x16x32_bf16 v[52:55], v[176:179], v[192:195], v[52:55]
	v_mfma_f32_16x16x32_bf16 v[48:51], v[184:187], v[192:195], v[48:51]
	v_mfma_f32_16x16x32_bf16 v[36:39], v[176:179], v[200:203], v[36:39]
	v_mfma_f32_16x16x32_bf16 v[32:35], v[184:187], v[200:203], v[32:35]
	v_mfma_f32_16x16x32_bf16 v[20:23], v[176:179], v[208:211], v[20:23]
	v_mfma_f32_16x16x32_bf16 v[16:19], v[184:187], v[208:211], v[16:19]
	v_mfma_f32_16x16x32_bf16 v[4:7], v[176:179], v[216:219], v[4:7]
	v_mfma_f32_16x16x32_bf16 v[0:3], v[184:187], v[216:219], v[0:3]
	s_setprio 0
	s_barrier
	s_add_i32 s18, 0, 0x18000
	v_add_u32_e32 v155, s18, v149
	s_add_i32 s19, 0, 0x1c000
	ds_read_b128 v[144:147], v155
	ds_read_b128 v[156:159], v155 offset:1024
	ds_read_b128 v[160:163], v155 offset:2048
	ds_read_b128 v[168:171], v155 offset:3072
	v_add_u32_e32 v155, s19, v149
	ds_read_b128 v[172:175], v155
	ds_read_b128 v[176:179], v155 offset:1024
	ds_read_b128 v[180:183], v155 offset:2048
	ds_read_b128 v[184:187], v155 offset:3072
	s_add_u32 s16, s52, 0x4000
	s_addc_u32 s17, s53, 0
	s_mov_b32 m0, s8
	v_lshl_add_u64 v[222:223], s[16:17], 0, v[128:129]
	ds_read_b128 v[188:191], v153 offset:32768
	ds_read_b128 v[192:195], v153 offset:33792
	ds_read_b128 v[196:199], v153 offset:34816
	ds_read_b128 v[200:203], v153 offset:35840
	ds_read_b128 v[204:207], v153 offset:36864
	ds_read_b128 v[208:211], v153 offset:37888
	ds_read_b128 v[212:215], v153 offset:38912
	ds_read_b128 v[216:219], v153 offset:39936
	global_load_lds_dwordx4 v[222:223], off
	v_lshl_add_u64 v[222:223], s[16:17], 0, v[132:133]
	s_mov_b32 m0, s9
	s_nop 0
	global_load_lds_dwordx4 v[222:223], off
	s_waitcnt vmcnt(8)
	s_waitcnt lgkmcnt(0)
	s_barrier
	s_setprio 1
	s_waitcnt lgkmcnt(0)
	v_mfma_f32_16x16x32_bf16 v[124:127], v[144:147], v[188:191], v[124:127]
	v_mfma_f32_16x16x32_bf16 v[120:123], v[160:163], v[188:191], v[120:123]
	v_mfma_f32_16x16x32_bf16 v[108:111], v[144:147], v[196:199], v[108:111]
	v_mfma_f32_16x16x32_bf16 v[104:107], v[160:163], v[196:199], v[104:107]
	v_mfma_f32_16x16x32_bf16 v[92:95], v[144:147], v[204:207], v[92:95]
	v_mfma_f32_16x16x32_bf16 v[88:91], v[160:163], v[204:207], v[88:91]
	v_mfma_f32_16x16x32_bf16 v[76:79], v[144:147], v[212:215], v[76:79]
	v_mfma_f32_16x16x32_bf16 v[72:75], v[160:163], v[212:215], v[72:75]
	v_mfma_f32_16x16x32_bf16 v[124:127], v[156:159], v[192:195], v[124:127]
	v_mfma_f32_16x16x32_bf16 v[120:123], v[168:171], v[192:195], v[120:123]
	v_mfma_f32_16x16x32_bf16 v[108:111], v[156:159], v[200:203], v[108:111]
	v_mfma_f32_16x16x32_bf16 v[104:107], v[168:171], v[200:203], v[104:107]
	v_mfma_f32_16x16x32_bf16 v[92:95], v[156:159], v[208:211], v[92:95]
	v_mfma_f32_16x16x32_bf16 v[88:91], v[168:171], v[208:211], v[88:91]
	v_mfma_f32_16x16x32_bf16 v[76:79], v[156:159], v[216:219], v[76:79]
	v_mfma_f32_16x16x32_bf16 v[72:75], v[168:171], v[216:219], v[72:75]
	s_setprio 0
	s_setprio 1
	v_mfma_f32_16x16x32_bf16 v[116:119], v[172:175], v[188:191], v[116:119]
	v_mfma_f32_16x16x32_bf16 v[112:115], v[180:183], v[188:191], v[112:115]
	v_mfma_f32_16x16x32_bf16 v[100:103], v[172:175], v[196:199], v[100:103]
	v_mfma_f32_16x16x32_bf16 v[96:99], v[180:183], v[196:199], v[96:99]
	v_mfma_f32_16x16x32_bf16 v[84:87], v[172:175], v[204:207], v[84:87]
	v_mfma_f32_16x16x32_bf16 v[80:83], v[180:183], v[204:207], v[80:83]
	v_mfma_f32_16x16x32_bf16 v[68:71], v[172:175], v[212:215], v[68:71]
	v_mfma_f32_16x16x32_bf16 v[64:67], v[180:183], v[212:215], v[64:67]
	v_mfma_f32_16x16x32_bf16 v[116:119], v[176:179], v[192:195], v[116:119]
	v_mfma_f32_16x16x32_bf16 v[112:115], v[184:187], v[192:195], v[112:115]
	v_mfma_f32_16x16x32_bf16 v[100:103], v[176:179], v[200:203], v[100:103]
	v_mfma_f32_16x16x32_bf16 v[96:99], v[184:187], v[200:203], v[96:99]
	v_mfma_f32_16x16x32_bf16 v[84:87], v[176:179], v[208:211], v[84:87]
	v_mfma_f32_16x16x32_bf16 v[80:83], v[184:187], v[208:211], v[80:83]
	v_mfma_f32_16x16x32_bf16 v[68:71], v[176:179], v[216:219], v[68:71]
	v_mfma_f32_16x16x32_bf16 v[64:67], v[184:187], v[216:219], v[64:67]
	s_setprio 0
	s_barrier
; #define PG8_STAGE(bufoff, gbase, voff) do { _Pragma("unroll") for (int _i = 0; _i < 2; ++_i) \
;         __builtin_amdgcn_global_load_lds((const unsigned*)((const char*)(gbase) + (voff)[_i]), (PG8_LAS unsigned*)(lds + (bufoff) + ldsw + _i * 8192), 16, 0, 0); } while (0)
; #define PG8_LDA(dst, b, h) do { _Pragma("unroll") for (int m = 0; m < 4; ++m) _Pragma("unroll") for (int k = 0; k < 2; ++k) dst[m][k] = *(const PG8_LAS bf16x8*)(lds + PG8_SA(b, h) + aoff + m * 2048 + k * 1024); } while (0)
; #define PG8_MMA(ai, bj, At, Bt) do { __builtin_amdgcn_s_setprio(1); _Pragma("unroll") for (int m = 0; m < 4; ++m) _Pragma("unroll") for (int n = 0; n < 2; ++n) _Pragma("unroll") for (int k = 0; k < 2; ++k) \
;         acc[ai][bj][m][n] = __builtin_amdgcn_mfma_f32_16x16x32_bf16(Bt[n][k], At[m][k], acc[ai][bj][m][n], 0, 0, 0); __builtin_amdgcn_s_setprio(0); } while (0)
; #define PG8_WAIT_V(n) asm volatile("s_waitcnt vmcnt(" #n ")" ::: "memory")
; #define PG8_WAIT_L(n) asm volatile("s_waitcnt lgkmcnt(" #n ")" ::: "memory")
; #define PG8_BAR __builtin_amdgcn_s_barrier()
; #define PG8_SCHED __builtin_amdgcn_sched_barrier(0)
; template <class Epi, class Sched, bool ALIGN_EPI = false, bool SP2 = false, bool ABLK = false>
; __device__ __forceinline__ void gemm_phase(PG8_LAS unsigned char* lds, const Gemm g, const Sched& S, const Epi& E) {
;     ...
;         for (int t = 0; t < nt; t += 2) {
;             const bool last = (t == nt - 2);
;             const char* a1 = cA + (size_t)(t + 1) * kstepA;
;             const char* a2 = last ? nA : cA + (size_t)(t + 2) * kstepA; const char* b2 = last ? nB : cB + (size_t)(t + 2) * kstep;
;             const char* a3 = a2 + kstepA; const char* b3 = b2 + kstep;
;     ...
;             PG8_LDA(At, 1, 1); PG8_STAGE(PG8_SB(1, 0), b3, voffB); PG8_STAGE(PG8_SB(1, 1), b3 + hstep, voffB); PG8_STAGE(PG8_SA(1, 0), a3, voffA);
;             PG8_WAIT_V(8); PG8_WAIT_L(0); PG8_BAR; PG8_MMA(1, 0, At, B0); PG8_MMA(1, 1, At, B1); PG8_BAR; PG8_SCHED;
	s_add_i32 s16, s18, s4
	v_lshl_add_u64 v[164:165], v[164:165], 0, s[30:31]
	s_mov_b32 m0, s16
	ds_read_b128 v[188:191], v153 offset:49152
	ds_read_b128 v[192:195], v153 offset:50176
	ds_read_b128 v[196:199], v153 offset:51200
	ds_read_b128 v[200:203], v153 offset:52224
	ds_read_b128 v[204:207], v153 offset:53248
	ds_read_b128 v[208:211], v153 offset:54272
	ds_read_b128 v[212:215], v153 offset:55296
	ds_read_b128 v[216:219], v153 offset:56320
	global_load_lds_dwordx4 v[164:165], off
	s_add_i32 m0, s16, 0x2000
	s_add_u32 s16, s50, 0xb0080
	v_lshl_add_u64 v[164:165], v[220:221], 0, s[30:31]
	s_addc_u32 s17, s51, 0
	s_add_i32 s18, s19, s4
	global_load_lds_dwordx4 v[164:165], off
	v_lshl_add_u64 v[164:165], s[16:17], 0, v[130:131]
	s_mov_b32 m0, s18
	s_nop 0
	global_load_lds_dwordx4 v[164:165], off
	v_lshl_add_u64 v[164:165], s[16:17], 0, v[134:135]
	s_add_i32 m0, s18, 0x2000
	s_nop 0
	global_load_lds_dwordx4 v[164:165], off
	v_lshl_add_u64 v[164:165], s[46:47], 0, v[128:129]
	s_mov_b32 m0, s11
	s_nop 0
	global_load_lds_dwordx4 v[164:165], off
	v_lshl_add_u64 v[164:165], s[46:47], 0, v[132:133]
	s_mov_b32 m0, s55
	s_nop 0
	global_load_lds_dwordx4 v[164:165], off
	s_waitcnt vmcnt(8)
	s_waitcnt lgkmcnt(0)
	s_barrier
	s_setprio 1
	s_waitcnt lgkmcnt(0)
	v_mfma_f32_16x16x32_bf16 v[60:63], v[144:147], v[188:191], v[60:63]
	v_mfma_f32_16x16x32_bf16 v[56:59], v[160:163], v[188:191], v[56:59]
	v_mfma_f32_16x16x32_bf16 v[44:47], v[144:147], v[196:199], v[44:47]
	v_mfma_f32_16x16x32_bf16 v[40:43], v[160:163], v[196:199], v[40:43]
	v_mfma_f32_16x16x32_bf16 v[28:31], v[144:147], v[204:207], v[28:31]
	v_mfma_f32_16x16x32_bf16 v[24:27], v[160:163], v[204:207], v[24:27]
	v_mfma_f32_16x16x32_bf16 v[12:15], v[144:147], v[212:215], v[12:15]
	v_mfma_f32_16x16x32_bf16 v[8:11], v[160:163], v[212:215], v[8:11]
	v_mfma_f32_16x16x32_bf16 v[60:63], v[156:159], v[192:195], v[60:63]
	v_mfma_f32_16x16x32_bf16 v[56:59], v[168:171], v[192:195], v[56:59]
	v_mfma_f32_16x16x32_bf16 v[44:47], v[156:159], v[200:203], v[44:47]
	v_mfma_f32_16x16x32_bf16 v[40:43], v[168:171], v[200:203], v[40:43]
	v_mfma_f32_16x16x32_bf16 v[28:31], v[156:159], v[208:211], v[28:31]
	v_mfma_f32_16x16x32_bf16 v[24:27], v[168:171], v[208:211], v[24:27]
	v_mfma_f32_16x16x32_bf16 v[12:15], v[156:159], v[216:219], v[12:15]
	v_mfma_f32_16x16x32_bf16 v[8:11], v[168:171], v[216:219], v[8:11]
	s_setprio 0
	s_setprio 1
	v_mfma_f32_16x16x32_bf16 v[52:55], v[172:175], v[188:191], v[52:55]
	v_mfma_f32_16x16x32_bf16 v[48:51], v[180:183], v[188:191], v[48:51]
	v_mfma_f32_16x16x32_bf16 v[36:39], v[172:175], v[196:199], v[36:39]
	v_mfma_f32_16x16x32_bf16 v[32:35], v[180:183], v[196:199], v[32:35]
	v_mfma_f32_16x16x32_bf16 v[20:23], v[172:175], v[204:207], v[20:23]
	v_mfma_f32_16x16x32_bf16 v[16:19], v[180:183], v[204:207], v[16:19]
	v_mfma_f32_16x16x32_bf16 v[4:7], v[172:175], v[212:215], v[4:7]
	v_mfma_f32_16x16x32_bf16 v[0:3], v[180:183], v[212:215], v[0:3]
	v_mfma_f32_16x16x32_bf16 v[52:55], v[176:179], v[192:195], v[52:55]
	v_mfma_f32_16x16x32_bf16 v[48:51], v[184:187], v[192:195], v[48:51]
	v_mfma_f32_16x16x32_bf16 v[36:39], v[176:179], v[200:203], v[36:39]
	v_mfma_f32_16x16x32_bf16 v[32:35], v[184:187], v[200:203], v[32:35]
	v_mfma_f32_16x16x32_bf16 v[20:23], v[176:179], v[208:211], v[20:23]
	v_mfma_f32_16x16x32_bf16 v[16:19], v[184:187], v[208:211], v[16:19]
	v_mfma_f32_16x16x32_bf16 v[4:7], v[176:179], v[216:219], v[4:7]
	v_mfma_f32_16x16x32_bf16 v[0:3], v[184:187], v[216:219], v[0:3]
	s_setprio 0
	s_barrier
	s_add_i32 s68, s68, 2
	s_add_u32 s14, s14, 0x100
	s_addc_u32 s15, s15, 0
	s_add_u32 s44, s44, 0x10000
	s_addc_u32 s45, s45, 0
	s_cmp_gt_u32 s68, 41
	s_cbranch_scc1 .Lpeel_post_1

; #define PG8_BAR __builtin_amdgcn_s_barrier()
; template <class Epi, class Sched, bool ALIGN_EPI = false, bool SP2 = false, bool ABLK = false>
; __device__ __forceinline__ void gemm_phase(PG8_LAS unsigned char* lds, const Gemm g, const Sched& S, const Epi& E) {
;     ...
;         if (!has_next) break;
; #pragma unroll
;         for (int a = 0; a < 2; ++a)
; #pragma unroll
;             for (int b = 0; b < 2; ++b)
; #pragma unroll
;                 for (int m = 0; m < 4; ++m)
; #pragma unroll
;                     for (int n = 0; n < 2; ++n) acc[a][b][m][n] = (f32x4){0.f, 0.f, 0.f, 0.f};
;         cur = nxt; cA = nA; cB = nB; ++ui;
;         if constexpr (ALIGN_EPI) { if (wr == 1) PG8_BAR; }
.LBB0_275:
	s_or_b64 exec, exec, s[44:45]
	s_and_b64 vcc, exec, s[42:43]
	s_mov_b64 s[42:43], -1
	s_cbranch_vccnz .LBB0_244
	s_andn2_b64 vcc, exec, s[28:29]
	s_cbranch_vccnz .LBB0_243
	s_mov_b32 s98, 1
	s_branch .LBB0_243

; #define PG8_STAGE(bufoff, gbase, voff) do { _Pragma("unroll") for (int _i = 0; _i < 2; ++_i) \
;         __builtin_amdgcn_global_load_lds((const unsigned*)((const char*)(gbase) + (voff)[_i]), (PG8_LAS unsigned*)(lds + (bufoff) + ldsw + _i * 8192), 16, 0, 0); } while (0)
; #define PG8_LDA(dst, b, h) do { _Pragma("unroll") for (int m = 0; m < 4; ++m) _Pragma("unroll") for (int k = 0; k < 2; ++k) dst[m][k] = *(const PG8_LAS bf16x8*)(lds + PG8_SA(b, h) + aoff + m * 2048 + k * 1024); } while (0)
; #define PG8_LDB(dst, b, h) do { _Pragma("unroll") for (int n = 0; n < 2; ++n) _Pragma("unroll") for (int k = 0; k < 2; ++k) dst[n][k] = *(const PG8_LAS bf16x8*)(lds + PG8_SB(b, h) + boff + n * 2048 + k * 1024); } while (0)
; #define PG8_MMA(ai, bj, At, Bt) do { __builtin_amdgcn_s_setprio(1); _Pragma("unroll") for (int m = 0; m < 4; ++m) _Pragma("unroll") for (int n = 0; n < 2; ++n) _Pragma("unroll") for (int k = 0; k < 2; ++k) \
;         acc[ai][bj][m][n] = __builtin_amdgcn_mfma_f32_16x16x32_bf16(Bt[n][k], At[m][k], acc[ai][bj][m][n], 0, 0, 0); __builtin_amdgcn_s_setprio(0); } while (0)
; template <class Epi, class Sched, bool ALIGN_EPI = false, bool SP2 = false, bool ABLK = false>
; __device__ __forceinline__ void gemm_phase(PG8_LAS unsigned char* lds, const Gemm g, const Sched& S, const Epi& E) {
;     ...
;     for (;;) {
;         const bool has_next = S.next(ui + 1, nxt);
;         const char* nA = has_next ? (const char*)g.A + (size_t)nxt.pm * tstep : cA; const char* nB = has_next ? (const char*)g.Bt + (size_t)nxt.pn * tstep : cB;
;         for (int t = 0; t < nt; t += 2) {
;             const bool last = (t == nt - 2);
;             const char* a1 = cA + (size_t)(t + 1) * kstepA;
;             const char* a2 = last ? nA : cA + (size_t)(t + 2) * kstepA; const char* b2 = last ? nB : cB + (size_t)(t + 2) * kstep;
;             const char* a3 = a2 + kstepA; const char* b3 = b2 + kstep;
;             if (last && has_next) S.a_ready(nxt);
;             if constexpr (SP2) {
;             PG8_LDB(B0, 0, 0); PG8_LDB(B1, 0, 1); PG8_SCHED; PG8_LDA(At, 0, 0); PG8_STAGE(PG8_SA(1, 1), a1 + hstepA, voffA);
;             PG8_WAIT_V(8); PG8_WAIT_L(0); PG8_BAR; PG8_MMA(0, 0, At, B0); PG8_MMA(0, 1, At, B1); PG8_BAR; PG8_SCHED;
;             PG8_LDA(At, 0, 1); PG8_STAGE(PG8_SB(0, 0), b2, voffB); PG8_STAGE(PG8_SB(0, 1), b2 + hstep, voffB); PG8_STAGE(PG8_SA(0, 0), a2, voffA);
.LBB0_344:
	s_ashr_i32 s55, s54, 31
	s_lshl_b64 s[4:5], s[54:55], 19
	s_add_u32 s76, s96, s4
	s_addc_u32 s77, s97, s5
	s_and_b64 s[4:5], s[40:41], exec
	s_cselect_b32 s1, s77, s43
	s_cselect_b32 s4, s76, s42
	s_ashr_i32 s37, s36, 31
	s_lshl_b64 s[6:7], s[36:37], 19
	s_add_u32 s78, s68, s6
	s_addc_u32 s79, s69, s7
	s_and_b64 s[6:7], s[40:41], exec
	s_cselect_b32 s5, s79, s53
	s_cselect_b32 s6, s78, s52
	s_add_u32 s42, s42, 0x40080
	s_addc_u32 s43, s43, 0
	s_add_u32 s7, s52, 0x100
	v_mov_b32_e32 v0, 0
	s_addc_u32 s8, s53, 0
	s_mov_b32 s9, -2
	s_cmp_eq_u32 s98, 1
	s_cbranch_scc0 .Ldefbar_2
	s_barrier
	s_mov_b32 s98, 0
.Ldefbar_2:
.LBB0_345:
	s_waitcnt lgkmcnt(0)
	ds_read_b128 v[152:155], v169
	ds_read_b128 v[156:159], v169 offset:1024
	ds_read_b128 v[160:163], v169 offset:2048
	ds_read_b128 v[176:179], v169 offset:3072
	ds_read_b128 v[180:183], v170
	ds_read_b128 v[184:187], v170 offset:1024
	ds_read_b128 v[188:191], v170 offset:2048
	ds_read_b128 v[192:195], v170 offset:3072
	s_add_u32 s10, s42, 0xfffc0080
	s_addc_u32 s11, s43, -1
	s_cmp_eq_u32 s9, 12
	s_cselect_b32 s67, s1, s11
	s_cselect_b32 s66, s4, s10
	s_cselect_b32 s53, s5, s8
	s_cselect_b32 s52, s6, s7
	v_lshl_add_u64 v[164:165], s[42:43], 0, v[144:145]
	s_add_i32 m0, s59, 0xc000
	ds_read_b128 v[196:199], v171
	ds_read_b128 v[200:203], v171 offset:1024
	ds_read_b128 v[204:207], v171 offset:2048
	ds_read_b128 v[208:211], v171 offset:3072
	ds_read_b128 v[212:215], v171 offset:4096
	ds_read_b128 v[216:219], v171 offset:5120
	ds_read_b128 v[220:223], v171 offset:6144
	ds_read_b128 v[224:227], v171 offset:7168
	global_load_lds_dwordx4 v[164:165], off
	v_lshl_add_u64 v[164:165], s[42:43], 0, v[146:147]
	s_add_i32 m0, s59, 0xe000
	s_nop 0
	global_load_lds_dwordx4 v[164:165], off
	s_waitcnt vmcnt(8)
	s_waitcnt lgkmcnt(0)
	s_barrier
	s_setprio 1
	s_waitcnt lgkmcnt(0)
	v_mfma_f32_16x16x32_bf16 v[124:127], v[152:155], v[196:199], 0
	v_mfma_f32_16x16x32_bf16 v[120:123], v[160:163], v[196:199], 0
	v_mfma_f32_16x16x32_bf16 v[108:111], v[152:155], v[204:207], 0
	v_mfma_f32_16x16x32_bf16 v[104:107], v[160:163], v[204:207], 0
	v_mfma_f32_16x16x32_bf16 v[92:95], v[152:155], v[212:215], 0
	v_mfma_f32_16x16x32_bf16 v[88:91], v[160:163], v[212:215], 0
	v_mfma_f32_16x16x32_bf16 v[76:79], v[152:155], v[220:223], 0
	v_mfma_f32_16x16x32_bf16 v[72:75], v[160:163], v[220:223], 0
	v_mfma_f32_16x16x32_bf16 v[124:127], v[156:159], v[200:203], v[124:127]
	v_mfma_f32_16x16x32_bf16 v[120:123], v[176:179], v[200:203], v[120:123]
	v_mfma_f32_16x16x32_bf16 v[108:111], v[156:159], v[208:211], v[108:111]
	v_mfma_f32_16x16x32_bf16 v[104:107], v[176:179], v[208:211], v[104:107]
	v_mfma_f32_16x16x32_bf16 v[92:95], v[156:159], v[216:219], v[92:95]
	v_mfma_f32_16x16x32_bf16 v[88:91], v[176:179], v[216:219], v[88:91]
	v_mfma_f32_16x16x32_bf16 v[76:79], v[156:159], v[224:227], v[76:79]
	v_mfma_f32_16x16x32_bf16 v[72:75], v[176:179], v[224:227], v[72:75]
	s_setprio 0
	s_setprio 1
	v_mfma_f32_16x16x32_bf16 v[116:119], v[180:183], v[196:199], 0
	v_mfma_f32_16x16x32_bf16 v[112:115], v[188:191], v[196:199], 0
	v_mfma_f32_16x16x32_bf16 v[100:103], v[180:183], v[204:207], 0
	v_mfma_f32_16x16x32_bf16 v[96:99], v[188:191], v[204:207], 0
	v_mfma_f32_16x16x32_bf16 v[84:87], v[180:183], v[212:215], 0
	v_mfma_f32_16x16x32_bf16 v[80:83], v[188:191], v[212:215], 0
	v_mfma_f32_16x16x32_bf16 v[68:71], v[180:183], v[220:223], 0
	v_mfma_f32_16x16x32_bf16 v[64:67], v[188:191], v[220:223], 0
	v_mfma_f32_16x16x32_bf16 v[116:119], v[184:187], v[200:203], v[116:119]
	v_mfma_f32_16x16x32_bf16 v[112:115], v[192:195], v[200:203], v[112:115]
	v_mfma_f32_16x16x32_bf16 v[100:103], v[184:187], v[208:211], v[100:103]
	v_mfma_f32_16x16x32_bf16 v[96:99], v[192:195], v[208:211], v[96:99]
	v_mfma_f32_16x16x32_bf16 v[84:87], v[184:187], v[216:219], v[84:87]
	v_mfma_f32_16x16x32_bf16 v[80:83], v[192:195], v[216:219], v[80:83]
	v_mfma_f32_16x16x32_bf16 v[68:71], v[184:187], v[224:227], v[68:71]
	v_mfma_f32_16x16x32_bf16 v[64:67], v[192:195], v[224:227], v[64:67]
	s_setprio 0
	s_barrier
	s_add_i32 s10, s34, s74
	v_lshl_add_u64 v[164:165], s[52:53], 0, v[130:131]
	s_mov_b32 m0, s10
	ds_read_b128 v[196:199], v171 offset:16384
	ds_read_b128 v[200:203], v171 offset:17408
	ds_read_b128 v[204:207], v171 offset:18432
	ds_read_b128 v[208:211], v171 offset:19456
	ds_read_b128 v[212:215], v171 offset:20480
	ds_read_b128 v[216:219], v171 offset:21504
	ds_read_b128 v[220:223], v171 offset:22528
	ds_read_b128 v[224:227], v171 offset:23552
	global_load_lds_dwordx4 v[164:165], off
	s_add_i32 m0, s10, 0x2000
	s_add_u32 s10, s52, 0x40000
	v_lshl_add_u64 v[228:229], s[52:53], 0, v[134:135]
	s_addc_u32 s11, s53, 0
	s_add_i32 s14, s35, s74
	global_load_lds_dwordx4 v[228:229], off
	v_lshl_add_u64 v[230:231], s[10:11], 0, v[130:131]
	s_mov_b32 m0, s14
	v_lshl_add_u64 v[232:233], s[66:67], 0, v[132:133]
	global_load_lds_dwordx4 v[230:231], off
	v_lshl_add_u64 v[230:231], s[10:11], 0, v[134:135]
	s_add_i32 m0, s14, 0x2000
	s_nop 0
	global_load_lds_dwordx4 v[230:231], off
	v_lshl_add_u64 v[230:231], s[66:67], 0, v[128:129]
	s_mov_b32 m0, s59
	s_nop 0
	global_load_lds_dwordx4 v[230:231], off
	s_mov_b32 m0, s75
	s_nop 0
	global_load_lds_dwordx4 v[232:233], off
	s_waitcnt vmcnt(8)
	s_waitcnt lgkmcnt(0)
	s_barrier
; #define PG8_STAGE(bufoff, gbase, voff) do { _Pragma("unroll") for (int _i = 0; _i < 2; ++_i) \
;         __builtin_amdgcn_global_load_lds((const unsigned*)((const char*)(gbase) + (voff)[_i]), (PG8_LAS unsigned*)(lds + (bufoff) + ldsw + _i * 8192), 16, 0, 0); } while (0)
; #define PG8_LDA(dst, b, h) do { _Pragma("unroll") for (int m = 0; m < 4; ++m) _Pragma("unroll") for (int k = 0; k < 2; ++k) dst[m][k] = *(const PG8_LAS bf16x8*)(lds + PG8_SA(b, h) + aoff + m * 2048 + k * 1024); } while (0)
; #define PG8_LDB(dst, b, h) do { _Pragma("unroll") for (int n = 0; n < 2; ++n) _Pragma("unroll") for (int k = 0; k < 2; ++k) dst[n][k] = *(const PG8_LAS bf16x8*)(lds + PG8_SB(b, h) + boff + n * 2048 + k * 1024); } while (0)
; #define PG8_MMA(ai, bj, At, Bt) do { __builtin_amdgcn_s_setprio(1); _Pragma("unroll") for (int m = 0; m < 4; ++m) _Pragma("unroll") for (int n = 0; n < 2; ++n) _Pragma("unroll") for (int k = 0; k < 2; ++k) \
;         acc[ai][bj][m][n] = __builtin_amdgcn_mfma_f32_16x16x32_bf16(Bt[n][k], At[m][k], acc[ai][bj][m][n], 0, 0, 0); __builtin_amdgcn_s_setprio(0); } while (0)
; #define PG8_WAIT_V(n) asm volatile("s_waitcnt vmcnt(" #n ")" ::: "memory")
; #define PG8_WAIT_L(n) asm volatile("s_waitcnt lgkmcnt(" #n ")" ::: "memory")
; #define PG8_BAR __builtin_amdgcn_s_barrier()
; #define PG8_SCHED __builtin_amdgcn_sched_barrier(0)
; template <class Epi, class Sched, bool ALIGN_EPI = false, bool SP2 = false, bool ABLK = false>
; __device__ __forceinline__ void gemm_phase(PG8_LAS unsigned char* lds, const Gemm g, const Sched& S, const Epi& E) {
;     ...
;             PG8_WAIT_V(8); PG8_WAIT_L(0); PG8_BAR; PG8_MMA(1, 0, At, B0); PG8_MMA(1, 1, At, B1); PG8_BAR; PG8_SCHED;
;             PG8_LDB(B0, 1, 0); PG8_LDB(B1, 1, 1); PG8_SCHED; PG8_LDA(At, 1, 0); PG8_STAGE(PG8_SA(0, 1), a2 + hstepA, voffA);
;             PG8_WAIT_V(8); PG8_WAIT_L(0); PG8_BAR; PG8_MMA(0, 0, At, B0); PG8_MMA(0, 1, At, B1); PG8_BAR; PG8_SCHED;
;             PG8_LDA(At, 1, 1); PG8_STAGE(PG8_SB(1, 0), b3, voffB); PG8_STAGE(PG8_SB(1, 1), b3 + hstep, voffB); PG8_STAGE(PG8_SA(1, 0), a3, voffA);
	s_setprio 1
	s_waitcnt lgkmcnt(0)
	v_mfma_f32_16x16x32_bf16 v[60:63], v[152:155], v[196:199], 0
	v_mfma_f32_16x16x32_bf16 v[56:59], v[160:163], v[196:199], 0
	v_mfma_f32_16x16x32_bf16 v[44:47], v[152:155], v[204:207], 0
	v_mfma_f32_16x16x32_bf16 v[40:43], v[160:163], v[204:207], 0
	v_mfma_f32_16x16x32_bf16 v[28:31], v[152:155], v[212:215], 0
	v_mfma_f32_16x16x32_bf16 v[24:27], v[160:163], v[212:215], 0
	v_mfma_f32_16x16x32_bf16 v[12:15], v[152:155], v[220:223], 0
	v_mfma_f32_16x16x32_bf16 v[8:11], v[160:163], v[220:223], 0
	v_mfma_f32_16x16x32_bf16 v[60:63], v[156:159], v[200:203], v[60:63]
	v_mfma_f32_16x16x32_bf16 v[56:59], v[176:179], v[200:203], v[56:59]
	v_mfma_f32_16x16x32_bf16 v[44:47], v[156:159], v[208:211], v[44:47]
	v_mfma_f32_16x16x32_bf16 v[40:43], v[176:179], v[208:211], v[40:43]
	v_mfma_f32_16x16x32_bf16 v[28:31], v[156:159], v[216:219], v[28:31]
	v_mfma_f32_16x16x32_bf16 v[24:27], v[176:179], v[216:219], v[24:27]
	v_mfma_f32_16x16x32_bf16 v[12:15], v[156:159], v[224:227], v[12:15]
	v_mfma_f32_16x16x32_bf16 v[8:11], v[176:179], v[224:227], v[8:11]
	s_setprio 0
	s_setprio 1
	v_mfma_f32_16x16x32_bf16 v[52:55], v[180:183], v[196:199], 0
	v_mfma_f32_16x16x32_bf16 v[48:51], v[188:191], v[196:199], 0
	v_mfma_f32_16x16x32_bf16 v[36:39], v[180:183], v[204:207], 0
	v_mfma_f32_16x16x32_bf16 v[32:35], v[188:191], v[204:207], 0
	v_mfma_f32_16x16x32_bf16 v[20:23], v[180:183], v[212:215], 0
	v_mfma_f32_16x16x32_bf16 v[16:19], v[188:191], v[212:215], 0
	v_mfma_f32_16x16x32_bf16 v[4:7], v[180:183], v[220:223], 0
	v_mfma_f32_16x16x32_bf16 v[0:3], v[188:191], v[220:223], 0
	v_mfma_f32_16x16x32_bf16 v[52:55], v[184:187], v[200:203], v[52:55]
	v_mfma_f32_16x16x32_bf16 v[48:51], v[192:195], v[200:203], v[48:51]
	v_mfma_f32_16x16x32_bf16 v[36:39], v[184:187], v[208:211], v[36:39]
	v_mfma_f32_16x16x32_bf16 v[32:35], v[192:195], v[208:211], v[32:35]
	v_mfma_f32_16x16x32_bf16 v[20:23], v[184:187], v[216:219], v[20:23]
	v_mfma_f32_16x16x32_bf16 v[16:19], v[192:195], v[216:219], v[16:19]
	v_mfma_f32_16x16x32_bf16 v[4:7], v[184:187], v[224:227], v[4:7]
	v_mfma_f32_16x16x32_bf16 v[0:3], v[192:195], v[224:227], v[0:3]
	s_setprio 0
	s_barrier
	s_add_i32 s14, 0, 0x18000
	v_add_u32_e32 v175, s14, v168
	s_add_i32 s15, 0, 0x1c000
	ds_read_b128 v[152:155], v175
	ds_read_b128 v[156:159], v175 offset:1024
	ds_read_b128 v[160:163], v175 offset:2048
	ds_read_b128 v[176:179], v175 offset:3072
	v_add_u32_e32 v175, s15, v168
	ds_read_b128 v[180:183], v175
	ds_read_b128 v[184:187], v175 offset:1024
	ds_read_b128 v[188:191], v175 offset:2048
	ds_read_b128 v[192:195], v175 offset:3072
	s_add_u32 s10, s66, 0x40000
	s_addc_u32 s11, s67, 0
	s_mov_b32 m0, s81
	v_lshl_add_u64 v[234:235], s[10:11], 0, v[128:129]
	ds_read_b128 v[196:199], v171 offset:32768
	ds_read_b128 v[200:203], v171 offset:33792
	ds_read_b128 v[204:207], v171 offset:34816
	ds_read_b128 v[208:211], v171 offset:35840
	ds_read_b128 v[212:215], v171 offset:36864
	ds_read_b128 v[216:219], v171 offset:37888
	ds_read_b128 v[220:223], v171 offset:38912
	ds_read_b128 v[224:227], v171 offset:39936
	global_load_lds_dwordx4 v[234:235], off
	v_lshl_add_u64 v[234:235], s[10:11], 0, v[132:133]
	s_mov_b32 m0, s12
	s_nop 0
	global_load_lds_dwordx4 v[234:235], off
	s_waitcnt vmcnt(8)
	s_waitcnt lgkmcnt(0)
	s_barrier
	s_setprio 1
	s_waitcnt lgkmcnt(0)
	v_mfma_f32_16x16x32_bf16 v[124:127], v[152:155], v[196:199], v[124:127]
	v_mfma_f32_16x16x32_bf16 v[120:123], v[160:163], v[196:199], v[120:123]
	v_mfma_f32_16x16x32_bf16 v[108:111], v[152:155], v[204:207], v[108:111]
	v_mfma_f32_16x16x32_bf16 v[104:107], v[160:163], v[204:207], v[104:107]
	v_mfma_f32_16x16x32_bf16 v[92:95], v[152:155], v[212:215], v[92:95]
	v_mfma_f32_16x16x32_bf16 v[88:91], v[160:163], v[212:215], v[88:91]
	v_mfma_f32_16x16x32_bf16 v[76:79], v[152:155], v[220:223], v[76:79]
	v_mfma_f32_16x16x32_bf16 v[72:75], v[160:163], v[220:223], v[72:75]
	v_mfma_f32_16x16x32_bf16 v[124:127], v[156:159], v[200:203], v[124:127]
	v_mfma_f32_16x16x32_bf16 v[120:123], v[176:179], v[200:203], v[120:123]
	v_mfma_f32_16x16x32_bf16 v[108:111], v[156:159], v[208:211], v[108:111]
	v_mfma_f32_16x16x32_bf16 v[104:107], v[176:179], v[208:211], v[104:107]
	v_mfma_f32_16x16x32_bf16 v[92:95], v[156:159], v[216:219], v[92:95]
	v_mfma_f32_16x16x32_bf16 v[88:91], v[176:179], v[216:219], v[88:91]
	v_mfma_f32_16x16x32_bf16 v[76:79], v[156:159], v[224:227], v[76:79]
	v_mfma_f32_16x16x32_bf16 v[72:75], v[176:179], v[224:227], v[72:75]
	s_setprio 0
	s_setprio 1
	v_mfma_f32_16x16x32_bf16 v[116:119], v[180:183], v[196:199], v[116:119]
	v_mfma_f32_16x16x32_bf16 v[112:115], v[188:191], v[196:199], v[112:115]
	v_mfma_f32_16x16x32_bf16 v[100:103], v[180:183], v[204:207], v[100:103]
	v_mfma_f32_16x16x32_bf16 v[96:99], v[188:191], v[204:207], v[96:99]
	v_mfma_f32_16x16x32_bf16 v[84:87], v[180:183], v[212:215], v[84:87]
	v_mfma_f32_16x16x32_bf16 v[80:83], v[188:191], v[212:215], v[80:83]
	v_mfma_f32_16x16x32_bf16 v[68:71], v[180:183], v[220:223], v[68:71]
	v_mfma_f32_16x16x32_bf16 v[64:67], v[188:191], v[220:223], v[64:67]
	v_mfma_f32_16x16x32_bf16 v[116:119], v[184:187], v[200:203], v[116:119]
	v_mfma_f32_16x16x32_bf16 v[112:115], v[192:195], v[200:203], v[112:115]
	v_mfma_f32_16x16x32_bf16 v[100:103], v[184:187], v[208:211], v[100:103]
	v_mfma_f32_16x16x32_bf16 v[96:99], v[192:195], v[208:211], v[96:99]
	v_mfma_f32_16x16x32_bf16 v[84:87], v[184:187], v[216:219], v[84:87]
	v_mfma_f32_16x16x32_bf16 v[80:83], v[192:195], v[216:219], v[80:83]
	v_mfma_f32_16x16x32_bf16 v[68:71], v[184:187], v[224:227], v[68:71]
	v_mfma_f32_16x16x32_bf16 v[64:67], v[192:195], v[224:227], v[64:67]
	s_setprio 0
	s_barrier
; #define PG8_STAGE(bufoff, gbase, voff) do { _Pragma("unroll") for (int _i = 0; _i < 2; ++_i) \
;         __builtin_amdgcn_global_load_lds((const unsigned*)((const char*)(gbase) + (voff)[_i]), (PG8_LAS unsigned*)(lds + (bufoff) + ldsw + _i * 8192), 16, 0, 0); } while (0)
; #define PG8_LDA(dst, b, h) do { _Pragma("unroll") for (int m = 0; m < 4; ++m) _Pragma("unroll") for (int k = 0; k < 2; ++k) dst[m][k] = *(const PG8_LAS bf16x8*)(lds + PG8_SA(b, h) + aoff + m * 2048 + k * 1024); } while (0)
; #define PG8_MMA(ai, bj, At, Bt) do { __builtin_amdgcn_s_setprio(1); _Pragma("unroll") for (int m = 0; m < 4; ++m) _Pragma("unroll") for (int n = 0; n < 2; ++n) _Pragma("unroll") for (int k = 0; k < 2; ++k) \
;         acc[ai][bj][m][n] = __builtin_amdgcn_mfma_f32_16x16x32_bf16(Bt[n][k], At[m][k], acc[ai][bj][m][n], 0, 0, 0); __builtin_amdgcn_s_setprio(0); } while (0)
; #define PG8_WAIT_V(n) asm volatile("s_waitcnt vmcnt(" #n ")" ::: "memory")
; #define PG8_WAIT_L(n) asm volatile("s_waitcnt lgkmcnt(" #n ")" ::: "memory")
; #define PG8_BAR __builtin_amdgcn_s_barrier()
; #define PG8_SCHED __builtin_amdgcn_sched_barrier(0)
; template <class Epi, class Sched, bool ALIGN_EPI = false, bool SP2 = false, bool ABLK = false>
; __device__ __forceinline__ void gemm_phase(PG8_LAS unsigned char* lds, const Gemm g, const Sched& S, const Epi& E) {
;     ...
;             PG8_LDA(At, 1, 1); PG8_STAGE(PG8_SB(1, 0), b3, voffB); PG8_STAGE(PG8_SB(1, 1), b3 + hstep, voffB); PG8_STAGE(PG8_SA(1, 0), a3, voffA);
;             PG8_WAIT_V(8); PG8_WAIT_L(0); PG8_BAR; PG8_MMA(1, 0, At, B0); PG8_MMA(1, 1, At, B1); PG8_BAR; PG8_SCHED;
	s_add_i32 s10, s14, s74
	v_lshl_add_u64 v[164:165], v[164:165], 0, s[28:29]
	s_mov_b32 m0, s10
	ds_read_b128 v[196:199], v171 offset:49152
	ds_read_b128 v[200:203], v171 offset:50176
	ds_read_b128 v[204:207], v171 offset:51200
	ds_read_b128 v[208:211], v171 offset:52224
	ds_read_b128 v[212:215], v171 offset:53248
	ds_read_b128 v[216:219], v171 offset:54272
	ds_read_b128 v[220:223], v171 offset:55296
	ds_read_b128 v[224:227], v171 offset:56320
	global_load_lds_dwordx4 v[164:165], off
	s_add_i32 m0, s10, 0x2000
	s_add_u32 s10, s52, 0x40080
	v_lshl_add_u64 v[164:165], v[228:229], 0, s[28:29]
	s_addc_u32 s11, s53, 0
	s_add_i32 s14, s15, s74
	global_load_lds_dwordx4 v[164:165], off
	v_lshl_add_u64 v[164:165], s[10:11], 0, v[130:131]
	s_mov_b32 m0, s14
	s_nop 0
	global_load_lds_dwordx4 v[164:165], off
	v_lshl_add_u64 v[164:165], s[10:11], 0, v[134:135]
	s_add_i32 m0, s14, 0x2000
	s_nop 0
	global_load_lds_dwordx4 v[164:165], off
	v_lshl_add_u64 v[164:165], v[230:231], 0, s[28:29]
	s_mov_b32 m0, s50
	s_nop 0
	global_load_lds_dwordx4 v[164:165], off
	v_lshl_add_u64 v[164:165], v[232:233], 0, s[28:29]
	s_mov_b32 m0, s51
	s_nop 0
	global_load_lds_dwordx4 v[164:165], off
	s_waitcnt vmcnt(8)
	s_waitcnt lgkmcnt(0)
	s_barrier
	s_setprio 1
	s_waitcnt lgkmcnt(0)
	v_mfma_f32_16x16x32_bf16 v[60:63], v[152:155], v[196:199], v[60:63]
	v_mfma_f32_16x16x32_bf16 v[56:59], v[160:163], v[196:199], v[56:59]
	v_mfma_f32_16x16x32_bf16 v[44:47], v[152:155], v[204:207], v[44:47]
	v_mfma_f32_16x16x32_bf16 v[40:43], v[160:163], v[204:207], v[40:43]
	v_mfma_f32_16x16x32_bf16 v[28:31], v[152:155], v[212:215], v[28:31]
	v_mfma_f32_16x16x32_bf16 v[24:27], v[160:163], v[212:215], v[24:27]
	v_mfma_f32_16x16x32_bf16 v[12:15], v[152:155], v[220:223], v[12:15]
	v_mfma_f32_16x16x32_bf16 v[8:11], v[160:163], v[220:223], v[8:11]
	v_mfma_f32_16x16x32_bf16 v[60:63], v[156:159], v[200:203], v[60:63]
	v_mfma_f32_16x16x32_bf16 v[56:59], v[176:179], v[200:203], v[56:59]
	v_mfma_f32_16x16x32_bf16 v[44:47], v[156:159], v[208:211], v[44:47]
	v_mfma_f32_16x16x32_bf16 v[40:43], v[176:179], v[208:211], v[40:43]
	v_mfma_f32_16x16x32_bf16 v[28:31], v[156:159], v[216:219], v[28:31]
	v_mfma_f32_16x16x32_bf16 v[24:27], v[176:179], v[216:219], v[24:27]
	v_mfma_f32_16x16x32_bf16 v[12:15], v[156:159], v[224:227], v[12:15]
	v_mfma_f32_16x16x32_bf16 v[8:11], v[176:179], v[224:227], v[8:11]
	s_setprio 0
	s_setprio 1
	v_mfma_f32_16x16x32_bf16 v[52:55], v[180:183], v[196:199], v[52:55]
	v_mfma_f32_16x16x32_bf16 v[48:51], v[188:191], v[196:199], v[48:51]
	v_mfma_f32_16x16x32_bf16 v[36:39], v[180:183], v[204:207], v[36:39]
	v_mfma_f32_16x16x32_bf16 v[32:35], v[188:191], v[204:207], v[32:35]
	v_mfma_f32_16x16x32_bf16 v[20:23], v[180:183], v[212:215], v[20:23]
	v_mfma_f32_16x16x32_bf16 v[16:19], v[188:191], v[212:215], v[16:19]
	v_mfma_f32_16x16x32_bf16 v[4:7], v[180:183], v[220:223], v[4:7]
	v_mfma_f32_16x16x32_bf16 v[0:3], v[188:191], v[220:223], v[0:3]
	v_mfma_f32_16x16x32_bf16 v[52:55], v[184:187], v[200:203], v[52:55]
	v_mfma_f32_16x16x32_bf16 v[48:51], v[192:195], v[200:203], v[48:51]
	v_mfma_f32_16x16x32_bf16 v[36:39], v[184:187], v[208:211], v[36:39]
	v_mfma_f32_16x16x32_bf16 v[32:35], v[192:195], v[208:211], v[32:35]
	v_mfma_f32_16x16x32_bf16 v[20:23], v[184:187], v[216:219], v[20:23]
	v_mfma_f32_16x16x32_bf16 v[16:19], v[192:195], v[216:219], v[16:19]
	v_mfma_f32_16x16x32_bf16 v[4:7], v[184:187], v[224:227], v[4:7]
	v_mfma_f32_16x16x32_bf16 v[0:3], v[192:195], v[224:227], v[0:3]
	s_setprio 0
	s_barrier
	s_add_i32 s9, s9, 2
	s_add_u32 s42, s42, 0x100
	s_addc_u32 s43, s43, 0
	s_add_u32 s7, s7, 0x100
	s_addc_u32 s8, s8, 0
	s_cmp_gt_u32 s9, 13
	s_cbranch_scc1 .Lpeel_post_2

; #define PG8_BAR __builtin_amdgcn_s_barrier()
; template <class Epi, class Sched, bool ALIGN_EPI = false, bool SP2 = false, bool ABLK = false>
; __device__ __forceinline__ void gemm_phase(PG8_LAS unsigned char* lds, const Gemm g, const Sched& S, const Epi& E) {
;     ...
;         if (!has_next) break;
; #pragma unroll
;         for (int a = 0; a < 2; ++a)
; #pragma unroll
;             for (int b = 0; b < 2; ++b)
; #pragma unroll
;                 for (int m = 0; m < 4; ++m)
; #pragma unroll
;                     for (int n = 0; n < 2; ++n) acc[a][b][m][n] = (f32x4){0.f, 0.f, 0.f, 0.f};
;         cur = nxt; cA = nA; cB = nB; ++ui;
;         if constexpr (ALIGN_EPI) { if (wr == 1) PG8_BAR; }
.LBB0_405:
	s_andn2_b64 vcc, exec, s[20:21]
	s_cbranch_vccnz .LBB0_340
	s_mov_b32 s98, 1
	s_branch .LBB0_340

; #define PG8_STAGE(bufoff, gbase, voff) do { _Pragma("unroll") for (int _i = 0; _i < 2; ++_i) \
;         __builtin_amdgcn_global_load_lds((const unsigned*)((const char*)(gbase) + (voff)[_i]), (PG8_LAS unsigned*)(lds + (bufoff) + ldsw + _i * 8192), 16, 0, 0); } while (0)
; #define PG8_LDA(dst, b, h) do { _Pragma("unroll") for (int m = 0; m < 4; ++m) _Pragma("unroll") for (int k = 0; k < 2; ++k) dst[m][k] = *(const PG8_LAS bf16x8*)(lds + PG8_SA(b, h) + aoff + m * 2048 + k * 1024); } while (0)
; #define PG8_LDB(dst, b, h) do { _Pragma("unroll") for (int n = 0; n < 2; ++n) _Pragma("unroll") for (int k = 0; k < 2; ++k) dst[n][k] = *(const PG8_LAS bf16x8*)(lds + PG8_SB(b, h) + boff + n * 2048 + k * 1024); } while (0)
; #define PG8_MMA(ai, bj, At, Bt) do { __builtin_amdgcn_s_setprio(1); _Pragma("unroll") for (int m = 0; m < 4; ++m) _Pragma("unroll") for (int n = 0; n < 2; ++n) _Pragma("unroll") for (int k = 0; k < 2; ++k) \
;         acc[ai][bj][m][n] = __builtin_amdgcn_mfma_f32_16x16x32_bf16(Bt[n][k], At[m][k], acc[ai][bj][m][n], 0, 0, 0); __builtin_amdgcn_s_setprio(0); } while (0)
; template <class Epi, class Sched, bool ALIGN_EPI = false, bool SP2 = false, bool ABLK = false>
; __device__ __forceinline__ void gemm_phase(PG8_LAS unsigned char* lds, const Gemm g, const Sched& S, const Epi& E) {
;     ...
;     for (;;) {
;         const bool has_next = S.next(ui + 1, nxt);
;         const char* nA = has_next ? (const char*)g.A + (size_t)nxt.pm * tstep : cA; const char* nB = has_next ? (const char*)g.Bt + (size_t)nxt.pn * tstep : cB;
;         for (int t = 0; t < nt; t += 2) {
;             const bool last = (t == nt - 2);
;             const char* a1 = cA + (size_t)(t + 1) * kstepA;
;             const char* a2 = last ? nA : cA + (size_t)(t + 2) * kstepA; const char* b2 = last ? nB : cB + (size_t)(t + 2) * kstep;
;             const char* a3 = a2 + kstepA; const char* b3 = b2 + kstep;
;             if (last && has_next) S.a_ready(nxt);
;             if constexpr (SP2) {
;             PG8_LDB(B0, 0, 0); PG8_LDB(B1, 0, 1); PG8_SCHED; PG8_LDA(At, 0, 0); PG8_STAGE(PG8_SA(1, 1), a1 + hstepA, voffA);
;             PG8_WAIT_V(8); PG8_WAIT_L(0); PG8_BAR; PG8_MMA(0, 0, At, B0); PG8_MMA(0, 1, At, B1); PG8_BAR; PG8_SCHED;
;             PG8_LDA(At, 0, 1); PG8_STAGE(PG8_SB(0, 0), b2, voffB); PG8_STAGE(PG8_SB(0, 1), b2 + hstep, voffB); PG8_STAGE(PG8_SA(0, 0), a2, voffA);
.LBB0_823:
	s_ashr_i32 s43, s42, 31
	s_lshl_b64 s[4:5], s[42:43], 19
	s_add_u32 s46, s96, s4
	s_addc_u32 s47, s97, s5
	s_and_b64 s[4:5], s[38:39], exec
	s_cselect_b32 s4, s47, s37
	s_cselect_b32 s5, s46, s36
	s_ashr_i32 s41, s40, 31
	s_lshl_b64 s[6:7], s[40:41], 19
	s_add_u32 s48, s55, s6
	s_addc_u32 s49, s56, s7
	s_and_b64 s[6:7], s[38:39], exec
	s_cselect_b32 s6, s49, s51
	s_cselect_b32 s7, s48, s50
	s_add_u32 s36, s36, 0x40080
	s_addc_u32 s37, s37, 0
	s_add_u32 s8, s50, 0x100
	v_mov_b32_e32 v0, 0
	s_addc_u32 s9, s51, 0
	s_mov_b32 s10, -2
	s_cmp_eq_u32 s98, 1
	s_cbranch_scc0 .Ldefbar_3
	s_barrier
	s_mov_b32 s98, 0
.Ldefbar_3:
.LBB0_824:
	ds_read_b128 v[156:159], v162
	ds_read_b128 v[168:171], v162 offset:1024
	ds_read_b128 v[172:175], v162 offset:2048
	ds_read_b128 v[176:179], v162 offset:3072
	ds_read_b128 v[180:183], v163
	ds_read_b128 v[184:187], v163 offset:1024
	ds_read_b128 v[188:191], v163 offset:2048
	ds_read_b128 v[192:195], v163 offset:3072
	s_add_u32 s11, s36, 0xfffc0080
	s_addc_u32 s14, s37, -1
	s_cmp_eq_u32 s10, 12
	s_cselect_b32 s53, s4, s14
	s_cselect_b32 s52, s5, s11
	s_cselect_b32 s51, s6, s9
	s_cselect_b32 s50, s7, s8
	v_lshl_add_u64 v[228:229], s[36:37], 0, v[148:149]
	s_add_i32 m0, s58, 0xc000
	ds_read_b128 v[196:199], v164
	ds_read_b128 v[200:203], v164 offset:1024
	ds_read_b128 v[204:207], v164 offset:2048
	ds_read_b128 v[208:211], v164 offset:3072
	ds_read_b128 v[212:215], v164 offset:4096
	ds_read_b128 v[216:219], v164 offset:5120
	ds_read_b128 v[220:223], v164 offset:6144
	ds_read_b128 v[224:227], v164 offset:7168
	global_load_lds_dwordx4 v[228:229], off
	v_lshl_add_u64 v[228:229], s[36:37], 0, v[150:151]
	s_add_i32 m0, s58, 0xe000
	s_nop 0
	global_load_lds_dwordx4 v[228:229], off
	s_waitcnt vmcnt(8)
	s_waitcnt lgkmcnt(0)
	s_barrier
	s_setprio 1
	s_waitcnt lgkmcnt(0)
	v_mfma_f32_16x16x32_bf16 v[124:127], v[156:159], v[196:199], 0
	v_mfma_f32_16x16x32_bf16 v[120:123], v[172:175], v[196:199], 0
	v_mfma_f32_16x16x32_bf16 v[108:111], v[156:159], v[204:207], 0
	v_mfma_f32_16x16x32_bf16 v[104:107], v[172:175], v[204:207], 0
	v_mfma_f32_16x16x32_bf16 v[92:95], v[156:159], v[212:215], 0
	v_mfma_f32_16x16x32_bf16 v[88:91], v[172:175], v[212:215], 0
	v_mfma_f32_16x16x32_bf16 v[76:79], v[156:159], v[220:223], 0
	v_mfma_f32_16x16x32_bf16 v[72:75], v[172:175], v[220:223], 0
	v_mfma_f32_16x16x32_bf16 v[124:127], v[168:171], v[200:203], v[124:127]
	v_mfma_f32_16x16x32_bf16 v[120:123], v[176:179], v[200:203], v[120:123]
	v_mfma_f32_16x16x32_bf16 v[108:111], v[168:171], v[208:211], v[108:111]
	v_mfma_f32_16x16x32_bf16 v[104:107], v[176:179], v[208:211], v[104:107]
	v_mfma_f32_16x16x32_bf16 v[92:95], v[168:171], v[216:219], v[92:95]
	v_mfma_f32_16x16x32_bf16 v[88:91], v[176:179], v[216:219], v[88:91]
	v_mfma_f32_16x16x32_bf16 v[76:79], v[168:171], v[224:227], v[76:79]
	v_mfma_f32_16x16x32_bf16 v[72:75], v[176:179], v[224:227], v[72:75]
	s_setprio 0
	s_setprio 1
	v_mfma_f32_16x16x32_bf16 v[116:119], v[180:183], v[196:199], 0
	v_mfma_f32_16x16x32_bf16 v[112:115], v[188:191], v[196:199], 0
	v_mfma_f32_16x16x32_bf16 v[100:103], v[180:183], v[204:207], 0
	v_mfma_f32_16x16x32_bf16 v[96:99], v[188:191], v[204:207], 0
	v_mfma_f32_16x16x32_bf16 v[84:87], v[180:183], v[212:215], 0
	v_mfma_f32_16x16x32_bf16 v[80:83], v[188:191], v[212:215], 0
	v_mfma_f32_16x16x32_bf16 v[68:71], v[180:183], v[220:223], 0
	v_mfma_f32_16x16x32_bf16 v[64:67], v[188:191], v[220:223], 0
	v_mfma_f32_16x16x32_bf16 v[116:119], v[184:187], v[200:203], v[116:119]
	v_mfma_f32_16x16x32_bf16 v[112:115], v[192:195], v[200:203], v[112:115]
	v_mfma_f32_16x16x32_bf16 v[100:103], v[184:187], v[208:211], v[100:103]
	v_mfma_f32_16x16x32_bf16 v[96:99], v[192:195], v[208:211], v[96:99]
	v_mfma_f32_16x16x32_bf16 v[84:87], v[184:187], v[216:219], v[84:87]
	v_mfma_f32_16x16x32_bf16 v[80:83], v[192:195], v[216:219], v[80:83]
	v_mfma_f32_16x16x32_bf16 v[68:71], v[184:187], v[224:227], v[68:71]
	v_mfma_f32_16x16x32_bf16 v[64:67], v[192:195], v[224:227], v[64:67]
	s_setprio 0
	s_barrier
	s_add_i32 s11, s70, s54
	v_lshl_add_u64 v[228:229], s[50:51], 0, v[132:133]
	s_mov_b32 m0, s11
	ds_read_b128 v[196:199], v164 offset:16384
	ds_read_b128 v[200:203], v164 offset:17408
	ds_read_b128 v[204:207], v164 offset:18432
	ds_read_b128 v[208:211], v164 offset:19456
	ds_read_b128 v[212:215], v164 offset:20480
	ds_read_b128 v[216:219], v164 offset:21504
	ds_read_b128 v[220:223], v164 offset:22528
	ds_read_b128 v[224:227], v164 offset:23552
	global_load_lds_dwordx4 v[228:229], off
	s_add_i32 m0, s11, 0x2000
	s_add_u32 s14, s50, 0x40000
	v_lshl_add_u64 v[230:231], s[50:51], 0, v[128:129]
	s_addc_u32 s15, s51, 0
	s_add_i32 s11, s71, s54
	global_load_lds_dwordx4 v[230:231], off
	v_lshl_add_u64 v[232:233], s[14:15], 0, v[132:133]
	s_mov_b32 m0, s11
	v_lshl_add_u64 v[234:235], s[52:53], 0, v[130:131]
	global_load_lds_dwordx4 v[232:233], off
	v_lshl_add_u64 v[232:233], s[14:15], 0, v[128:129]
	s_add_i32 m0, s11, 0x2000
	s_nop 0
	global_load_lds_dwordx4 v[232:233], off
	v_lshl_add_u64 v[232:233], s[52:53], 0, v[134:135]
	s_mov_b32 m0, s58
	s_nop 0
	global_load_lds_dwordx4 v[232:233], off
	s_mov_b32 m0, s59
	s_nop 0
	global_load_lds_dwordx4 v[234:235], off
	s_waitcnt vmcnt(8)
	s_waitcnt lgkmcnt(0)
	s_barrier
; #define PG8_STAGE(bufoff, gbase, voff) do { _Pragma("unroll") for (int _i = 0; _i < 2; ++_i) \
;         __builtin_amdgcn_global_load_lds((const unsigned*)((const char*)(gbase) + (voff)[_i]), (PG8_LAS unsigned*)(lds + (bufoff) + ldsw + _i * 8192), 16, 0, 0); } while (0)
; #define PG8_LDA(dst, b, h) do { _Pragma("unroll") for (int m = 0; m < 4; ++m) _Pragma("unroll") for (int k = 0; k < 2; ++k) dst[m][k] = *(const PG8_LAS bf16x8*)(lds + PG8_SA(b, h) + aoff + m * 2048 + k * 1024); } while (0)
; #define PG8_LDB(dst, b, h) do { _Pragma("unroll") for (int n = 0; n < 2; ++n) _Pragma("unroll") for (int k = 0; k < 2; ++k) dst[n][k] = *(const PG8_LAS bf16x8*)(lds + PG8_SB(b, h) + boff + n * 2048 + k * 1024); } while (0)
; #define PG8_MMA(ai, bj, At, Bt) do { __builtin_amdgcn_s_setprio(1); _Pragma("unroll") for (int m = 0; m < 4; ++m) _Pragma("unroll") for (int n = 0; n < 2; ++n) _Pragma("unroll") for (int k = 0; k < 2; ++k) \
;         acc[ai][bj][m][n] = __builtin_amdgcn_mfma_f32_16x16x32_bf16(Bt[n][k], At[m][k], acc[ai][bj][m][n], 0, 0, 0); __builtin_amdgcn_s_setprio(0); } while (0)
; #define PG8_WAIT_V(n) asm volatile("s_waitcnt vmcnt(" #n ")" ::: "memory")
; #define PG8_WAIT_L(n) asm volatile("s_waitcnt lgkmcnt(" #n ")" ::: "memory")
; #define PG8_BAR __builtin_amdgcn_s_barrier()
; #define PG8_SCHED __builtin_amdgcn_sched_barrier(0)
; template <class Epi, class Sched, bool ALIGN_EPI = false, bool SP2 = false, bool ABLK = false>
; __device__ __forceinline__ void gemm_phase(PG8_LAS unsigned char* lds, const Gemm g, const Sched& S, const Epi& E) {
;     ...
;             PG8_WAIT_V(8); PG8_WAIT_L(0); PG8_BAR; PG8_MMA(1, 0, At, B0); PG8_MMA(1, 1, At, B1); PG8_BAR; PG8_SCHED;
;             PG8_LDB(B0, 1, 0); PG8_LDB(B1, 1, 1); PG8_SCHED; PG8_LDA(At, 1, 0); PG8_STAGE(PG8_SA(0, 1), a2 + hstepA, voffA);
;             PG8_WAIT_V(8); PG8_WAIT_L(0); PG8_BAR; PG8_MMA(0, 0, At, B0); PG8_MMA(0, 1, At, B1); PG8_BAR; PG8_SCHED;
;             PG8_LDA(At, 1, 1); PG8_STAGE(PG8_SB(1, 0), b3, voffB); PG8_STAGE(PG8_SB(1, 1), b3 + hstep, voffB); PG8_STAGE(PG8_SA(1, 0), a3, voffA);
	s_setprio 1
	s_waitcnt lgkmcnt(0)
	v_mfma_f32_16x16x32_bf16 v[60:63], v[156:159], v[196:199], 0
	v_mfma_f32_16x16x32_bf16 v[56:59], v[172:175], v[196:199], 0
	v_mfma_f32_16x16x32_bf16 v[44:47], v[156:159], v[204:207], 0
	v_mfma_f32_16x16x32_bf16 v[40:43], v[172:175], v[204:207], 0
	v_mfma_f32_16x16x32_bf16 v[28:31], v[156:159], v[212:215], 0
	v_mfma_f32_16x16x32_bf16 v[24:27], v[172:175], v[212:215], 0
	v_mfma_f32_16x16x32_bf16 v[12:15], v[156:159], v[220:223], 0
	v_mfma_f32_16x16x32_bf16 v[8:11], v[172:175], v[220:223], 0
	v_mfma_f32_16x16x32_bf16 v[60:63], v[168:171], v[200:203], v[60:63]
	v_mfma_f32_16x16x32_bf16 v[56:59], v[176:179], v[200:203], v[56:59]
	v_mfma_f32_16x16x32_bf16 v[44:47], v[168:171], v[208:211], v[44:47]
	v_mfma_f32_16x16x32_bf16 v[40:43], v[176:179], v[208:211], v[40:43]
	v_mfma_f32_16x16x32_bf16 v[28:31], v[168:171], v[216:219], v[28:31]
	v_mfma_f32_16x16x32_bf16 v[24:27], v[176:179], v[216:219], v[24:27]
	v_mfma_f32_16x16x32_bf16 v[12:15], v[168:171], v[224:227], v[12:15]
	v_mfma_f32_16x16x32_bf16 v[8:11], v[176:179], v[224:227], v[8:11]
	s_setprio 0
	s_setprio 1
	v_mfma_f32_16x16x32_bf16 v[52:55], v[180:183], v[196:199], 0
	v_mfma_f32_16x16x32_bf16 v[48:51], v[188:191], v[196:199], 0
	v_mfma_f32_16x16x32_bf16 v[36:39], v[180:183], v[204:207], 0
	v_mfma_f32_16x16x32_bf16 v[32:35], v[188:191], v[204:207], 0
	v_mfma_f32_16x16x32_bf16 v[20:23], v[180:183], v[212:215], 0
	v_mfma_f32_16x16x32_bf16 v[16:19], v[188:191], v[212:215], 0
	v_mfma_f32_16x16x32_bf16 v[4:7], v[180:183], v[220:223], 0
	v_mfma_f32_16x16x32_bf16 v[0:3], v[188:191], v[220:223], 0
	v_mfma_f32_16x16x32_bf16 v[52:55], v[184:187], v[200:203], v[52:55]
	v_mfma_f32_16x16x32_bf16 v[48:51], v[192:195], v[200:203], v[48:51]
	v_mfma_f32_16x16x32_bf16 v[36:39], v[184:187], v[208:211], v[36:39]
	v_mfma_f32_16x16x32_bf16 v[32:35], v[192:195], v[208:211], v[32:35]
	v_mfma_f32_16x16x32_bf16 v[20:23], v[184:187], v[216:219], v[20:23]
	v_mfma_f32_16x16x32_bf16 v[16:19], v[192:195], v[216:219], v[16:19]
	v_mfma_f32_16x16x32_bf16 v[4:7], v[184:187], v[224:227], v[4:7]
	v_mfma_f32_16x16x32_bf16 v[0:3], v[192:195], v[224:227], v[0:3]
	s_setprio 0
	s_barrier
	s_add_i32 s11, 0, 0x18000
	s_add_i32 s16, 0, 0x1c000
	v_add_u32_e32 v176, s11, v161
	v_add_u32_e32 v192, s16, v161
	ds_read_b128 v[156:159], v176
	ds_read_b128 v[168:171], v176 offset:1024
	ds_read_b128 v[172:175], v176 offset:2048
	ds_read_b128 v[176:179], v176 offset:3072
	ds_read_b128 v[180:183], v192
	ds_read_b128 v[184:187], v192 offset:1024
	ds_read_b128 v[188:191], v192 offset:2048
	ds_read_b128 v[192:195], v192 offset:3072
	s_add_u32 s14, s52, 0x40000
	s_addc_u32 s15, s53, 0
	s_mov_b32 m0, s60
	v_lshl_add_u64 v[236:237], s[14:15], 0, v[134:135]
	ds_read_b128 v[196:199], v164 offset:32768
	ds_read_b128 v[200:203], v164 offset:33792
	ds_read_b128 v[204:207], v164 offset:34816
	ds_read_b128 v[208:211], v164 offset:35840
	ds_read_b128 v[212:215], v164 offset:36864
	ds_read_b128 v[216:219], v164 offset:37888
	ds_read_b128 v[220:223], v164 offset:38912
	ds_read_b128 v[224:227], v164 offset:39936
	global_load_lds_dwordx4 v[236:237], off
	v_lshl_add_u64 v[236:237], s[14:15], 0, v[130:131]
	s_mov_b32 m0, s61
	s_nop 0
	global_load_lds_dwordx4 v[236:237], off
	s_waitcnt vmcnt(8)
	s_waitcnt lgkmcnt(0)
	s_barrier
	s_setprio 1
	s_waitcnt lgkmcnt(0)
	v_mfma_f32_16x16x32_bf16 v[124:127], v[156:159], v[196:199], v[124:127]
	v_mfma_f32_16x16x32_bf16 v[120:123], v[172:175], v[196:199], v[120:123]
	v_mfma_f32_16x16x32_bf16 v[108:111], v[156:159], v[204:207], v[108:111]
	v_mfma_f32_16x16x32_bf16 v[104:107], v[172:175], v[204:207], v[104:107]
	v_mfma_f32_16x16x32_bf16 v[92:95], v[156:159], v[212:215], v[92:95]
	v_mfma_f32_16x16x32_bf16 v[88:91], v[172:175], v[212:215], v[88:91]
	v_mfma_f32_16x16x32_bf16 v[76:79], v[156:159], v[220:223], v[76:79]
	v_mfma_f32_16x16x32_bf16 v[72:75], v[172:175], v[220:223], v[72:75]
	v_mfma_f32_16x16x32_bf16 v[124:127], v[168:171], v[200:203], v[124:127]
	v_mfma_f32_16x16x32_bf16 v[120:123], v[176:179], v[200:203], v[120:123]
	v_mfma_f32_16x16x32_bf16 v[108:111], v[168:171], v[208:211], v[108:111]
	v_mfma_f32_16x16x32_bf16 v[104:107], v[176:179], v[208:211], v[104:107]
	v_mfma_f32_16x16x32_bf16 v[92:95], v[168:171], v[216:219], v[92:95]
	v_mfma_f32_16x16x32_bf16 v[88:91], v[176:179], v[216:219], v[88:91]
	v_mfma_f32_16x16x32_bf16 v[76:79], v[168:171], v[224:227], v[76:79]
	v_mfma_f32_16x16x32_bf16 v[72:75], v[176:179], v[224:227], v[72:75]
	s_setprio 0
	s_setprio 1
	v_mfma_f32_16x16x32_bf16 v[116:119], v[180:183], v[196:199], v[116:119]
	v_mfma_f32_16x16x32_bf16 v[112:115], v[188:191], v[196:199], v[112:115]
	v_mfma_f32_16x16x32_bf16 v[100:103], v[180:183], v[204:207], v[100:103]
	v_mfma_f32_16x16x32_bf16 v[96:99], v[188:191], v[204:207], v[96:99]
	v_mfma_f32_16x16x32_bf16 v[84:87], v[180:183], v[212:215], v[84:87]
	v_mfma_f32_16x16x32_bf16 v[80:83], v[188:191], v[212:215], v[80:83]
	v_mfma_f32_16x16x32_bf16 v[68:71], v[180:183], v[220:223], v[68:71]
	v_mfma_f32_16x16x32_bf16 v[64:67], v[188:191], v[220:223], v[64:67]
	v_mfma_f32_16x16x32_bf16 v[116:119], v[184:187], v[200:203], v[116:119]
	v_mfma_f32_16x16x32_bf16 v[112:115], v[192:195], v[200:203], v[112:115]
	v_mfma_f32_16x16x32_bf16 v[100:103], v[184:187], v[208:211], v[100:103]
	v_mfma_f32_16x16x32_bf16 v[96:99], v[192:195], v[208:211], v[96:99]
	v_mfma_f32_16x16x32_bf16 v[84:87], v[184:187], v[216:219], v[84:87]
	v_mfma_f32_16x16x32_bf16 v[80:83], v[192:195], v[216:219], v[80:83]
	v_mfma_f32_16x16x32_bf16 v[68:71], v[184:187], v[224:227], v[68:71]
	v_mfma_f32_16x16x32_bf16 v[64:67], v[192:195], v[224:227], v[64:67]
	s_setprio 0
	s_barrier
; #define PG8_STAGE(bufoff, gbase, voff) do { _Pragma("unroll") for (int _i = 0; _i < 2; ++_i) \
;         __builtin_amdgcn_global_load_lds((const unsigned*)((const char*)(gbase) + (voff)[_i]), (PG8_LAS unsigned*)(lds + (bufoff) + ldsw + _i * 8192), 16, 0, 0); } while (0)
; #define PG8_LDA(dst, b, h) do { _Pragma("unroll") for (int m = 0; m < 4; ++m) _Pragma("unroll") for (int k = 0; k < 2; ++k) dst[m][k] = *(const PG8_LAS bf16x8*)(lds + PG8_SA(b, h) + aoff + m * 2048 + k * 1024); } while (0)
; #define PG8_MMA(ai, bj, At, Bt) do { __builtin_amdgcn_s_setprio(1); _Pragma("unroll") for (int m = 0; m < 4; ++m) _Pragma("unroll") for (int n = 0; n < 2; ++n) _Pragma("unroll") for (int k = 0; k < 2; ++k) \
;         acc[ai][bj][m][n] = __builtin_amdgcn_mfma_f32_16x16x32_bf16(Bt[n][k], At[m][k], acc[ai][bj][m][n], 0, 0, 0); __builtin_amdgcn_s_setprio(0); } while (0)
; #define PG8_WAIT_V(n) asm volatile("s_waitcnt vmcnt(" #n ")" ::: "memory")
; #define PG8_WAIT_L(n) asm volatile("s_waitcnt lgkmcnt(" #n ")" ::: "memory")
; #define PG8_BAR __builtin_amdgcn_s_barrier()
; #define PG8_SCHED __builtin_amdgcn_sched_barrier(0)
; template <class Epi, class Sched, bool ALIGN_EPI = false, bool SP2 = false, bool ABLK = false>
; __device__ __forceinline__ void gemm_phase(PG8_LAS unsigned char* lds, const Gemm g, const Sched& S, const Epi& E) {
;     ...
;             PG8_LDA(At, 1, 1); PG8_STAGE(PG8_SB(1, 0), b3, voffB); PG8_STAGE(PG8_SB(1, 1), b3 + hstep, voffB); PG8_STAGE(PG8_SA(1, 0), a3, voffA);
;             PG8_WAIT_V(8); PG8_WAIT_L(0); PG8_BAR; PG8_MMA(1, 0, At, B0); PG8_MMA(1, 1, At, B1); PG8_BAR; PG8_SCHED;
	s_add_i32 s11, s11, s54
	v_lshl_add_u64 v[228:229], v[228:229], 0, s[30:31]
	s_mov_b32 m0, s11
	ds_read_b128 v[196:199], v164 offset:49152
	ds_read_b128 v[200:203], v164 offset:50176
	ds_read_b128 v[204:207], v164 offset:51200
	ds_read_b128 v[208:211], v164 offset:52224
	ds_read_b128 v[212:215], v164 offset:53248
	ds_read_b128 v[216:219], v164 offset:54272
	ds_read_b128 v[220:223], v164 offset:55296
	ds_read_b128 v[224:227], v164 offset:56320
	global_load_lds_dwordx4 v[228:229], off
	s_add_i32 m0, s11, 0x2000
	s_add_u32 s14, s50, 0x40080
	v_lshl_add_u64 v[228:229], v[230:231], 0, s[30:31]
	s_addc_u32 s15, s51, 0
	s_add_i32 s11, s16, s54
	global_load_lds_dwordx4 v[228:229], off
	v_lshl_add_u64 v[228:229], s[14:15], 0, v[132:133]
	s_mov_b32 m0, s11
	s_nop 0
	global_load_lds_dwordx4 v[228:229], off
	v_lshl_add_u64 v[228:229], s[14:15], 0, v[128:129]
	s_add_i32 m0, s11, 0x2000
	s_nop 0
	global_load_lds_dwordx4 v[228:229], off
	v_lshl_add_u64 v[228:229], v[232:233], 0, s[30:31]
	s_mov_b32 m0, s68
	s_nop 0
	global_load_lds_dwordx4 v[228:229], off
	v_lshl_add_u64 v[228:229], v[234:235], 0, s[30:31]
	s_mov_b32 m0, s69
	s_nop 0
	global_load_lds_dwordx4 v[228:229], off
	s_waitcnt vmcnt(8)
	s_waitcnt lgkmcnt(0)
	s_barrier
	s_setprio 1
	s_waitcnt lgkmcnt(0)
	v_mfma_f32_16x16x32_bf16 v[60:63], v[156:159], v[196:199], v[60:63]
	v_mfma_f32_16x16x32_bf16 v[56:59], v[172:175], v[196:199], v[56:59]
	v_mfma_f32_16x16x32_bf16 v[44:47], v[156:159], v[204:207], v[44:47]
	v_mfma_f32_16x16x32_bf16 v[40:43], v[172:175], v[204:207], v[40:43]
	v_mfma_f32_16x16x32_bf16 v[28:31], v[156:159], v[212:215], v[28:31]
	v_mfma_f32_16x16x32_bf16 v[24:27], v[172:175], v[212:215], v[24:27]
	v_mfma_f32_16x16x32_bf16 v[12:15], v[156:159], v[220:223], v[12:15]
	v_mfma_f32_16x16x32_bf16 v[8:11], v[172:175], v[220:223], v[8:11]
	v_mfma_f32_16x16x32_bf16 v[60:63], v[168:171], v[200:203], v[60:63]
	v_mfma_f32_16x16x32_bf16 v[56:59], v[176:179], v[200:203], v[56:59]
	v_mfma_f32_16x16x32_bf16 v[44:47], v[168:171], v[208:211], v[44:47]
	v_mfma_f32_16x16x32_bf16 v[40:43], v[176:179], v[208:211], v[40:43]
	v_mfma_f32_16x16x32_bf16 v[28:31], v[168:171], v[216:219], v[28:31]
	v_mfma_f32_16x16x32_bf16 v[24:27], v[176:179], v[216:219], v[24:27]
	v_mfma_f32_16x16x32_bf16 v[12:15], v[168:171], v[224:227], v[12:15]
	v_mfma_f32_16x16x32_bf16 v[8:11], v[176:179], v[224:227], v[8:11]
	s_setprio 0
	s_setprio 1
	v_mfma_f32_16x16x32_bf16 v[52:55], v[180:183], v[196:199], v[52:55]
	v_mfma_f32_16x16x32_bf16 v[48:51], v[188:191], v[196:199], v[48:51]
	v_mfma_f32_16x16x32_bf16 v[36:39], v[180:183], v[204:207], v[36:39]
	v_mfma_f32_16x16x32_bf16 v[32:35], v[188:191], v[204:207], v[32:35]
	v_mfma_f32_16x16x32_bf16 v[20:23], v[180:183], v[212:215], v[20:23]
	v_mfma_f32_16x16x32_bf16 v[16:19], v[188:191], v[212:215], v[16:19]
	v_mfma_f32_16x16x32_bf16 v[4:7], v[180:183], v[220:223], v[4:7]
	v_mfma_f32_16x16x32_bf16 v[0:3], v[188:191], v[220:223], v[0:3]
	v_mfma_f32_16x16x32_bf16 v[52:55], v[184:187], v[200:203], v[52:55]
	v_mfma_f32_16x16x32_bf16 v[48:51], v[192:195], v[200:203], v[48:51]
	v_mfma_f32_16x16x32_bf16 v[36:39], v[184:187], v[208:211], v[36:39]
	v_mfma_f32_16x16x32_bf16 v[32:35], v[192:195], v[208:211], v[32:35]
	v_mfma_f32_16x16x32_bf16 v[20:23], v[184:187], v[216:219], v[20:23]
	v_mfma_f32_16x16x32_bf16 v[16:19], v[192:195], v[216:219], v[16:19]
	v_mfma_f32_16x16x32_bf16 v[4:7], v[184:187], v[224:227], v[4:7]
	v_mfma_f32_16x16x32_bf16 v[0:3], v[192:195], v[224:227], v[0:3]
	s_setprio 0
	s_barrier
	s_add_i32 s10, s10, 2
	s_add_u32 s36, s36, 0x100
	s_addc_u32 s37, s37, 0
	s_add_u32 s8, s8, 0x100
	s_addc_u32 s9, s9, 0
	s_cmp_gt_u32 s10, 13
	s_cbranch_scc1 .Lpeel_post_3

; __device__ __forceinline__ float silu_f(float g) { return g * __builtin_amdgcn_rcpf(1.f + __builtin_amdgcn_exp2f(-1.4426950408889634f * g)); }
; __device__ __forceinline__ u32x4 pack8(f32x4 a, f32x4 b) { u32x4 o; o.x = cvt_pk(a.x, a.y); o.y = cvt_pk(a.z, a.w); o.z = cvt_pk(b.x, b.y); o.w = cvt_pk(b.z, b.w); return o; }
; __device__ __forceinline__ float rstd_of(const float* SS, int row, float invw) { return 1.0f / sqrtf(SS[row] * invw + EPS); }
;     __device__ __forceinline__ void operator()(const f32x4 (&acc)[2][2][4][2], const pg8::Unit& u, int wr, int wc, int fr, int fq) const {
;         const int row0 = u.pm * 256 + wr * 64 + fr, col0 = u.pn * 128 + wc * 32 + 8 * fq;
;         bf16_t* hb = H + (size_t)u.pm * 256 * FF + (size_t)(col0 >> 6) * (256 * 64) + (col0 & 63);
; #pragma unroll
;         for (int ai = 0; ai < 2; ++ai)
; #pragma unroll
;             for (int m = 0; m < 4; ++m) {
;                 const int row = row0 + ai * 128 + m * 16;
;                 const float r = SCALE ? rstd_of(SS, row, 1.f / 1024.f) : 1.f;
;                 const f32x4 g0 = acc[ai][0][m][0] * r, g1 = acc[ai][0][m][1] * r, u0 = acc[ai][1][m][0] * r, u1 = acc[ai][1][m][1] * r;
;                 f32x4 h0, h1;
;                 h0.x = silu_f(g0.x) * u0.x; h0.y = silu_f(g0.y) * u0.y; h0.z = silu_f(g0.z) * u0.z; h0.w = silu_f(g0.w) * u0.w;
;                 h1.x = silu_f(g1.x) * u1.x; h1.y = silu_f(g1.y) * u1.y; h1.z = silu_f(g1.z) * u1.z; h1.w = silu_f(g1.w) * u1.w;
;                 *(u32x4*)(hb + (wr * 64 + fr + ai * 128 + m * 16) * 64) = pack8(h0, h1);
.LBB0_827:
	v_lshl_add_u32 v158, s0, 8, v160
	v_ashrrev_i32_e32 v159, 31, v158
	v_lshl_add_u64 v[158:159], v[158:159], 2, s[44:45]
	global_load_dword v200, v[158:159], off
	global_load_dword v201, v[158:159], off offset:64
	global_load_dword v202, v[158:159], off offset:128
	global_load_dword v203, v[158:159], off offset:192
	global_load_dword v204, v[158:159], off offset:512
	global_load_dword v205, v[158:159], off offset:576
	global_load_dword v206, v[158:159], off offset:640
	global_load_dword v207, v[158:159], off offset:704
	s_lshl_b32 s1, s1, 7
	s_or_b32 s1, s1, s67
	s_mul_hi_i32 s4, s0, 0x160000
	s_mul_i32 s0, s0, 0x160000
	s_add_u32 s5, s64, s0
	s_addc_u32 s4, s65, s4
	s_ashr_i32 s0, s1, 6
	s_ashr_i32 s1, s0, 31
	s_lshl_b64 s[0:1], s[0:1], 15
	s_add_u32 s0, s5, s0
	s_addc_u32 s1, s4, s1
	v_lshl_add_u64 v[156:157], s[0:1], 0, v[136:137]
	v_mov_b32_e32 v208, 0xbfb8aa3b
	v_mov_b32_e32 v209, 0xbfb8aa3b
	v_mov_b32_e32 v210, 1.0
	v_mov_b32_e32 v211, 1.0
	s_movk_i32 s0, 0x1000
	v_lshl_add_u64 v[212:213], v[138:139], 1, v[156:157]
	v_add_co_u32_e32 v214, vcc, s0, v212
	v_addc_co_u32_e32 v215, vcc, 0, v213, vcc
	v_lshl_add_u64 v[216:217], v[140:141], 1, v[156:157]
	v_lshl_add_u64 v[218:219], v[142:143], 1, v[156:157]
	v_lshl_add_u64 v[220:221], v[144:145], 1, v[156:157]
	v_lshl_add_u64 v[222:223], v[146:147], 1, v[156:157]
	s_waitcnt vmcnt(0)
	v_fmamk_f32 v200, v200, 0x3a800000, v165
	v_fmamk_f32 v201, v201, 0x3a800000, v165
	v_fmamk_f32 v202, v202, 0x3a800000, v165
	v_fmamk_f32 v203, v203, 0x3a800000, v165
	v_fmamk_f32 v204, v204, 0x3a800000, v165
	v_fmamk_f32 v205, v205, 0x3a800000, v165
	v_fmamk_f32 v206, v206, 0x3a800000, v165
	v_fmamk_f32 v207, v207, 0x3a800000, v165
	v_rsq_f32_e32 v200, v200
	v_rsq_f32_e32 v201, v201
	v_rsq_f32_e32 v202, v202
	v_rsq_f32_e32 v203, v203
	v_rsq_f32_e32 v204, v204
	v_rsq_f32_e32 v205, v205
	v_rsq_f32_e32 v206, v206
	v_rsq_f32_e32 v207, v207
	v_pk_mul_f32 v[124:125], v[124:125], v[200:201] op_sel_hi:[1,0]
	v_pk_mul_f32 v[126:127], v[126:127], v[200:201] op_sel_hi:[1,0]
	v_pk_mul_f32 v[120:121], v[120:121], v[200:201] op_sel_hi:[1,0]
	v_pk_mul_f32 v[122:123], v[122:123], v[200:201] op_sel_hi:[1,0]
	v_pk_mul_f32 v[116:117], v[116:117], v[200:201] op_sel_hi:[1,0]
	v_pk_mul_f32 v[118:119], v[118:119], v[200:201] op_sel_hi:[1,0]
	v_pk_mul_f32 v[112:113], v[112:113], v[200:201] op_sel_hi:[1,0]
	v_pk_mul_f32 v[114:115], v[114:115], v[200:201] op_sel_hi:[1,0]
	v_pk_mul_f32 v[168:169], v[124:125], v[208:209]
	v_pk_mul_f32 v[170:171], v[126:127], v[208:209]
	v_pk_mul_f32 v[172:173], v[120:121], v[208:209]
	v_pk_mul_f32 v[174:175], v[122:123], v[208:209]
	v_exp_f32_e32 v168, v168
	v_exp_f32_e32 v169, v169
	v_exp_f32_e32 v170, v170
	v_exp_f32_e32 v171, v171
	v_exp_f32_e32 v172, v172
	v_exp_f32_e32 v173, v173
	v_exp_f32_e32 v174, v174
	v_exp_f32_e32 v175, v175
	v_pk_add_f32 v[168:169], v[168:169], v[210:211]
	v_pk_add_f32 v[170:171], v[170:171], v[210:211]
	v_pk_add_f32 v[172:173], v[172:173], v[210:211]
	v_pk_add_f32 v[174:175], v[174:175], v[210:211]
	v_rcp_f32_e32 v168, v168
	v_rcp_f32_e32 v169, v169
	v_rcp_f32_e32 v170, v170
	v_rcp_f32_e32 v171, v171
	v_rcp_f32_e32 v172, v172
	v_rcp_f32_e32 v173, v173
	v_rcp_f32_e32 v174, v174
	v_rcp_f32_e32 v175, v175
	v_pk_mul_f32 v[168:169], v[124:125], v[168:169]
	v_pk_mul_f32 v[170:171], v[126:127], v[170:171]
	v_pk_mul_f32 v[172:173], v[120:121], v[172:173]
	v_pk_mul_f32 v[174:175], v[122:123], v[174:175]
	v_pk_mul_f32 v[168:169], v[116:117], v[168:169]
	v_pk_mul_f32 v[170:171], v[118:119], v[170:171]
	v_pk_mul_f32 v[172:173], v[112:113], v[172:173]
	v_pk_mul_f32 v[174:175], v[114:115], v[174:175]
	v_cvt_pk_bf16_f32 v112, v168, v169
	v_cvt_pk_bf16_f32 v113, v170, v171
	v_cvt_pk_bf16_f32 v114, v172, v173
	v_cvt_pk_bf16_f32 v115, v174, v175
	global_store_dwordx4 v[212:213], v[112:115], off
	v_pk_mul_f32 v[108:109], v[108:109], v[200:201] op_sel:[0,1] op_sel_hi:[1,1]
	v_pk_mul_f32 v[110:111], v[110:111], v[200:201] op_sel:[0,1] op_sel_hi:[1,1]
	v_pk_mul_f32 v[104:105], v[104:105], v[200:201] op_sel:[0,1] op_sel_hi:[1,1]
	v_pk_mul_f32 v[106:107], v[106:107], v[200:201] op_sel:[0,1] op_sel_hi:[1,1]
	v_pk_mul_f32 v[100:101], v[100:101], v[200:201] op_sel:[0,1] op_sel_hi:[1,1]
	v_pk_mul_f32 v[102:103], v[102:103], v[200:201] op_sel:[0,1] op_sel_hi:[1,1]
	v_pk_mul_f32 v[96:97], v[96:97], v[200:201] op_sel:[0,1] op_sel_hi:[1,1]
	v_pk_mul_f32 v[98:99], v[98:99], v[200:201] op_sel:[0,1] op_sel_hi:[1,1]
	v_pk_mul_f32 v[176:177], v[108:109], v[208:209]
	v_pk_mul_f32 v[178:179], v[110:111], v[208:209]
	v_pk_mul_f32 v[180:181], v[104:105], v[208:209]
	v_pk_mul_f32 v[182:183], v[106:107], v[208:209]
	v_exp_f32_e32 v176, v176
	v_exp_f32_e32 v177, v177
	v_exp_f32_e32 v178, v178
	v_exp_f32_e32 v179, v179
	v_exp_f32_e32 v180, v180
	v_exp_f32_e32 v181, v181
	v_exp_f32_e32 v182, v182
	v_exp_f32_e32 v183, v183
	v_pk_add_f32 v[176:177], v[176:177], v[210:211]
	v_pk_add_f32 v[178:179], v[178:179], v[210:211]
	v_pk_add_f32 v[180:181], v[180:181], v[210:211]
	v_pk_add_f32 v[182:183], v[182:183], v[210:211]
	v_rcp_f32_e32 v176, v176
	v_rcp_f32_e32 v177, v177
	v_rcp_f32_e32 v178, v178
	v_rcp_f32_e32 v179, v179
	v_rcp_f32_e32 v180, v180
	v_rcp_f32_e32 v181, v181
	v_rcp_f32_e32 v182, v182
	v_rcp_f32_e32 v183, v183
	v_pk_mul_f32 v[176:177], v[108:109], v[176:177]
	v_pk_mul_f32 v[178:179], v[110:111], v[178:179]
	v_pk_mul_f32 v[180:181], v[104:105], v[180:181]
	v_pk_mul_f32 v[182:183], v[106:107], v[182:183]
	v_pk_mul_f32 v[176:177], v[100:101], v[176:177]
	v_pk_mul_f32 v[178:179], v[102:103], v[178:179]
	v_pk_mul_f32 v[180:181], v[96:97], v[180:181]
	v_pk_mul_f32 v[182:183], v[98:99], v[182:183]
; __device__ __forceinline__ float silu_f(float g) { return g * __builtin_amdgcn_rcpf(1.f + __builtin_amdgcn_exp2f(-1.4426950408889634f * g)); }
; __device__ __forceinline__ u32x4 pack8(f32x4 a, f32x4 b) { u32x4 o; o.x = cvt_pk(a.x, a.y); o.y = cvt_pk(a.z, a.w); o.z = cvt_pk(b.x, b.y); o.w = cvt_pk(b.z, b.w); return o; }
; __device__ __forceinline__ float rstd_of(const float* SS, int row, float invw) { return 1.0f / sqrtf(SS[row] * invw + EPS); }
;     __device__ __forceinline__ void operator()(const f32x4 (&acc)[2][2][4][2], const pg8::Unit& u, int wr, int wc, int fr, int fq) const {
;     ...
;             for (int m = 0; m < 4; ++m) {
;                 const int row = row0 + ai * 128 + m * 16;
;                 const float r = SCALE ? rstd_of(SS, row, 1.f / 1024.f) : 1.f;
;                 const f32x4 g0 = acc[ai][0][m][0] * r, g1 = acc[ai][0][m][1] * r, u0 = acc[ai][1][m][0] * r, u1 = acc[ai][1][m][1] * r;
;                 f32x4 h0, h1;
;                 h0.x = silu_f(g0.x) * u0.x; h0.y = silu_f(g0.y) * u0.y; h0.z = silu_f(g0.z) * u0.z; h0.w = silu_f(g0.w) * u0.w;
;                 h1.x = silu_f(g1.x) * u1.x; h1.y = silu_f(g1.y) * u1.y; h1.z = silu_f(g1.z) * u1.z; h1.w = silu_f(g1.w) * u1.w;
;                 *(u32x4*)(hb + (wr * 64 + fr + ai * 128 + m * 16) * 64) = pack8(h0, h1);
	v_cvt_pk_bf16_f32 v96, v176, v177
	v_cvt_pk_bf16_f32 v97, v178, v179
	v_cvt_pk_bf16_f32 v98, v180, v181
	v_cvt_pk_bf16_f32 v99, v182, v183
	global_store_dwordx4 v[212:213], v[96:99], off offset:2048
	v_pk_mul_f32 v[92:93], v[92:93], v[202:203] op_sel_hi:[1,0]
	v_pk_mul_f32 v[94:95], v[94:95], v[202:203] op_sel_hi:[1,0]
	v_pk_mul_f32 v[88:89], v[88:89], v[202:203] op_sel_hi:[1,0]
	v_pk_mul_f32 v[90:91], v[90:91], v[202:203] op_sel_hi:[1,0]
	v_pk_mul_f32 v[84:85], v[84:85], v[202:203] op_sel_hi:[1,0]
	v_pk_mul_f32 v[86:87], v[86:87], v[202:203] op_sel_hi:[1,0]
	v_pk_mul_f32 v[80:81], v[80:81], v[202:203] op_sel_hi:[1,0]
	v_pk_mul_f32 v[82:83], v[82:83], v[202:203] op_sel_hi:[1,0]
	v_pk_mul_f32 v[168:169], v[92:93], v[208:209]
	v_pk_mul_f32 v[170:171], v[94:95], v[208:209]
	v_pk_mul_f32 v[172:173], v[88:89], v[208:209]
	v_pk_mul_f32 v[174:175], v[90:91], v[208:209]
	v_exp_f32_e32 v168, v168
	v_exp_f32_e32 v169, v169
	v_exp_f32_e32 v170, v170
	v_exp_f32_e32 v171, v171
	v_exp_f32_e32 v172, v172
	v_exp_f32_e32 v173, v173
	v_exp_f32_e32 v174, v174
	v_exp_f32_e32 v175, v175
	v_pk_add_f32 v[168:169], v[168:169], v[210:211]
	v_pk_add_f32 v[170:171], v[170:171], v[210:211]
	v_pk_add_f32 v[172:173], v[172:173], v[210:211]
	v_pk_add_f32 v[174:175], v[174:175], v[210:211]
	v_rcp_f32_e32 v168, v168
	v_rcp_f32_e32 v169, v169
	v_rcp_f32_e32 v170, v170
	v_rcp_f32_e32 v171, v171
	v_rcp_f32_e32 v172, v172
	v_rcp_f32_e32 v173, v173
	v_rcp_f32_e32 v174, v174
	v_rcp_f32_e32 v175, v175
	v_pk_mul_f32 v[168:169], v[92:93], v[168:169]
	v_pk_mul_f32 v[170:171], v[94:95], v[170:171]
	v_pk_mul_f32 v[172:173], v[88:89], v[172:173]
	v_pk_mul_f32 v[174:175], v[90:91], v[174:175]
	v_pk_mul_f32 v[168:169], v[84:85], v[168:169]
	v_pk_mul_f32 v[170:171], v[86:87], v[170:171]
	v_pk_mul_f32 v[172:173], v[80:81], v[172:173]
	v_pk_mul_f32 v[174:175], v[82:83], v[174:175]
	v_cvt_pk_bf16_f32 v80, v168, v169
	v_cvt_pk_bf16_f32 v81, v170, v171
	v_cvt_pk_bf16_f32 v82, v172, v173
	v_cvt_pk_bf16_f32 v83, v174, v175
	global_store_dwordx4 v[214:215], v[80:83], off
	v_pk_mul_f32 v[76:77], v[76:77], v[202:203] op_sel:[0,1] op_sel_hi:[1,1]
	v_pk_mul_f32 v[78:79], v[78:79], v[202:203] op_sel:[0,1] op_sel_hi:[1,1]
	v_pk_mul_f32 v[72:73], v[72:73], v[202:203] op_sel:[0,1] op_sel_hi:[1,1]
	v_pk_mul_f32 v[74:75], v[74:75], v[202:203] op_sel:[0,1] op_sel_hi:[1,1]
	v_pk_mul_f32 v[68:69], v[68:69], v[202:203] op_sel:[0,1] op_sel_hi:[1,1]
	v_pk_mul_f32 v[70:71], v[70:71], v[202:203] op_sel:[0,1] op_sel_hi:[1,1]
	v_pk_mul_f32 v[64:65], v[64:65], v[202:203] op_sel:[0,1] op_sel_hi:[1,1]
	v_pk_mul_f32 v[66:67], v[66:67], v[202:203] op_sel:[0,1] op_sel_hi:[1,1]
	v_pk_mul_f32 v[176:177], v[76:77], v[208:209]
	v_pk_mul_f32 v[178:179], v[78:79], v[208:209]
	v_pk_mul_f32 v[180:181], v[72:73], v[208:209]
	v_pk_mul_f32 v[182:183], v[74:75], v[208:209]
	v_exp_f32_e32 v176, v176
	v_exp_f32_e32 v177, v177
	v_exp_f32_e32 v178, v178
	v_exp_f32_e32 v179, v179
	v_exp_f32_e32 v180, v180
	v_exp_f32_e32 v181, v181
	v_exp_f32_e32 v182, v182
	v_exp_f32_e32 v183, v183
	v_pk_add_f32 v[176:177], v[176:177], v[210:211]
	v_pk_add_f32 v[178:179], v[178:179], v[210:211]
	v_pk_add_f32 v[180:181], v[180:181], v[210:211]
	v_pk_add_f32 v[182:183], v[182:183], v[210:211]
	v_rcp_f32_e32 v176, v176
	v_rcp_f32_e32 v177, v177
	v_rcp_f32_e32 v178, v178
	v_rcp_f32_e32 v179, v179
	v_rcp_f32_e32 v180, v180
	v_rcp_f32_e32 v181, v181
	v_rcp_f32_e32 v182, v182
	v_rcp_f32_e32 v183, v183
	v_pk_mul_f32 v[176:177], v[76:77], v[176:177]
	v_pk_mul_f32 v[178:179], v[78:79], v[178:179]
	v_pk_mul_f32 v[180:181], v[72:73], v[180:181]
	v_pk_mul_f32 v[182:183], v[74:75], v[182:183]
	v_pk_mul_f32 v[176:177], v[68:69], v[176:177]
	v_pk_mul_f32 v[178:179], v[70:71], v[178:179]
	v_pk_mul_f32 v[180:181], v[64:65], v[180:181]
	v_pk_mul_f32 v[182:183], v[66:67], v[182:183]
	v_cvt_pk_bf16_f32 v64, v176, v177
	v_cvt_pk_bf16_f32 v65, v178, v179
	v_cvt_pk_bf16_f32 v66, v180, v181
	v_cvt_pk_bf16_f32 v67, v182, v183
	global_store_dwordx4 v[214:215], v[64:67], off offset:2048
	v_pk_mul_f32 v[60:61], v[60:61], v[204:205] op_sel_hi:[1,0]
	v_pk_mul_f32 v[62:63], v[62:63], v[204:205] op_sel_hi:[1,0]
	v_pk_mul_f32 v[56:57], v[56:57], v[204:205] op_sel_hi:[1,0]
	v_pk_mul_f32 v[58:59], v[58:59], v[204:205] op_sel_hi:[1,0]
	v_pk_mul_f32 v[52:53], v[52:53], v[204:205] op_sel_hi:[1,0]
	v_pk_mul_f32 v[54:55], v[54:55], v[204:205] op_sel_hi:[1,0]
	v_pk_mul_f32 v[48:49], v[48:49], v[204:205] op_sel_hi:[1,0]
	v_pk_mul_f32 v[50:51], v[50:51], v[204:205] op_sel_hi:[1,0]
	v_pk_mul_f32 v[168:169], v[60:61], v[208:209]
	v_pk_mul_f32 v[170:171], v[62:63], v[208:209]
	v_pk_mul_f32 v[172:173], v[56:57], v[208:209]
	v_pk_mul_f32 v[174:175], v[58:59], v[208:209]
	v_exp_f32_e32 v168, v168
	v_exp_f32_e32 v169, v169
	v_exp_f32_e32 v170, v170
	v_exp_f32_e32 v171, v171
	v_exp_f32_e32 v172, v172
	v_exp_f32_e32 v173, v173
	v_exp_f32_e32 v174, v174
	v_exp_f32_e32 v175, v175
	v_pk_add_f32 v[168:169], v[168:169], v[210:211]
	v_pk_add_f32 v[170:171], v[170:171], v[210:211]
	v_pk_add_f32 v[172:173], v[172:173], v[210:211]
	v_pk_add_f32 v[174:175], v[174:175], v[210:211]
	v_rcp_f32_e32 v168, v168
	v_rcp_f32_e32 v169, v169
	v_rcp_f32_e32 v170, v170
	v_rcp_f32_e32 v171, v171
	v_rcp_f32_e32 v172, v172
	v_rcp_f32_e32 v173, v173
	v_rcp_f32_e32 v174, v174
	v_rcp_f32_e32 v175, v175
	v_pk_mul_f32 v[168:169], v[60:61], v[168:169]
	v_pk_mul_f32 v[170:171], v[62:63], v[170:171]
	v_pk_mul_f32 v[172:173], v[56:57], v[172:173]
	v_pk_mul_f32 v[174:175], v[58:59], v[174:175]
	v_pk_mul_f32 v[168:169], v[52:53], v[168:169]
	v_pk_mul_f32 v[170:171], v[54:55], v[170:171]
	v_pk_mul_f32 v[172:173], v[48:49], v[172:173]
; #define PG8_BAR __builtin_amdgcn_s_barrier()
; __device__ __forceinline__ float silu_f(float g) { return g * __builtin_amdgcn_rcpf(1.f + __builtin_amdgcn_exp2f(-1.4426950408889634f * g)); }
; __device__ __forceinline__ u32x4 pack8(f32x4 a, f32x4 b) { u32x4 o; o.x = cvt_pk(a.x, a.y); o.y = cvt_pk(a.z, a.w); o.z = cvt_pk(b.x, b.y); o.w = cvt_pk(b.z, b.w); return o; }
; __device__ __forceinline__ float rstd_of(const float* SS, int row, float invw) { return 1.0f / sqrtf(SS[row] * invw + EPS); }
; template <class Epi, class Sched, bool ALIGN_EPI = false, bool SP2 = false, bool ABLK = false>
; __device__ __forceinline__ void gemm_phase(PG8_LAS unsigned char* lds, const Gemm g, const Sched& S, const Epi& E) {
;     ...
;         if (!has_next) break;
; #pragma unroll
;         for (int a = 0; a < 2; ++a)
; #pragma unroll
;             for (int b = 0; b < 2; ++b)
; #pragma unroll
;                 for (int m = 0; m < 4; ++m)
; #pragma unroll
;                     for (int n = 0; n < 2; ++n) acc[a][b][m][n] = (f32x4){0.f, 0.f, 0.f, 0.f};
;         cur = nxt; cA = nA; cB = nB; ++ui;
;         if constexpr (ALIGN_EPI) { if (wr == 1) PG8_BAR; }
;     __device__ __forceinline__ void operator()(const f32x4 (&acc)[2][2][4][2], const pg8::Unit& u, int wr, int wc, int fr, int fq) const {
;     ...
;             for (int m = 0; m < 4; ++m) {
;                 const int row = row0 + ai * 128 + m * 16;
;                 const float r = SCALE ? rstd_of(SS, row, 1.f / 1024.f) : 1.f;
;                 const f32x4 g0 = acc[ai][0][m][0] * r, g1 = acc[ai][0][m][1] * r, u0 = acc[ai][1][m][0] * r, u1 = acc[ai][1][m][1] * r;
;                 f32x4 h0, h1;
;                 h0.x = silu_f(g0.x) * u0.x; h0.y = silu_f(g0.y) * u0.y; h0.z = silu_f(g0.z) * u0.z; h0.w = silu_f(g0.w) * u0.w;
;                 h1.x = silu_f(g1.x) * u1.x; h1.y = silu_f(g1.y) * u1.y; h1.z = silu_f(g1.z) * u1.z; h1.w = silu_f(g1.w) * u1.w;
;                 *(u32x4*)(hb + (wr * 64 + fr + ai * 128 + m * 16) * 64) = pack8(h0, h1);
	v_pk_mul_f32 v[174:175], v[50:51], v[174:175]
	v_cvt_pk_bf16_f32 v48, v168, v169
	v_cvt_pk_bf16_f32 v49, v170, v171
	v_cvt_pk_bf16_f32 v50, v172, v173
	v_cvt_pk_bf16_f32 v51, v174, v175
	global_store_dwordx4 v[216:217], v[48:51], off
	v_pk_mul_f32 v[44:45], v[44:45], v[204:205] op_sel:[0,1] op_sel_hi:[1,1]
	v_pk_mul_f32 v[46:47], v[46:47], v[204:205] op_sel:[0,1] op_sel_hi:[1,1]
	v_pk_mul_f32 v[40:41], v[40:41], v[204:205] op_sel:[0,1] op_sel_hi:[1,1]
	v_pk_mul_f32 v[42:43], v[42:43], v[204:205] op_sel:[0,1] op_sel_hi:[1,1]
	v_pk_mul_f32 v[36:37], v[36:37], v[204:205] op_sel:[0,1] op_sel_hi:[1,1]
	v_pk_mul_f32 v[38:39], v[38:39], v[204:205] op_sel:[0,1] op_sel_hi:[1,1]
	v_pk_mul_f32 v[32:33], v[32:33], v[204:205] op_sel:[0,1] op_sel_hi:[1,1]
	v_pk_mul_f32 v[34:35], v[34:35], v[204:205] op_sel:[0,1] op_sel_hi:[1,1]
	v_pk_mul_f32 v[176:177], v[44:45], v[208:209]
	v_pk_mul_f32 v[178:179], v[46:47], v[208:209]
	v_pk_mul_f32 v[180:181], v[40:41], v[208:209]
	v_pk_mul_f32 v[182:183], v[42:43], v[208:209]
	v_exp_f32_e32 v176, v176
	v_exp_f32_e32 v177, v177
	v_exp_f32_e32 v178, v178
	v_exp_f32_e32 v179, v179
	v_exp_f32_e32 v180, v180
	v_exp_f32_e32 v181, v181
	v_exp_f32_e32 v182, v182
	v_exp_f32_e32 v183, v183
	v_pk_add_f32 v[176:177], v[176:177], v[210:211]
	v_pk_add_f32 v[178:179], v[178:179], v[210:211]
	v_pk_add_f32 v[180:181], v[180:181], v[210:211]
	v_pk_add_f32 v[182:183], v[182:183], v[210:211]
	v_rcp_f32_e32 v176, v176
	v_rcp_f32_e32 v177, v177
	v_rcp_f32_e32 v178, v178
	v_rcp_f32_e32 v179, v179
	v_rcp_f32_e32 v180, v180
	v_rcp_f32_e32 v181, v181
	v_rcp_f32_e32 v182, v182
	v_rcp_f32_e32 v183, v183
	v_pk_mul_f32 v[176:177], v[44:45], v[176:177]
	v_pk_mul_f32 v[178:179], v[46:47], v[178:179]
	v_pk_mul_f32 v[180:181], v[40:41], v[180:181]
	v_pk_mul_f32 v[182:183], v[42:43], v[182:183]
	v_pk_mul_f32 v[176:177], v[36:37], v[176:177]
	v_pk_mul_f32 v[178:179], v[38:39], v[178:179]
	v_pk_mul_f32 v[180:181], v[32:33], v[180:181]
	v_pk_mul_f32 v[182:183], v[34:35], v[182:183]
	v_cvt_pk_bf16_f32 v32, v176, v177
	v_cvt_pk_bf16_f32 v33, v178, v179
	v_cvt_pk_bf16_f32 v34, v180, v181
	v_cvt_pk_bf16_f32 v35, v182, v183
	global_store_dwordx4 v[218:219], v[32:35], off
	v_pk_mul_f32 v[28:29], v[28:29], v[206:207] op_sel_hi:[1,0]
	v_pk_mul_f32 v[30:31], v[30:31], v[206:207] op_sel_hi:[1,0]
	v_pk_mul_f32 v[24:25], v[24:25], v[206:207] op_sel_hi:[1,0]
	v_pk_mul_f32 v[26:27], v[26:27], v[206:207] op_sel_hi:[1,0]
	v_pk_mul_f32 v[20:21], v[20:21], v[206:207] op_sel_hi:[1,0]
	v_pk_mul_f32 v[22:23], v[22:23], v[206:207] op_sel_hi:[1,0]
	v_pk_mul_f32 v[16:17], v[16:17], v[206:207] op_sel_hi:[1,0]
	v_pk_mul_f32 v[18:19], v[18:19], v[206:207] op_sel_hi:[1,0]
	v_pk_mul_f32 v[168:169], v[28:29], v[208:209]
	v_pk_mul_f32 v[170:171], v[30:31], v[208:209]
	v_pk_mul_f32 v[172:173], v[24:25], v[208:209]
	v_pk_mul_f32 v[174:175], v[26:27], v[208:209]
	v_exp_f32_e32 v168, v168
	v_exp_f32_e32 v169, v169
	v_exp_f32_e32 v170, v170
	v_exp_f32_e32 v171, v171
	v_exp_f32_e32 v172, v172
	v_exp_f32_e32 v173, v173
	v_exp_f32_e32 v174, v174
	v_exp_f32_e32 v175, v175
	v_pk_add_f32 v[168:169], v[168:169], v[210:211]
	v_pk_add_f32 v[170:171], v[170:171], v[210:211]
	v_pk_add_f32 v[172:173], v[172:173], v[210:211]
	v_pk_add_f32 v[174:175], v[174:175], v[210:211]
	v_rcp_f32_e32 v168, v168
	v_rcp_f32_e32 v169, v169
	v_rcp_f32_e32 v170, v170
	v_rcp_f32_e32 v171, v171
	v_rcp_f32_e32 v172, v172
	v_rcp_f32_e32 v173, v173
	v_rcp_f32_e32 v174, v174
	v_rcp_f32_e32 v175, v175
	v_pk_mul_f32 v[168:169], v[28:29], v[168:169]
	v_pk_mul_f32 v[170:171], v[30:31], v[170:171]
	v_pk_mul_f32 v[172:173], v[24:25], v[172:173]
	v_pk_mul_f32 v[174:175], v[26:27], v[174:175]
	v_pk_mul_f32 v[168:169], v[20:21], v[168:169]
	v_pk_mul_f32 v[170:171], v[22:23], v[170:171]
	v_pk_mul_f32 v[172:173], v[16:17], v[172:173]
	v_pk_mul_f32 v[174:175], v[18:19], v[174:175]
	v_cvt_pk_bf16_f32 v16, v168, v169
	v_cvt_pk_bf16_f32 v17, v170, v171
	v_cvt_pk_bf16_f32 v18, v172, v173
	v_cvt_pk_bf16_f32 v19, v174, v175
	global_store_dwordx4 v[220:221], v[16:19], off
	v_pk_mul_f32 v[12:13], v[12:13], v[206:207] op_sel:[0,1] op_sel_hi:[1,1]
	v_pk_mul_f32 v[14:15], v[14:15], v[206:207] op_sel:[0,1] op_sel_hi:[1,1]
	v_pk_mul_f32 v[8:9], v[8:9], v[206:207] op_sel:[0,1] op_sel_hi:[1,1]
	v_pk_mul_f32 v[10:11], v[10:11], v[206:207] op_sel:[0,1] op_sel_hi:[1,1]
	v_pk_mul_f32 v[4:5], v[4:5], v[206:207] op_sel:[0,1] op_sel_hi:[1,1]
	v_pk_mul_f32 v[6:7], v[6:7], v[206:207] op_sel:[0,1] op_sel_hi:[1,1]
	v_pk_mul_f32 v[0:1], v[0:1], v[206:207] op_sel:[0,1] op_sel_hi:[1,1]
	v_pk_mul_f32 v[2:3], v[2:3], v[206:207] op_sel:[0,1] op_sel_hi:[1,1]
	v_pk_mul_f32 v[176:177], v[12:13], v[208:209]
	v_pk_mul_f32 v[178:179], v[14:15], v[208:209]
	v_pk_mul_f32 v[180:181], v[8:9], v[208:209]
	v_pk_mul_f32 v[182:183], v[10:11], v[208:209]
	v_exp_f32_e32 v176, v176
	v_exp_f32_e32 v177, v177
	v_exp_f32_e32 v178, v178
	v_exp_f32_e32 v179, v179
	v_exp_f32_e32 v180, v180
	v_exp_f32_e32 v181, v181
	v_exp_f32_e32 v182, v182
	v_exp_f32_e32 v183, v183
	v_pk_add_f32 v[176:177], v[176:177], v[210:211]
	v_pk_add_f32 v[178:179], v[178:179], v[210:211]
	v_pk_add_f32 v[180:181], v[180:181], v[210:211]
	v_pk_add_f32 v[182:183], v[182:183], v[210:211]
	v_rcp_f32_e32 v176, v176
	v_rcp_f32_e32 v177, v177
	v_rcp_f32_e32 v178, v178
	v_rcp_f32_e32 v179, v179
	v_rcp_f32_e32 v180, v180
	v_rcp_f32_e32 v181, v181
	v_rcp_f32_e32 v182, v182
	v_rcp_f32_e32 v183, v183
	v_pk_mul_f32 v[176:177], v[12:13], v[176:177]
	v_pk_mul_f32 v[178:179], v[14:15], v[178:179]
	v_pk_mul_f32 v[180:181], v[8:9], v[180:181]
	v_pk_mul_f32 v[182:183], v[10:11], v[182:183]
	v_pk_mul_f32 v[176:177], v[4:5], v[176:177]
	v_pk_mul_f32 v[178:179], v[6:7], v[178:179]
	v_pk_mul_f32 v[180:181], v[0:1], v[180:181]
	v_pk_mul_f32 v[182:183], v[2:3], v[182:183]
	v_cvt_pk_bf16_f32 v0, v176, v177
	v_cvt_pk_bf16_f32 v1, v178, v179
	v_cvt_pk_bf16_f32 v2, v180, v181
	v_cvt_pk_bf16_f32 v3, v182, v183
	global_store_dwordx4 v[222:223], v[0:3], off
	s_mov_b64 s[0:1], -1
	s_andn2_b64 vcc, exec, s[38:39]
	s_cbranch_vccnz .LBB0_820
	s_andn2_b64 vcc, exec, s[28:29]
	s_cbranch_vccnz .LBB0_819
	s_mov_b32 s98, 1
	s_branch .LBB0_819

; #define PG8_STAGE(bufoff, gbase, voff) do { _Pragma("unroll") for (int _i = 0; _i < 2; ++_i) \
;         __builtin_amdgcn_global_load_lds((const unsigned*)((const char*)(gbase) + (voff)[_i]), (PG8_LAS unsigned*)(lds + (bufoff) + ldsw + _i * 8192), 16, 0, 0); } while (0)
; #define PG8_LDA(dst, b, h) do { _Pragma("unroll") for (int m = 0; m < 4; ++m) _Pragma("unroll") for (int k = 0; k < 2; ++k) dst[m][k] = *(const PG8_LAS bf16x8*)(lds + PG8_SA(b, h) + aoff + m * 2048 + k * 1024); } while (0)
; #define PG8_LDB(dst, b, h) do { _Pragma("unroll") for (int n = 0; n < 2; ++n) _Pragma("unroll") for (int k = 0; k < 2; ++k) dst[n][k] = *(const PG8_LAS bf16x8*)(lds + PG8_SB(b, h) + boff + n * 2048 + k * 1024); } while (0)
; #define PG8_WAIT_V(n) asm volatile("s_waitcnt vmcnt(" #n ")" ::: "memory")
; #define PG8_WAIT_L(n) asm volatile("s_waitcnt lgkmcnt(" #n ")" ::: "memory")
; #define PG8_BAR __builtin_amdgcn_s_barrier()
; #define PG8_SCHED __builtin_amdgcn_sched_barrier(0)
; template <class Epi, class Sched, bool ALIGN_EPI = false, bool SP2 = false, bool ABLK = false>
; __device__ __forceinline__ void gemm_phase(PG8_LAS unsigned char* lds, const Gemm g, const Sched& S, const Epi& E) {
;     ...
;     for (;;) {
;         const bool has_next = S.next(ui + 1, nxt);
;         const char* nA = has_next ? (const char*)g.A + (size_t)nxt.pm * tstep : cA; const char* nB = has_next ? (const char*)g.Bt + (size_t)nxt.pn * tstep : cB;
;         for (int t = 0; t < nt; t += 2) {
;             const bool last = (t == nt - 2);
;             const char* a1 = cA + (size_t)(t + 1) * kstepA;
;             const char* a2 = last ? nA : cA + (size_t)(t + 2) * kstepA; const char* b2 = last ? nB : cB + (size_t)(t + 2) * kstep;
;             const char* a3 = a2 + kstepA; const char* b3 = b2 + kstep;
;             if (last && has_next) S.a_ready(nxt);
;             if constexpr (SP2) {
;             PG8_LDB(B0, 0, 0); PG8_LDB(B1, 0, 1); PG8_SCHED; PG8_LDA(At, 0, 0); PG8_STAGE(PG8_SA(1, 1), a1 + hstepA, voffA);
;             PG8_WAIT_V(8); PG8_WAIT_L(0); PG8_BAR; PG8_MMA(0, 0, At, B0); PG8_MMA(0, 1, At, B1); PG8_BAR; PG8_SCHED;
;             PG8_LDA(At, 0, 1); PG8_STAGE(PG8_SB(0, 0), b2, voffB); PG8_STAGE(PG8_SB(0, 1), b2 + hstep, voffB); PG8_STAGE(PG8_SA(0, 0), a2, voffA);
;             PG8_WAIT_V(8); PG8_WAIT_L(0); PG8_BAR; PG8_MMA(1, 0, At, B0); PG8_MMA(1, 1, At, B1); PG8_BAR; PG8_SCHED;
.LBB0_904:
	s_add_u32 s14, s44, 0x100
	s_addc_u32 s15, s45, 0
	s_add_u32 s44, s46, 0xc000
	v_mov_b32_e32 v0, 0
	s_addc_u32 s45, s47, 0
	s_mov_b32 s60, -2
	s_waitcnt lgkmcnt(0)
	s_cmp_eq_u32 s98, 1
	s_cbranch_scc0 .Ldefbar_4
	s_barrier
	s_mov_b32 s98, 0
.Ldefbar_4:
.LBB0_905:
	ds_read_b128 v[144:147], v151
	ds_read_b128 v[156:159], v151 offset:1024
	ds_read_b128 v[160:163], v151 offset:2048
	ds_read_b128 v[168:171], v151 offset:3072
	ds_read_b128 v[172:175], v152
	ds_read_b128 v[176:179], v152 offset:1024
	ds_read_b128 v[180:183], v152 offset:2048
	ds_read_b128 v[184:187], v152 offset:3072
	s_add_u32 s16, s44, 0x4000
	s_addc_u32 s17, s45, 0
	s_cmp_eq_u32 s60, 40
	s_cselect_b32 s50, s0, s16
	s_cselect_b32 s51, s1, s17
	s_cselect_b32 s48, s42, s14
	s_cselect_b32 s49, s43, s15
	s_add_u32 s46, s50, 0x8000
	s_addc_u32 s47, s51, 0
	v_lshl_add_u64 v[164:165], s[44:45], 0, v[136:137]
	s_add_i32 m0, s7, 0xc000
	ds_read_b128 v[188:191], v153
	ds_read_b128 v[192:195], v153 offset:1024
	ds_read_b128 v[196:199], v153 offset:2048
	ds_read_b128 v[200:203], v153 offset:3072
	ds_read_b128 v[204:207], v153 offset:4096
	ds_read_b128 v[208:211], v153 offset:5120
	ds_read_b128 v[212:215], v153 offset:6144
	ds_read_b128 v[216:219], v153 offset:7168
	global_load_lds_dwordx4 v[164:165], off
	v_lshl_add_u64 v[164:165], s[44:45], 0, v[138:139]
	s_add_i32 m0, s7, 0xe000
	s_nop 0
	global_load_lds_dwordx4 v[164:165], off
	s_waitcnt vmcnt(8)
	s_waitcnt lgkmcnt(0)
	s_barrier
	s_setprio 1
	s_waitcnt lgkmcnt(0)
	v_mfma_f32_16x16x32_bf16 v[124:127], v[144:147], v[188:191], 0
	v_mfma_f32_16x16x32_bf16 v[120:123], v[160:163], v[188:191], 0
	v_mfma_f32_16x16x32_bf16 v[108:111], v[144:147], v[196:199], 0
	v_mfma_f32_16x16x32_bf16 v[104:107], v[160:163], v[196:199], 0
	v_mfma_f32_16x16x32_bf16 v[92:95], v[144:147], v[204:207], 0
	v_mfma_f32_16x16x32_bf16 v[88:91], v[160:163], v[204:207], 0
	v_mfma_f32_16x16x32_bf16 v[76:79], v[144:147], v[212:215], 0
	v_mfma_f32_16x16x32_bf16 v[72:75], v[160:163], v[212:215], 0
	v_mfma_f32_16x16x32_bf16 v[124:127], v[156:159], v[192:195], v[124:127]
	v_mfma_f32_16x16x32_bf16 v[120:123], v[168:171], v[192:195], v[120:123]
	v_mfma_f32_16x16x32_bf16 v[108:111], v[156:159], v[200:203], v[108:111]
	v_mfma_f32_16x16x32_bf16 v[104:107], v[168:171], v[200:203], v[104:107]
	v_mfma_f32_16x16x32_bf16 v[92:95], v[156:159], v[208:211], v[92:95]
	v_mfma_f32_16x16x32_bf16 v[88:91], v[168:171], v[208:211], v[88:91]
	v_mfma_f32_16x16x32_bf16 v[76:79], v[156:159], v[216:219], v[76:79]
	v_mfma_f32_16x16x32_bf16 v[72:75], v[168:171], v[216:219], v[72:75]
	s_setprio 0
	s_setprio 1
	v_mfma_f32_16x16x32_bf16 v[116:119], v[172:175], v[188:191], 0
	v_mfma_f32_16x16x32_bf16 v[112:115], v[180:183], v[188:191], 0
	v_mfma_f32_16x16x32_bf16 v[100:103], v[172:175], v[196:199], 0
	v_mfma_f32_16x16x32_bf16 v[96:99], v[180:183], v[196:199], 0
	v_mfma_f32_16x16x32_bf16 v[84:87], v[172:175], v[204:207], 0
	v_mfma_f32_16x16x32_bf16 v[80:83], v[180:183], v[204:207], 0
	v_mfma_f32_16x16x32_bf16 v[68:71], v[172:175], v[212:215], 0
	v_mfma_f32_16x16x32_bf16 v[64:67], v[180:183], v[212:215], 0
	v_mfma_f32_16x16x32_bf16 v[116:119], v[176:179], v[192:195], v[116:119]
	v_mfma_f32_16x16x32_bf16 v[112:115], v[184:187], v[192:195], v[112:115]
	v_mfma_f32_16x16x32_bf16 v[100:103], v[176:179], v[200:203], v[100:103]
	v_mfma_f32_16x16x32_bf16 v[96:99], v[184:187], v[200:203], v[96:99]
	v_mfma_f32_16x16x32_bf16 v[84:87], v[176:179], v[208:211], v[84:87]
	v_mfma_f32_16x16x32_bf16 v[80:83], v[184:187], v[208:211], v[80:83]
	v_mfma_f32_16x16x32_bf16 v[68:71], v[176:179], v[216:219], v[68:71]
	v_mfma_f32_16x16x32_bf16 v[64:67], v[184:187], v[216:219], v[64:67]
	s_setprio 0
	s_barrier
	s_add_i32 s16, s54, s4
	v_lshl_add_u64 v[164:165], s[48:49], 0, v[130:131]
	s_mov_b32 m0, s16
	ds_read_b128 v[188:191], v153 offset:16384
	ds_read_b128 v[192:195], v153 offset:17408
	ds_read_b128 v[196:199], v153 offset:18432
	ds_read_b128 v[200:203], v153 offset:19456
	ds_read_b128 v[204:207], v153 offset:20480
	ds_read_b128 v[208:211], v153 offset:21504
	ds_read_b128 v[212:215], v153 offset:22528
	ds_read_b128 v[216:219], v153 offset:23552
	global_load_lds_dwordx4 v[164:165], off
	s_add_i32 m0, s16, 0x2000
	s_add_u32 s16, s48, 0xb0000
	v_lshl_add_u64 v[220:221], s[48:49], 0, v[134:135]
	s_addc_u32 s17, s49, 0
	s_add_i32 s18, s55, s4
	global_load_lds_dwordx4 v[220:221], off
	v_lshl_add_u64 v[222:223], s[16:17], 0, v[130:131]
	s_mov_b32 m0, s18
	s_nop 0
	global_load_lds_dwordx4 v[222:223], off
	v_lshl_add_u64 v[222:223], s[16:17], 0, v[134:135]
	s_add_i32 m0, s18, 0x2000
	s_nop 0
	global_load_lds_dwordx4 v[222:223], off
	v_lshl_add_u64 v[222:223], s[50:51], 0, v[128:129]
	s_mov_b32 m0, s7
	s_nop 0
	global_load_lds_dwordx4 v[222:223], off
	v_lshl_add_u64 v[222:223], s[50:51], 0, v[132:133]
	s_mov_b32 m0, s8
	s_nop 0
	global_load_lds_dwordx4 v[222:223], off
	s_waitcnt vmcnt(8)
	s_waitcnt lgkmcnt(0)
	s_barrier
; #define PG8_STAGE(bufoff, gbase, voff) do { _Pragma("unroll") for (int _i = 0; _i < 2; ++_i) \
;         __builtin_amdgcn_global_load_lds((const unsigned*)((const char*)(gbase) + (voff)[_i]), (PG8_LAS unsigned*)(lds + (bufoff) + ldsw + _i * 8192), 16, 0, 0); } while (0)
; #define PG8_LDA(dst, b, h) do { _Pragma("unroll") for (int m = 0; m < 4; ++m) _Pragma("unroll") for (int k = 0; k < 2; ++k) dst[m][k] = *(const PG8_LAS bf16x8*)(lds + PG8_SA(b, h) + aoff + m * 2048 + k * 1024); } while (0)
; #define PG8_LDB(dst, b, h) do { _Pragma("unroll") for (int n = 0; n < 2; ++n) _Pragma("unroll") for (int k = 0; k < 2; ++k) dst[n][k] = *(const PG8_LAS bf16x8*)(lds + PG8_SB(b, h) + boff + n * 2048 + k * 1024); } while (0)
; #define PG8_MMA(ai, bj, At, Bt) do { __builtin_amdgcn_s_setprio(1); _Pragma("unroll") for (int m = 0; m < 4; ++m) _Pragma("unroll") for (int n = 0; n < 2; ++n) _Pragma("unroll") for (int k = 0; k < 2; ++k) \
;         acc[ai][bj][m][n] = __builtin_amdgcn_mfma_f32_16x16x32_bf16(Bt[n][k], At[m][k], acc[ai][bj][m][n], 0, 0, 0); __builtin_amdgcn_s_setprio(0); } while (0)
; #define PG8_WAIT_V(n) asm volatile("s_waitcnt vmcnt(" #n ")" ::: "memory")
; #define PG8_WAIT_L(n) asm volatile("s_waitcnt lgkmcnt(" #n ")" ::: "memory")
; #define PG8_BAR __builtin_amdgcn_s_barrier()
; #define PG8_SCHED __builtin_amdgcn_sched_barrier(0)
; template <class Epi, class Sched, bool ALIGN_EPI = false, bool SP2 = false, bool ABLK = false>
; __device__ __forceinline__ void gemm_phase(PG8_LAS unsigned char* lds, const Gemm g, const Sched& S, const Epi& E) {
;     ...
;             PG8_WAIT_V(8); PG8_WAIT_L(0); PG8_BAR; PG8_MMA(1, 0, At, B0); PG8_MMA(1, 1, At, B1); PG8_BAR; PG8_SCHED;
;             PG8_LDB(B0, 1, 0); PG8_LDB(B1, 1, 1); PG8_SCHED; PG8_LDA(At, 1, 0); PG8_STAGE(PG8_SA(0, 1), a2 + hstepA, voffA);
;             PG8_WAIT_V(8); PG8_WAIT_L(0); PG8_BAR; PG8_MMA(0, 0, At, B0); PG8_MMA(0, 1, At, B1); PG8_BAR; PG8_SCHED;
;             PG8_LDA(At, 1, 1); PG8_STAGE(PG8_SB(1, 0), b3, voffB); PG8_STAGE(PG8_SB(1, 1), b3 + hstep, voffB); PG8_STAGE(PG8_SA(1, 0), a3, voffA);
	s_setprio 1
	s_waitcnt lgkmcnt(0)
	v_mfma_f32_16x16x32_bf16 v[60:63], v[144:147], v[188:191], 0
	v_mfma_f32_16x16x32_bf16 v[56:59], v[160:163], v[188:191], 0
	v_mfma_f32_16x16x32_bf16 v[44:47], v[144:147], v[196:199], 0
	v_mfma_f32_16x16x32_bf16 v[40:43], v[160:163], v[196:199], 0
	v_mfma_f32_16x16x32_bf16 v[28:31], v[144:147], v[204:207], 0
	v_mfma_f32_16x16x32_bf16 v[24:27], v[160:163], v[204:207], 0
	v_mfma_f32_16x16x32_bf16 v[12:15], v[144:147], v[212:215], 0
	v_mfma_f32_16x16x32_bf16 v[8:11], v[160:163], v[212:215], 0
	v_mfma_f32_16x16x32_bf16 v[60:63], v[156:159], v[192:195], v[60:63]
	v_mfma_f32_16x16x32_bf16 v[56:59], v[168:171], v[192:195], v[56:59]
	v_mfma_f32_16x16x32_bf16 v[44:47], v[156:159], v[200:203], v[44:47]
	v_mfma_f32_16x16x32_bf16 v[40:43], v[168:171], v[200:203], v[40:43]
	v_mfma_f32_16x16x32_bf16 v[28:31], v[156:159], v[208:211], v[28:31]
	v_mfma_f32_16x16x32_bf16 v[24:27], v[168:171], v[208:211], v[24:27]
	v_mfma_f32_16x16x32_bf16 v[12:15], v[156:159], v[216:219], v[12:15]
	v_mfma_f32_16x16x32_bf16 v[8:11], v[168:171], v[216:219], v[8:11]
	s_setprio 0
	s_setprio 1
	v_mfma_f32_16x16x32_bf16 v[52:55], v[172:175], v[188:191], 0
	v_mfma_f32_16x16x32_bf16 v[48:51], v[180:183], v[188:191], 0
	v_mfma_f32_16x16x32_bf16 v[36:39], v[172:175], v[196:199], 0
	v_mfma_f32_16x16x32_bf16 v[32:35], v[180:183], v[196:199], 0
	v_mfma_f32_16x16x32_bf16 v[20:23], v[172:175], v[204:207], 0
	v_mfma_f32_16x16x32_bf16 v[16:19], v[180:183], v[204:207], 0
	v_mfma_f32_16x16x32_bf16 v[4:7], v[172:175], v[212:215], 0
	v_mfma_f32_16x16x32_bf16 v[0:3], v[180:183], v[212:215], 0
	v_mfma_f32_16x16x32_bf16 v[52:55], v[176:179], v[192:195], v[52:55]
	v_mfma_f32_16x16x32_bf16 v[48:51], v[184:187], v[192:195], v[48:51]
	v_mfma_f32_16x16x32_bf16 v[36:39], v[176:179], v[200:203], v[36:39]
	v_mfma_f32_16x16x32_bf16 v[32:35], v[184:187], v[200:203], v[32:35]
	v_mfma_f32_16x16x32_bf16 v[20:23], v[176:179], v[208:211], v[20:23]
	v_mfma_f32_16x16x32_bf16 v[16:19], v[184:187], v[208:211], v[16:19]
	v_mfma_f32_16x16x32_bf16 v[4:7], v[176:179], v[216:219], v[4:7]
	v_mfma_f32_16x16x32_bf16 v[0:3], v[184:187], v[216:219], v[0:3]
	s_setprio 0
	s_barrier
	s_add_i32 s18, 0, 0x18000
	v_add_u32_e32 v155, s18, v149
	s_add_i32 s19, 0, 0x1c000
	ds_read_b128 v[144:147], v155
	ds_read_b128 v[156:159], v155 offset:1024
	ds_read_b128 v[160:163], v155 offset:2048
	ds_read_b128 v[168:171], v155 offset:3072
	v_add_u32_e32 v155, s19, v149
	ds_read_b128 v[172:175], v155
	ds_read_b128 v[176:179], v155 offset:1024
	ds_read_b128 v[180:183], v155 offset:2048
	ds_read_b128 v[184:187], v155 offset:3072
	s_add_u32 s16, s50, 0x4000
	s_addc_u32 s17, s51, 0
	s_mov_b32 m0, s9
	v_lshl_add_u64 v[222:223], s[16:17], 0, v[128:129]
	ds_read_b128 v[188:191], v153 offset:32768
	ds_read_b128 v[192:195], v153 offset:33792
	ds_read_b128 v[196:199], v153 offset:34816
	ds_read_b128 v[200:203], v153 offset:35840
	ds_read_b128 v[204:207], v153 offset:36864
	ds_read_b128 v[208:211], v153 offset:37888
	ds_read_b128 v[212:215], v153 offset:38912
	ds_read_b128 v[216:219], v153 offset:39936
	global_load_lds_dwordx4 v[222:223], off
	v_lshl_add_u64 v[222:223], s[16:17], 0, v[132:133]
	s_mov_b32 m0, s10
	s_nop 0
	global_load_lds_dwordx4 v[222:223], off
	s_waitcnt vmcnt(8)
	s_waitcnt lgkmcnt(0)
	s_barrier
	s_setprio 1
	s_waitcnt lgkmcnt(0)
	v_mfma_f32_16x16x32_bf16 v[124:127], v[144:147], v[188:191], v[124:127]
	v_mfma_f32_16x16x32_bf16 v[120:123], v[160:163], v[188:191], v[120:123]
	v_mfma_f32_16x16x32_bf16 v[108:111], v[144:147], v[196:199], v[108:111]
	v_mfma_f32_16x16x32_bf16 v[104:107], v[160:163], v[196:199], v[104:107]
	v_mfma_f32_16x16x32_bf16 v[92:95], v[144:147], v[204:207], v[92:95]
	v_mfma_f32_16x16x32_bf16 v[88:91], v[160:163], v[204:207], v[88:91]
	v_mfma_f32_16x16x32_bf16 v[76:79], v[144:147], v[212:215], v[76:79]
	v_mfma_f32_16x16x32_bf16 v[72:75], v[160:163], v[212:215], v[72:75]
	v_mfma_f32_16x16x32_bf16 v[124:127], v[156:159], v[192:195], v[124:127]
	v_mfma_f32_16x16x32_bf16 v[120:123], v[168:171], v[192:195], v[120:123]
	v_mfma_f32_16x16x32_bf16 v[108:111], v[156:159], v[200:203], v[108:111]
	v_mfma_f32_16x16x32_bf16 v[104:107], v[168:171], v[200:203], v[104:107]
	v_mfma_f32_16x16x32_bf16 v[92:95], v[156:159], v[208:211], v[92:95]
	v_mfma_f32_16x16x32_bf16 v[88:91], v[168:171], v[208:211], v[88:91]
	v_mfma_f32_16x16x32_bf16 v[76:79], v[156:159], v[216:219], v[76:79]
	v_mfma_f32_16x16x32_bf16 v[72:75], v[168:171], v[216:219], v[72:75]
	s_setprio 0
	s_setprio 1
	v_mfma_f32_16x16x32_bf16 v[116:119], v[172:175], v[188:191], v[116:119]
	v_mfma_f32_16x16x32_bf16 v[112:115], v[180:183], v[188:191], v[112:115]
	v_mfma_f32_16x16x32_bf16 v[100:103], v[172:175], v[196:199], v[100:103]
	v_mfma_f32_16x16x32_bf16 v[96:99], v[180:183], v[196:199], v[96:99]
	v_mfma_f32_16x16x32_bf16 v[84:87], v[172:175], v[204:207], v[84:87]
	v_mfma_f32_16x16x32_bf16 v[80:83], v[180:183], v[204:207], v[80:83]
	v_mfma_f32_16x16x32_bf16 v[68:71], v[172:175], v[212:215], v[68:71]
	v_mfma_f32_16x16x32_bf16 v[64:67], v[180:183], v[212:215], v[64:67]
	v_mfma_f32_16x16x32_bf16 v[116:119], v[176:179], v[192:195], v[116:119]
	v_mfma_f32_16x16x32_bf16 v[112:115], v[184:187], v[192:195], v[112:115]
	v_mfma_f32_16x16x32_bf16 v[100:103], v[176:179], v[200:203], v[100:103]
	v_mfma_f32_16x16x32_bf16 v[96:99], v[184:187], v[200:203], v[96:99]
	v_mfma_f32_16x16x32_bf16 v[84:87], v[176:179], v[208:211], v[84:87]
	v_mfma_f32_16x16x32_bf16 v[80:83], v[184:187], v[208:211], v[80:83]
	v_mfma_f32_16x16x32_bf16 v[68:71], v[176:179], v[216:219], v[68:71]
	v_mfma_f32_16x16x32_bf16 v[64:67], v[184:187], v[216:219], v[64:67]
	s_setprio 0
	s_barrier
; #define PG8_STAGE(bufoff, gbase, voff) do { _Pragma("unroll") for (int _i = 0; _i < 2; ++_i) \
;         __builtin_amdgcn_global_load_lds((const unsigned*)((const char*)(gbase) + (voff)[_i]), (PG8_LAS unsigned*)(lds + (bufoff) + ldsw + _i * 8192), 16, 0, 0); } while (0)
; #define PG8_LDA(dst, b, h) do { _Pragma("unroll") for (int m = 0; m < 4; ++m) _Pragma("unroll") for (int k = 0; k < 2; ++k) dst[m][k] = *(const PG8_LAS bf16x8*)(lds + PG8_SA(b, h) + aoff + m * 2048 + k * 1024); } while (0)
; #define PG8_MMA(ai, bj, At, Bt) do { __builtin_amdgcn_s_setprio(1); _Pragma("unroll") for (int m = 0; m < 4; ++m) _Pragma("unroll") for (int n = 0; n < 2; ++n) _Pragma("unroll") for (int k = 0; k < 2; ++k) \
;         acc[ai][bj][m][n] = __builtin_amdgcn_mfma_f32_16x16x32_bf16(Bt[n][k], At[m][k], acc[ai][bj][m][n], 0, 0, 0); __builtin_amdgcn_s_setprio(0); } while (0)
; #define PG8_WAIT_V(n) asm volatile("s_waitcnt vmcnt(" #n ")" ::: "memory")
; #define PG8_WAIT_L(n) asm volatile("s_waitcnt lgkmcnt(" #n ")" ::: "memory")
; #define PG8_BAR __builtin_amdgcn_s_barrier()
; #define PG8_SCHED __builtin_amdgcn_sched_barrier(0)
; template <class Epi, class Sched, bool ALIGN_EPI = false, bool SP2 = false, bool ABLK = false>
; __device__ __forceinline__ void gemm_phase(PG8_LAS unsigned char* lds, const Gemm g, const Sched& S, const Epi& E) {
;     ...
;             PG8_LDA(At, 1, 1); PG8_STAGE(PG8_SB(1, 0), b3, voffB); PG8_STAGE(PG8_SB(1, 1), b3 + hstep, voffB); PG8_STAGE(PG8_SA(1, 0), a3, voffA);
;             PG8_WAIT_V(8); PG8_WAIT_L(0); PG8_BAR; PG8_MMA(1, 0, At, B0); PG8_MMA(1, 1, At, B1); PG8_BAR; PG8_SCHED;
	s_add_i32 s16, s18, s4
	v_lshl_add_u64 v[164:165], v[164:165], 0, s[30:31]
	s_mov_b32 m0, s16
	ds_read_b128 v[188:191], v153 offset:49152
	ds_read_b128 v[192:195], v153 offset:50176
	ds_read_b128 v[196:199], v153 offset:51200
	ds_read_b128 v[200:203], v153 offset:52224
	ds_read_b128 v[204:207], v153 offset:53248
	ds_read_b128 v[208:211], v153 offset:54272
	ds_read_b128 v[212:215], v153 offset:55296
	ds_read_b128 v[216:219], v153 offset:56320
	global_load_lds_dwordx4 v[164:165], off
	s_add_i32 m0, s16, 0x2000
	s_add_u32 s16, s48, 0xb0080
	v_lshl_add_u64 v[164:165], v[220:221], 0, s[30:31]
	s_addc_u32 s17, s49, 0
	s_add_i32 s18, s19, s4
	global_load_lds_dwordx4 v[164:165], off
	v_lshl_add_u64 v[164:165], s[16:17], 0, v[130:131]
	s_mov_b32 m0, s18
	s_nop 0
	global_load_lds_dwordx4 v[164:165], off
	v_lshl_add_u64 v[164:165], s[16:17], 0, v[134:135]
	s_add_i32 m0, s18, 0x2000
	s_nop 0
	global_load_lds_dwordx4 v[164:165], off
	v_lshl_add_u64 v[164:165], s[46:47], 0, v[128:129]
	s_mov_b32 m0, s52
	s_nop 0
	global_load_lds_dwordx4 v[164:165], off
	v_lshl_add_u64 v[164:165], s[46:47], 0, v[132:133]
	s_mov_b32 m0, s53
	s_nop 0
	global_load_lds_dwordx4 v[164:165], off
	s_waitcnt vmcnt(8)
	s_waitcnt lgkmcnt(0)
	s_barrier
	s_setprio 1
	s_waitcnt lgkmcnt(0)
	v_mfma_f32_16x16x32_bf16 v[60:63], v[144:147], v[188:191], v[60:63]
	v_mfma_f32_16x16x32_bf16 v[56:59], v[160:163], v[188:191], v[56:59]
	v_mfma_f32_16x16x32_bf16 v[44:47], v[144:147], v[196:199], v[44:47]
	v_mfma_f32_16x16x32_bf16 v[40:43], v[160:163], v[196:199], v[40:43]
	v_mfma_f32_16x16x32_bf16 v[28:31], v[144:147], v[204:207], v[28:31]
	v_mfma_f32_16x16x32_bf16 v[24:27], v[160:163], v[204:207], v[24:27]
	v_mfma_f32_16x16x32_bf16 v[12:15], v[144:147], v[212:215], v[12:15]
	v_mfma_f32_16x16x32_bf16 v[8:11], v[160:163], v[212:215], v[8:11]
	v_mfma_f32_16x16x32_bf16 v[60:63], v[156:159], v[192:195], v[60:63]
	v_mfma_f32_16x16x32_bf16 v[56:59], v[168:171], v[192:195], v[56:59]
	v_mfma_f32_16x16x32_bf16 v[44:47], v[156:159], v[200:203], v[44:47]
	v_mfma_f32_16x16x32_bf16 v[40:43], v[168:171], v[200:203], v[40:43]
	v_mfma_f32_16x16x32_bf16 v[28:31], v[156:159], v[208:211], v[28:31]
	v_mfma_f32_16x16x32_bf16 v[24:27], v[168:171], v[208:211], v[24:27]
	v_mfma_f32_16x16x32_bf16 v[12:15], v[156:159], v[216:219], v[12:15]
	v_mfma_f32_16x16x32_bf16 v[8:11], v[168:171], v[216:219], v[8:11]
	s_setprio 0
	s_setprio 1
	v_mfma_f32_16x16x32_bf16 v[52:55], v[172:175], v[188:191], v[52:55]
	v_mfma_f32_16x16x32_bf16 v[48:51], v[180:183], v[188:191], v[48:51]
	v_mfma_f32_16x16x32_bf16 v[36:39], v[172:175], v[196:199], v[36:39]
	v_mfma_f32_16x16x32_bf16 v[32:35], v[180:183], v[196:199], v[32:35]
	v_mfma_f32_16x16x32_bf16 v[20:23], v[172:175], v[204:207], v[20:23]
	v_mfma_f32_16x16x32_bf16 v[16:19], v[180:183], v[204:207], v[16:19]
	v_mfma_f32_16x16x32_bf16 v[4:7], v[172:175], v[212:215], v[4:7]
	v_mfma_f32_16x16x32_bf16 v[0:3], v[180:183], v[212:215], v[0:3]
	v_mfma_f32_16x16x32_bf16 v[52:55], v[176:179], v[192:195], v[52:55]
	v_mfma_f32_16x16x32_bf16 v[48:51], v[184:187], v[192:195], v[48:51]
	v_mfma_f32_16x16x32_bf16 v[36:39], v[176:179], v[200:203], v[36:39]
	v_mfma_f32_16x16x32_bf16 v[32:35], v[184:187], v[200:203], v[32:35]
	v_mfma_f32_16x16x32_bf16 v[20:23], v[176:179], v[208:211], v[20:23]
	v_mfma_f32_16x16x32_bf16 v[16:19], v[184:187], v[208:211], v[16:19]
	v_mfma_f32_16x16x32_bf16 v[4:7], v[176:179], v[216:219], v[4:7]
	v_mfma_f32_16x16x32_bf16 v[0:3], v[184:187], v[216:219], v[0:3]
	s_setprio 0
	s_barrier
	s_add_i32 s60, s60, 2
	s_add_u32 s14, s14, 0x100
	s_addc_u32 s15, s15, 0
	s_add_u32 s44, s44, 0x10000
	s_addc_u32 s45, s45, 0
	s_cmp_gt_u32 s60, 41
	s_cbranch_scc1 .Lpeel_post_4

; #define PG8_BAR __builtin_amdgcn_s_barrier()
; template <class Epi, class Sched, bool ALIGN_EPI = false, bool SP2 = false, bool ABLK = false>
; __device__ __forceinline__ void gemm_phase(PG8_LAS unsigned char* lds, const Gemm g, const Sched& S, const Epi& E) {
;     ...
;         if (!has_next) break;
; #pragma unroll
;         for (int a = 0; a < 2; ++a)
; #pragma unroll
;             for (int b = 0; b < 2; ++b)
; #pragma unroll
;                 for (int m = 0; m < 4; ++m)
; #pragma unroll
;                     for (int n = 0; n < 2; ++n) acc[a][b][m][n] = (f32x4){0.f, 0.f, 0.f, 0.f};
;         cur = nxt; cA = nA; cB = nB; ++ui;
;         if constexpr (ALIGN_EPI) { if (wr == 1) PG8_BAR; }
.LBB0_924:
	s_or_b64 exec, exec, s[44:45]
	s_and_b64 vcc, exec, s[40:41]
	s_mov_b64 s[40:41], -1
	s_cbranch_vccnz .LBB0_893
	s_andn2_b64 vcc, exec, s[28:29]
	s_cbranch_vccnz .LBB0_892
	s_mov_b32 s98, 1
	s_branch .LBB0_892

; __global__ void __launch_bounds__(512, 2) mk_fwd(Params p) {
	.amdhsa_kernel _Z6mk_fwd6Params
		.amdhsa_group_segment_fixed_size 0
		.amdhsa_private_segment_fixed_size 0
		.amdhsa_kernarg_size 480
		.amdhsa_user_sgpr_count 2
		.amdhsa_user_sgpr_dispatch_ptr 0
		.amdhsa_user_sgpr_queue_ptr 0
		.amdhsa_user_sgpr_kernarg_segment_ptr 1
		.amdhsa_user_sgpr_dispatch_id 0
		.amdhsa_user_sgpr_kernarg_preload_length 0
		.amdhsa_user_sgpr_kernarg_preload_offset 0
		.amdhsa_user_sgpr_private_segment_size 0
		.amdhsa_uses_dynamic_stack 0
		.amdhsa_enable_private_segment 0
		.amdhsa_system_sgpr_workgroup_id_x 1
		.amdhsa_system_sgpr_workgroup_id_y 0
		.amdhsa_system_sgpr_workgroup_id_z 0
		.amdhsa_system_sgpr_workgroup_info 0
		.amdhsa_system_vgpr_workitem_id 2
		.amdhsa_next_free_vgpr 256
		.amdhsa_next_free_sgpr 100
		.amdhsa_accum_offset 256
		.amdhsa_reserve_vcc 1
		.amdhsa_float_round_mode_32 0
		.amdhsa_float_round_mode_16_64 0
		.amdhsa_float_denorm_mode_32 3
		.amdhsa_float_denorm_mode_16_64 3
		.amdhsa_dx10_clamp 1
		.amdhsa_ieee_mode 1
		.amdhsa_fp16_overflow 0
		.amdhsa_tg_split 0
		.amdhsa_exception_fp_ieee_invalid_op 0
		.amdhsa_exception_fp_denorm_src 0
		.amdhsa_exception_fp_ieee_div_zero 0
		.amdhsa_exception_fp_ieee_overflow 0
		.amdhsa_exception_fp_ieee_underflow 0
		.amdhsa_exception_fp_ieee_inexact 0
		.amdhsa_exception_int_div_zero 0
	.end_amdhsa_kernel

; __global__ void __launch_bounds__(512, 2) mk_fwd(Params p) {
amdhsa.kernels:
  - .agpr_count:     0
    .args:
      - .offset:         0
        .size:           224
        .value_kind:     by_value
      - .offset:         224
        .size:           4
        .value_kind:     hidden_block_count_x
      - .offset:         228
        .size:           4
        .value_kind:     hidden_block_count_y
      - .offset:         232
        .size:           4
        .value_kind:     hidden_block_count_z
      - .offset:         236
        .size:           2
        .value_kind:     hidden_group_size_x
      - .offset:         238
        .size:           2
        .value_kind:     hidden_group_size_y
      - .offset:         240
        .size:           2
        .value_kind:     hidden_group_size_z
      - .offset:         242
        .size:           2
        .value_kind:     hidden_remainder_x
      - .offset:         244
        .size:           2
        .value_kind:     hidden_remainder_y
      - .offset:         246
        .size:           2
        .value_kind:     hidden_remainder_z
      - .offset:         264
        .size:           8
        .value_kind:     hidden_global_offset_x
      - .offset:         272
        .size:           8
        .value_kind:     hidden_global_offset_y
      - .offset:         280
        .size:           8
        .value_kind:     hidden_global_offset_z
      - .offset:         288
        .size:           2
        .value_kind:     hidden_grid_dims
      - .offset:         312
        .size:           8
        .value_kind:     hidden_multigrid_sync_arg
      - .offset:         344
        .size:           4
        .value_kind:     hidden_dynamic_lds_size
    .group_segment_fixed_size: 0
    .kernarg_segment_align: 8
    .kernarg_segment_size: 480
    .language:       OpenCL C
    .language_version:
      - 2
      - 0
    .max_flat_workgroup_size: 512
    .name:           _Z6mk_fwd6Params
    .private_segment_fixed_size: 0
    .sgpr_count:     106
    .sgpr_spill_count: 94
    .symbol:         _Z6mk_fwd6Params.kd
    .uniform_work_group_size: 1
    .uses_dynamic_stack: false
    .vgpr_count:     256
    .vgpr_spill_count: 0
    .wavefront_size: 64
